# weight transposes: item stores left in flight instead of waited per item
# baseline (speedup 1.0000x reference)
; template <class Map>
; __device__ __forceinline__ void transpose_item(const float* W, int K, int N, bf16_t* WT, float* scr, int item, int nblk, int lane, Map srccol) {
;     const int kb = item / nblk, nb = item % nblk, k0 = 64 * kb, n0 = 32 * nb;
;     const int sc = srccol(n0 + (lane & 31));
;     float tv[32];
;     const float* wp = W + (size_t)(k0 + (lane >> 5)) * N + (sc >= 0 ? sc : 0);
; #pragma unroll
;     for (int i = 0; i < 32; ++i) tv[i] = wp[(size_t)(2 * i) * N];
; #pragma unroll
;     for (int i = 0; i < 32; ++i) { const int kk = 2 * i + (lane >> 5); scr[kk * 33 + (lane & 31)] = sc >= 0 ? tv[i] : 0.f; }
.LBB0_11:
	s_mul_hi_i32 s8, s62, 0x2e8ba2e9
	s_lshr_b32 s9, s8, 31
	s_ashr_i32 s8, s8, 5
	s_add_i32 s9, s8, s9
	s_mul_i32 s65, s9, 0xffffea00
	s_lshl_b32 s8, s9, 6
	s_mulk_i32 s9, 0xf500
	s_add_i32 s65, s63, s65
	s_add_i32 s66, s64, s9
	v_or_b32_e32 v25, s65, v1
	v_and_or_b32 v2, s62, 4, v12
	v_mov_b64_e32 v[6:7], s[10:11]
	v_or_b32_e32 v21, s8, v8
	s_and_b32 s68, s66, 0xffffff80
	s_and_b32 s69, s65, 0x60
	v_lshlrev_b32_e32 v27, 1, v25
	v_mad_i64_i32 v[6:7], s[66:67], v21, s24, v[6:7]
	v_add_u32_e32 v24, s65, v9
	v_add_u32_e32 v21, s68, v11
	v_or_b32_e32 v2, s69, v2
	v_and_b32_e32 v32, 24, v27
	s_ashr_i32 s9, s8, 31
	v_ashrrev_i32_e32 v25, 31, v24
	v_add_u32_e32 v26, 8, v24
	v_add_u32_e32 v28, 16, v24
	v_add_u32_e32 v30, 24, v24
	v_or3_b32 v2, v2, v32, v21
	v_cmp_lt_i32_e32 vcc, -1, v21
	v_lshl_add_u64 v[22:23], s[8:9], 1, v[4:5]
	v_lshlrev_b64 v[24:25], 11, v[24:25]
	v_ashrrev_i32_e32 v27, 31, v26
	v_ashrrev_i32_e32 v29, 31, v28
	v_ashrrev_i32_e32 v31, 31, v30
	v_cndmask_b32_e32 v2, 0, v2, vcc
	v_lshl_add_u64 v[38:39], v[22:23], 0, v[24:25]
	v_lshlrev_b64 v[24:25], 11, v[26:27]
	v_lshlrev_b64 v[26:27], 11, v[28:29]
	v_lshlrev_b64 v[28:29], 11, v[30:31]
	v_lshl_add_u64 v[6:7], v[2:3], 2, v[6:7]
	v_lshl_add_u64 v[40:41], v[22:23], 0, v[24:25]
	v_lshl_add_u64 v[42:43], v[22:23], 0, v[26:27]
	v_lshl_add_u64 v[44:45], v[22:23], 0, v[28:29]
	v_add_co_u32_e64 v22, s[8:9], s25, v6
	s_add_i32 s62, s62, s4
	s_nop 0
	v_addc_co_u32_e64 v23, s[8:9], 0, v7, s[8:9]
	v_add_co_u32_e64 v24, s[8:9], s26, v6
	s_add_i32 s63, s63, s97
	s_nop 0
	v_addc_co_u32_e64 v25, s[8:9], 0, v7, s[8:9]
	v_add_co_u32_e64 v26, s[8:9], s27, v6
	s_add_i32 s64, s64, s70
	s_nop 0
	v_addc_co_u32_e64 v27, s[8:9], 0, v7, s[8:9]
	v_add_co_u32_e64 v28, s[8:9], s28, v6
	s_cmpk_gt_i32 s62, 0xaff
	s_nop 0
	v_addc_co_u32_e64 v29, s[8:9], 0, v7, s[8:9]
	v_add_co_u32_e64 v30, s[8:9], s29, v6
	s_nop 1
	v_addc_co_u32_e64 v31, s[8:9], 0, v7, s[8:9]
	v_add_co_u32_e64 v32, s[8:9], s30, v6
	s_nop 1
	v_addc_co_u32_e64 v33, s[8:9], 0, v7, s[8:9]
	v_add_co_u32_e64 v34, s[8:9], s31, v6
	s_nop 1
	v_addc_co_u32_e64 v35, s[8:9], 0, v7, s[8:9]
	v_add_co_u32_e64 v36, s[8:9], s33, v6
	s_nop 1
	v_addc_co_u32_e64 v37, s[8:9], 0, v7, s[8:9]
	v_add_co_u32_e64 v46, s[8:9], s34, v6
	s_nop 1
	v_addc_co_u32_e64 v47, s[8:9], 0, v7, s[8:9]
	v_add_co_u32_e64 v48, s[8:9], s35, v6
	s_nop 1
	v_addc_co_u32_e64 v49, s[8:9], 0, v7, s[8:9]
	v_add_co_u32_e64 v50, s[8:9], s40, v6
	s_nop 1
	v_addc_co_u32_e64 v51, s[8:9], 0, v7, s[8:9]
	v_add_co_u32_e64 v52, s[8:9], s41, v6
	s_nop 1
	v_addc_co_u32_e64 v53, s[8:9], 0, v7, s[8:9]
	v_add_co_u32_e64 v54, s[8:9], s42, v6
	s_nop 1
	v_addc_co_u32_e64 v55, s[8:9], 0, v7, s[8:9]
	v_add_co_u32_e64 v56, s[8:9], s43, v6
	s_nop 1
	v_addc_co_u32_e64 v57, s[8:9], 0, v7, s[8:9]
	v_add_co_u32_e64 v58, s[8:9], s44, v6
	s_nop 1
	v_addc_co_u32_e64 v59, s[8:9], 0, v7, s[8:9]
	v_add_co_u32_e64 v60, s[8:9], s45, v6
	s_nop 1
	v_addc_co_u32_e64 v61, s[8:9], 0, v7, s[8:9]
	v_add_co_u32_e64 v62, s[8:9], s46, v6
	s_nop 1
	v_addc_co_u32_e64 v63, s[8:9], 0, v7, s[8:9]
	v_add_co_u32_e64 v64, s[8:9], s47, v6
	s_nop 1
	v_addc_co_u32_e64 v65, s[8:9], 0, v7, s[8:9]
	v_add_co_u32_e64 v66, s[8:9], s48, v6
	s_nop 1
	v_addc_co_u32_e64 v67, s[8:9], 0, v7, s[8:9]
	v_add_co_u32_e64 v68, s[8:9], s49, v6
	s_nop 1
	v_addc_co_u32_e64 v69, s[8:9], 0, v7, s[8:9]
	v_add_co_u32_e64 v70, s[8:9], s50, v6
	s_nop 1
	v_addc_co_u32_e64 v71, s[8:9], 0, v7, s[8:9]
	v_add_co_u32_e64 v72, s[8:9], s51, v6
	s_nop 1
	v_addc_co_u32_e64 v73, s[8:9], 0, v7, s[8:9]
	v_add_co_u32_e64 v74, s[8:9], s52, v6
	s_nop 1
	v_addc_co_u32_e64 v75, s[8:9], 0, v7, s[8:9]
	v_add_co_u32_e64 v76, s[8:9], s53, v6
	s_nop 1
	v_addc_co_u32_e64 v77, s[8:9], 0, v7, s[8:9]
	v_add_co_u32_e64 v78, s[8:9], s54, v6
	s_nop 1
	v_addc_co_u32_e64 v79, s[8:9], 0, v7, s[8:9]
	v_add_co_u32_e64 v80, s[8:9], s55, v6
	s_nop 1
	v_addc_co_u32_e64 v81, s[8:9], 0, v7, s[8:9]
	v_add_co_u32_e64 v82, s[8:9], s56, v6
	s_nop 1
	v_addc_co_u32_e64 v83, s[8:9], 0, v7, s[8:9]
	v_add_co_u32_e64 v84, s[8:9], s57, v6
	s_nop 1
	v_addc_co_u32_e64 v85, s[8:9], 0, v7, s[8:9]
	v_add_co_u32_e64 v86, s[8:9], s58, v6
	s_nop 1
	v_addc_co_u32_e64 v87, s[8:9], 0, v7, s[8:9]
	v_add_co_u32_e64 v88, s[8:9], s59, v6
	s_nop 1
	v_addc_co_u32_e64 v89, s[8:9], 0, v7, s[8:9]
	v_add_co_u32_e64 v90, s[8:9], s60, v6
	s_nop 1
	v_addc_co_u32_e64 v91, s[8:9], 0, v7, s[8:9]
	global_load_dword v2, v[6:7], off
	s_nop 0
	global_load_dword v6, v[22:23], off
	global_load_dword v7, v[24:25], off
	global_load_dword v21, v[26:27], off
	s_nop 0
	global_load_dword v22, v[28:29], off
	global_load_dword v23, v[30:31], off
	global_load_dword v24, v[32:33], off
	global_load_dword v25, v[34:35], off
	global_load_dword v26, v[36:37], off
	global_load_dword v27, v[46:47], off
	global_load_dword v28, v[48:49], off
	global_load_dword v29, v[50:51], off
	global_load_dword v30, v[52:53], off
	global_load_dword v31, v[54:55], off
	global_load_dword v32, v[56:57], off
	global_load_dword v33, v[58:59], off
	global_load_dword v34, v[60:61], off
	global_load_dword v35, v[62:63], off
	global_load_dword v36, v[64:65], off
	global_load_dword v37, v[66:67], off
	global_load_dword v46, v[68:69], off
	global_load_dword v47, v[70:71], off
	global_load_dword v48, v[72:73], off
	global_load_dword v49, v[74:75], off
	global_load_dword v50, v[76:77], off
	global_load_dword v51, v[78:79], off
	global_load_dword v52, v[80:81], off
	global_load_dword v53, v[82:83], off
	global_load_dword v54, v[84:85], off
	global_load_dword v55, v[86:87], off
	global_load_dword v56, v[88:89], off
	global_load_dword v57, v[90:91], off
	s_waitcnt vmcnt(31)
; __device__ __forceinline__ unsigned pk2(float lo, float hi) { unsigned r; asm("v_cvt_pk_bf16_f32 %0, %1, %2" : "=v"(r) : "v"(lo), "v"(hi)); return r; }
; template <class Map>
; __device__ __forceinline__ void transpose_item(const float* W, int K, int N, bf16_t* WT, float* scr, int item, int nblk, int lane, Map srccol) {
;     ...
;     for (int i = 0; i < 32; ++i) { const int kk = 2 * i + (lane >> 5); scr[kk * 33 + (lane & 31)] = sc >= 0 ? tv[i] : 0.f; }
;     __builtin_amdgcn_s_waitcnt(0); asm volatile("" ::: "memory");
;     const int c = lane & 7;
; #pragma unroll
;     for (int j = 0; j < 4; ++j) { const int n = (lane >> 3) + 8 * j; const float* s = scr + (8 * c) * 33 + n;
;         u32x4 o; o.x = pk2(s[0 * 33], s[1 * 33]); o.y = pk2(s[2 * 33], s[3 * 33]); o.z = pk2(s[4 * 33], s[5 * 33]); o.w = pk2(s[6 * 33], s[7 * 33]);
;         *(u32x4*)(WT + (size_t)(n0 + n) * K + k0 + 8 * c) = o; }
;     __builtin_amdgcn_s_waitcnt(0); asm volatile("" ::: "memory");
	v_cndmask_b32_e32 v2, 0, v2, vcc
	s_waitcnt vmcnt(30)
	v_cndmask_b32_e32 v6, 0, v6, vcc
	s_waitcnt vmcnt(29)
	v_cndmask_b32_e32 v7, 0, v7, vcc
	s_waitcnt vmcnt(28)
	v_cndmask_b32_e32 v21, 0, v21, vcc
	s_waitcnt vmcnt(27)
	v_cndmask_b32_e32 v22, 0, v22, vcc
	s_waitcnt vmcnt(26)
	v_cndmask_b32_e32 v23, 0, v23, vcc
	s_waitcnt vmcnt(25)
	v_cndmask_b32_e32 v24, 0, v24, vcc
	s_waitcnt vmcnt(24)
	v_cndmask_b32_e32 v25, 0, v25, vcc
	s_waitcnt vmcnt(23)
	v_cndmask_b32_e32 v26, 0, v26, vcc
	s_waitcnt vmcnt(22)
	v_cndmask_b32_e32 v27, 0, v27, vcc
	s_waitcnt vmcnt(21)
	v_cndmask_b32_e32 v28, 0, v28, vcc
	s_waitcnt vmcnt(20)
	v_cndmask_b32_e32 v29, 0, v29, vcc
	s_waitcnt vmcnt(19)
	v_cndmask_b32_e32 v30, 0, v30, vcc
	s_waitcnt vmcnt(18)
	v_cndmask_b32_e32 v31, 0, v31, vcc
	s_waitcnt vmcnt(17)
	v_cndmask_b32_e32 v32, 0, v32, vcc
	s_waitcnt vmcnt(16)
	v_cndmask_b32_e32 v33, 0, v33, vcc
	s_waitcnt vmcnt(15)
	v_cndmask_b32_e32 v34, 0, v34, vcc
	s_waitcnt vmcnt(14)
	v_cndmask_b32_e32 v35, 0, v35, vcc
	s_waitcnt vmcnt(13)
	v_cndmask_b32_e32 v36, 0, v36, vcc
	s_waitcnt vmcnt(12)
	v_cndmask_b32_e32 v37, 0, v37, vcc
	s_waitcnt vmcnt(11)
	v_cndmask_b32_e32 v46, 0, v46, vcc
	s_waitcnt vmcnt(10)
	v_cndmask_b32_e32 v47, 0, v47, vcc
	s_waitcnt vmcnt(9)
	v_cndmask_b32_e32 v48, 0, v48, vcc
	s_waitcnt vmcnt(8)
	v_cndmask_b32_e32 v49, 0, v49, vcc
	s_waitcnt vmcnt(7)
	v_cndmask_b32_e32 v50, 0, v50, vcc
	s_waitcnt vmcnt(6)
	v_cndmask_b32_e32 v51, 0, v51, vcc
	s_waitcnt vmcnt(5)
	v_cndmask_b32_e32 v52, 0, v52, vcc
	s_waitcnt vmcnt(4)
	v_cndmask_b32_e32 v53, 0, v53, vcc
	s_waitcnt vmcnt(3)
	v_cndmask_b32_e32 v54, 0, v54, vcc
	s_waitcnt vmcnt(2)
	v_cndmask_b32_e32 v55, 0, v55, vcc
	s_waitcnt vmcnt(1)
	v_cndmask_b32_e32 v56, 0, v56, vcc
	s_waitcnt vmcnt(0)
	v_cndmask_b32_e32 v57, 0, v57, vcc
	ds_write2_b32 v13, v2, v6 offset1:66
	ds_write2_b32 v13, v7, v21 offset0:132 offset1:198
	ds_write2_b32 v14, v22, v23 offset0:8 offset1:74
	ds_write2_b32 v14, v24, v25 offset0:140 offset1:206
	ds_write2_b32 v15, v26, v27 offset0:16 offset1:82
	ds_write2_b32 v15, v28, v29 offset0:148 offset1:214
	ds_write2_b32 v16, v30, v31 offset0:24 offset1:90
	ds_write2_b32 v16, v32, v33 offset0:156 offset1:222
	ds_write2_b32 v17, v34, v35 offset0:32 offset1:98
	ds_write2_b32 v17, v36, v37 offset0:164 offset1:230
	ds_write2_b32 v18, v46, v47 offset0:40 offset1:106
	ds_write2_b32 v18, v48, v49 offset0:172 offset1:238
	ds_write2_b32 v19, v50, v51 offset0:48 offset1:114
	ds_write2_b32 v19, v52, v53 offset0:180 offset1:246
	ds_write2_b32 v20, v54, v55 offset0:56 offset1:122
	ds_write2_b32 v20, v56, v57 offset0:188 offset1:254
	s_waitcnt vmcnt(0) expcnt(0) lgkmcnt(0)
	ds_read2_b32 v[6:7], v10 offset0:33 offset1:41
	ds_read2_b32 v[24:25], v10 offset1:8
	ds_read2_b32 v[26:27], v10 offset0:66 offset1:74
	ds_read2_b32 v[28:29], v10 offset0:99 offset1:107
	ds_read2_b32 v[30:31], v10 offset0:132 offset1:140
	ds_read2_b32 v[32:33], v10 offset0:165 offset1:173
	ds_read2_b32 v[34:35], v10 offset0:198 offset1:206
	ds_read2_b32 v[36:37], v10 offset0:231 offset1:239
	ds_read2_b32 v[46:47], v10 offset0:16 offset1:24
	ds_read2_b32 v[48:49], v10 offset0:49 offset1:57
	ds_read2_b32 v[50:51], v10 offset0:82 offset1:90
	ds_read2_b32 v[52:53], v10 offset0:115 offset1:123
	ds_read2_b32 v[54:55], v10 offset0:148 offset1:156
	ds_read2_b32 v[56:57], v10 offset0:181 offset1:189
	ds_read2_b32 v[58:59], v10 offset0:214 offset1:222
	ds_read2_b32 v[60:61], v10 offset0:247 offset1:255
	s_waitcnt lgkmcnt(14)
	v_cvt_pk_bf16_f32 v22, v24, v6
	s_waitcnt lgkmcnt(12)
	v_cvt_pk_bf16_f32 v23, v26, v28
	v_cvt_pk_bf16_f32 v26, v25, v7
	s_waitcnt lgkmcnt(10)
	v_cvt_pk_bf16_f32 v24, v30, v32
	s_waitcnt lgkmcnt(8)
	v_cvt_pk_bf16_f32 v25, v34, v36
	v_cvt_pk_bf16_f32 v27, v27, v29
	v_cvt_pk_bf16_f32 v28, v31, v33
	v_cvt_pk_bf16_f32 v29, v35, v37
	s_waitcnt lgkmcnt(6)
	v_cvt_pk_bf16_f32 v30, v46, v48
	s_waitcnt lgkmcnt(4)
	v_cvt_pk_bf16_f32 v31, v50, v52
	s_waitcnt lgkmcnt(2)
	v_cvt_pk_bf16_f32 v32, v54, v56
	s_waitcnt lgkmcnt(0)
	v_cvt_pk_bf16_f32 v33, v58, v60
	v_cvt_pk_bf16_f32 v34, v47, v49
	v_cvt_pk_bf16_f32 v35, v51, v53
	v_cvt_pk_bf16_f32 v36, v55, v57
	v_cvt_pk_bf16_f32 v37, v59, v61
	global_store_dwordx4 v[38:39], v[22:25], off
	global_store_dwordx4 v[40:41], v[26:29], off
	global_store_dwordx4 v[42:43], v[30:33], off
	global_store_dwordx4 v[44:45], v[34:37], off
	s_waitcnt lgkmcnt(0)
	s_cbranch_scc0 .LBB0_11
	s_branch .LBB0_6

; template <class Map>
; __device__ __forceinline__ void transpose_item(const float* W, int K, int N, bf16_t* WT, float* scr, int item, int nblk, int lane, Map srccol) {
;     const int kb = item / nblk, nb = item % nblk, k0 = 64 * kb, n0 = 32 * nb;
;     const int sc = srccol(n0 + (lane & 31));
;     float tv[32];
;     const float* wp = W + (size_t)(k0 + (lane >> 5)) * N + (sc >= 0 ? sc : 0);
; #pragma unroll
;     for (int i = 0; i < 32; ++i) tv[i] = wp[(size_t)(2 * i) * N];
; #pragma unroll
;     for (int i = 0; i < 32; ++i) { const int kk = 2 * i + (lane >> 5); scr[kk * 33 + (lane & 31)] = sc >= 0 ? tv[i] : 0.f; }
.LBB0_218:
	s_ashr_i32 s6, s19, 31
	s_lshr_b32 s6, s6, 27
	s_add_i32 s6, s19, s6
	s_ashr_i32 s22, s6, 5
	s_andn2_b32 s6, s6, 31
	s_lshl_b32 s10, s22, 6
	s_lshl_b32 s7, s22, 10
	s_sub_i32 s6, s19, s6
	v_subrev_u32_e32 v0, s7, v13
	v_or_b32_e32 v16, s10, v6
	v_and_b32_e32 v15, 24, v14
	v_and_b32_e32 v0, 0xffffffe3, v0
	v_ashrrev_i32_e32 v17, 31, v16
	s_cmp_gt_i32 s6, -1
	v_or3_b32 v0, v0, v9, v15
	v_lshlrev_b64 v[16:17], 12, v[16:17]
	s_cselect_b64 vcc, -1, 0
	v_lshl_add_u64 v[16:17], s[2:3], 0, v[16:17]
	v_cndmask_b32_e32 v0, 0, v0, vcc
	v_lshl_add_u64 v[40:41], v[0:1], 2, v[16:17]
	v_add_co_u32_e64 v16, s[6:7], s63, v40
	global_load_dword v44, v[40:41], off
	s_nop 0
	v_addc_co_u32_e64 v17, s[6:7], 0, v41, s[6:7]
	global_load_dword v45, v[16:17], off
	v_add_co_u32_e64 v16, s[6:7], s23, v40
	s_mul_i32 s22, s22, 0xffd40000
	s_nop 0
	v_addc_co_u32_e64 v17, s[6:7], 0, v41, s[6:7]
	global_load_dword v46, v[16:17], off
	v_add_co_u32_e64 v16, s[6:7], s58, v40
	s_ashr_i32 s11, s10, 31
	s_nop 0
	v_addc_co_u32_e64 v17, s[6:7], 0, v41, s[6:7]
	global_load_dword v47, v[16:17], off
	v_add_co_u32_e64 v16, s[6:7], s60, v40
	s_add_i32 s19, s19, s13
	s_nop 0
	v_addc_co_u32_e64 v17, s[6:7], 0, v41, s[6:7]
	global_load_dword v48, v[16:17], off
	v_add_co_u32_e64 v16, s[6:7], s26, v40
	v_add_u32_e32 v13, s20, v13
	s_nop 0
	v_addc_co_u32_e64 v17, s[6:7], 0, v41, s[6:7]
	global_load_dword v49, v[16:17], off
	v_add_co_u32_e64 v16, s[6:7], s29, v40
	v_add_u32_e32 v14, s21, v14
	s_nop 0
	v_addc_co_u32_e64 v17, s[6:7], 0, v41, s[6:7]
	global_load_dword v36, v[16:17], off
	v_add_co_u32_e64 v16, s[6:7], s30, v40
	s_cmpk_gt_i32 s19, 0x57f
	s_nop 0
	v_addc_co_u32_e64 v17, s[6:7], 0, v41, s[6:7]
	global_load_dword v37, v[16:17], off
	v_add_co_u32_e64 v16, s[6:7], s24, v40
	s_waitcnt vmcnt(1)
	v_cndmask_b32_e32 v36, 0, v36, vcc
	v_addc_co_u32_e64 v17, s[6:7], 0, v41, s[6:7]
	global_load_dword v38, v[16:17], off
	v_add_co_u32_e64 v16, s[6:7], s55, v40
	s_waitcnt vmcnt(1)
	v_cndmask_b32_e32 v37, 0, v37, vcc
	v_addc_co_u32_e64 v17, s[6:7], 0, v41, s[6:7]
	global_load_dword v39, v[16:17], off
	v_add_co_u32_e64 v16, s[6:7], s56, v40
	s_nop 1
	v_addc_co_u32_e64 v17, s[6:7], 0, v41, s[6:7]
	global_load_dword v32, v[16:17], off
	v_add_co_u32_e64 v16, s[6:7], s57, v40
	s_waitcnt vmcnt(0)
	v_cndmask_b32_e32 v32, 0, v32, vcc
	v_addc_co_u32_e64 v17, s[6:7], 0, v41, s[6:7]
	global_load_dword v33, v[16:17], off
	v_add_co_u32_e64 v16, s[6:7], s59, v40
	s_waitcnt vmcnt(0)
	v_cndmask_b32_e32 v33, 0, v33, vcc
	v_addc_co_u32_e64 v17, s[6:7], 0, v41, s[6:7]
	global_load_dword v34, v[16:17], off
	v_add_co_u32_e64 v16, s[6:7], s25, v40
	s_nop 1
	v_addc_co_u32_e64 v17, s[6:7], 0, v41, s[6:7]
	global_load_dword v35, v[16:17], off
	v_add_co_u32_e64 v16, s[6:7], s27, v40
	s_nop 1
	v_addc_co_u32_e64 v17, s[6:7], 0, v41, s[6:7]
	global_load_dword v28, v[16:17], off
	v_add_co_u32_e64 v16, s[6:7], s28, v40
	s_waitcnt vmcnt(0)
	v_cndmask_b32_e32 v28, 0, v28, vcc
	v_addc_co_u32_e64 v17, s[6:7], 0, v41, s[6:7]
	global_load_dword v29, v[16:17], off
	v_add_co_u32_e64 v16, s[6:7], s31, v40
	s_waitcnt vmcnt(0)
	v_cndmask_b32_e32 v29, 0, v29, vcc
	v_addc_co_u32_e64 v17, s[6:7], 0, v41, s[6:7]
	global_load_dword v30, v[16:17], off
	v_add_co_u32_e64 v16, s[6:7], s34, v40
	s_nop 1
	v_addc_co_u32_e64 v17, s[6:7], 0, v41, s[6:7]
	global_load_dword v31, v[16:17], off
	v_add_co_u32_e64 v16, s[6:7], s35, v40
	s_nop 1
	v_addc_co_u32_e64 v17, s[6:7], 0, v41, s[6:7]
	global_load_dword v24, v[16:17], off
	v_add_co_u32_e64 v16, s[6:7], s1, v40
	s_waitcnt vmcnt(0)
	v_cndmask_b32_e32 v24, 0, v24, vcc
	v_addc_co_u32_e64 v17, s[6:7], 0, v41, s[6:7]
	global_load_dword v25, v[16:17], off
	v_add_co_u32_e64 v16, s[6:7], s40, v40
	s_waitcnt vmcnt(0)
	v_cndmask_b32_e32 v25, 0, v25, vcc
	v_addc_co_u32_e64 v17, s[6:7], 0, v41, s[6:7]
	global_load_dword v26, v[16:17], off
	v_add_co_u32_e64 v16, s[6:7], s41, v40
	s_nop 1
	v_addc_co_u32_e64 v17, s[6:7], 0, v41, s[6:7]
	global_load_dword v27, v[16:17], off
	v_add_co_u32_e64 v16, s[6:7], s33, v40
	s_nop 1
	v_addc_co_u32_e64 v17, s[6:7], 0, v41, s[6:7]
	global_load_dword v20, v[16:17], off
	v_add_co_u32_e64 v16, s[6:7], s44, v40
	s_waitcnt vmcnt(0)
	v_cndmask_b32_e32 v20, 0, v20, vcc
	v_addc_co_u32_e64 v17, s[6:7], 0, v41, s[6:7]
	global_load_dword v21, v[16:17], off
	v_add_co_u32_e64 v16, s[6:7], s0, v40
	s_waitcnt vmcnt(0)
	v_cndmask_b32_e32 v21, 0, v21, vcc
	v_addc_co_u32_e64 v17, s[6:7], 0, v41, s[6:7]
	global_load_dword v22, v[16:17], off
	v_add_co_u32_e64 v16, s[6:7], s45, v40
	s_nop 1
	v_addc_co_u32_e64 v17, s[6:7], 0, v41, s[6:7]
	global_load_dword v23, v[16:17], off
	v_add_co_u32_e64 v16, s[6:7], s46, v40
	s_nop 1
	v_addc_co_u32_e64 v17, s[6:7], 0, v41, s[6:7]
	v_add_co_u32_e64 v18, s[6:7], s47, v40
	global_load_dword v16, v[16:17], off
	s_nop 0
	v_addc_co_u32_e64 v19, s[6:7], 0, v41, s[6:7]
	global_load_dword v17, v[18:19], off
	v_add_co_u32_e64 v18, s[6:7], s48, v40
	s_waitcnt vmcnt(1)
; __device__ __forceinline__ unsigned pk2(float lo, float hi) { unsigned r; asm("v_cvt_pk_bf16_f32 %0, %1, %2" : "=v"(r) : "v"(lo), "v"(hi)); return r; }
; template <class Map>
; __device__ __forceinline__ void transpose_item(const float* W, int K, int N, bf16_t* WT, float* scr, int item, int nblk, int lane, Map srccol) {
;     ...
;     for (int i = 0; i < 32; ++i) { const int kk = 2 * i + (lane >> 5); scr[kk * 33 + (lane & 31)] = sc >= 0 ? tv[i] : 0.f; }
;     __builtin_amdgcn_s_waitcnt(0); asm volatile("" ::: "memory");
;     const int c = lane & 7;
; #pragma unroll
;     for (int j = 0; j < 4; ++j) { const int n = (lane >> 3) + 8 * j; const float* s = scr + (8 * c) * 33 + n;
;         u32x4 o; o.x = pk2(s[0 * 33], s[1 * 33]); o.y = pk2(s[2 * 33], s[3 * 33]); o.z = pk2(s[4 * 33], s[5 * 33]); o.w = pk2(s[6 * 33], s[7 * 33]);
;         *(u32x4*)(WT + (size_t)(n0 + n) * K + k0 + 8 * c) = o; }
;     __builtin_amdgcn_s_waitcnt(0); asm volatile("" ::: "memory");
	v_cndmask_b32_e32 v16, 0, v16, vcc
	v_addc_co_u32_e64 v19, s[6:7], 0, v41, s[6:7]
	v_add_co_u32_e64 v42, s[6:7], s49, v40
	global_load_dword v18, v[18:19], off
	s_nop 0
	v_addc_co_u32_e64 v43, s[6:7], 0, v41, s[6:7]
	global_load_dword v19, v[42:43], off
	v_add_co_u32_e64 v42, s[6:7], s50, v40
	s_waitcnt vmcnt(2)
	v_cndmask_b32_e32 v17, 0, v17, vcc
	v_addc_co_u32_e64 v43, s[6:7], 0, v41, s[6:7]
	v_add_co_u32_e64 v40, s[6:7], s52, v40
	global_load_dword v0, v[42:43], off
	s_nop 0
	v_addc_co_u32_e64 v41, s[6:7], 0, v41, s[6:7]
	global_load_dword v15, v[40:41], off
	v_add_u32_e32 v42, 0x400, v7
	ds_write2_b32 v42, v36, v37 offset0:140 offset1:206
	v_cndmask_b32_e32 v36, 0, v38, vcc
	v_add_u32_e32 v38, 0x800, v7
	ds_write2_b32 v38, v32, v33 offset0:148 offset1:214
	v_cndmask_b32_e32 v32, 0, v34, vcc
	v_add_u32_e32 v34, 0xc00, v7
	ds_write2_b32 v34, v28, v29 offset0:156 offset1:222
	v_cndmask_b32_e32 v28, 0, v30, vcc
	v_add_u32_e32 v30, 0x1000, v7
	v_cndmask_b32_e32 v40, 0, v44, vcc
	v_cndmask_b32_e32 v41, 0, v45, vcc
	ds_write2_b32 v30, v24, v25 offset0:164 offset1:230
	v_cndmask_b32_e32 v24, 0, v26, vcc
	v_add_u32_e32 v26, 0x1400, v7
	ds_write2_b32 v7, v40, v41 offset1:66
	v_cndmask_b32_e32 v40, 0, v46, vcc
	v_cndmask_b32_e32 v41, 0, v47, vcc
	ds_write2_b32 v26, v20, v21 offset0:172 offset1:238
	v_cndmask_b32_e32 v20, 0, v22, vcc
	v_add_u32_e32 v22, 0x1800, v7
	ds_write2_b32 v7, v40, v41 offset0:132 offset1:198
	v_cndmask_b32_e32 v40, 0, v48, vcc
	v_cndmask_b32_e32 v41, 0, v49, vcc
	v_cndmask_b32_e32 v37, 0, v39, vcc
	v_cndmask_b32_e32 v33, 0, v35, vcc
	v_cndmask_b32_e32 v29, 0, v31, vcc
	v_cndmask_b32_e32 v25, 0, v27, vcc
	v_cndmask_b32_e32 v21, 0, v23, vcc
	ds_write2_b32 v22, v16, v17 offset0:180 offset1:246
	ds_write2_b32 v42, v40, v41 offset0:8 offset1:74
	ds_write2_b32 v38, v36, v37 offset0:16 offset1:82
	ds_write2_b32 v34, v32, v33 offset0:24 offset1:90
	ds_write2_b32 v30, v28, v29 offset0:32 offset1:98
	ds_write2_b32 v26, v24, v25 offset0:40 offset1:106
	ds_write2_b32 v22, v20, v21 offset0:48 offset1:114
	v_add_u32_e32 v38, s22, v12
	v_lshl_add_u64 v[20:21], s[10:11], 1, v[2:3]
	v_ashrrev_i32_e32 v39, 31, v38
	v_lshl_add_u64 v[40:41], v[38:39], 1, v[20:21]
	s_mul_i32 s6, s13, 0x16000
	v_add_u32_e32 v12, s6, v12
	s_waitcnt vmcnt(3)
	v_cndmask_b32_e32 v16, 0, v18, vcc
	v_add_u32_e32 v18, 0x1c00, v7
	s_waitcnt vmcnt(2)
	v_cndmask_b32_e32 v17, 0, v19, vcc
	ds_write2_b32 v18, v16, v17 offset0:56 offset1:122
	s_waitcnt vmcnt(1)
	v_cndmask_b32_e32 v0, 0, v0, vcc
	s_waitcnt vmcnt(0)
	v_cndmask_b32_e32 v15, 0, v15, vcc
	ds_write2_b32 v18, v0, v15 offset0:188 offset1:254
	s_waitcnt vmcnt(0) expcnt(0) lgkmcnt(0)
	ds_read2_b32 v[22:23], v8 offset0:33 offset1:41
	ds_read2_b32 v[24:25], v8 offset1:8
	ds_read2_b32 v[26:27], v8 offset0:66 offset1:74
	ds_read2_b32 v[28:29], v8 offset0:99 offset1:107
	ds_read2_b32 v[30:31], v8 offset0:132 offset1:140
	ds_read2_b32 v[32:33], v8 offset0:165 offset1:173
	ds_read2_b32 v[34:35], v8 offset0:198 offset1:206
	ds_read2_b32 v[36:37], v8 offset0:231 offset1:239
	s_waitcnt lgkmcnt(6)
	v_cvt_pk_bf16_f32 v16, v24, v22
	v_add_u32_e32 v22, 0x5800, v38
	s_waitcnt lgkmcnt(4)
	v_cvt_pk_bf16_f32 v17, v26, v28
	s_waitcnt lgkmcnt(2)
	v_cvt_pk_bf16_f32 v18, v30, v32
	s_waitcnt lgkmcnt(0)
	v_cvt_pk_bf16_f32 v19, v34, v36
	global_store_dwordx4 v[40:41], v[16:19], off
	v_add_u32_e32 v40, 0xb000, v38
	v_ashrrev_i32_e32 v41, 31, v40
	v_cvt_pk_bf16_f32 v16, v25, v23
	v_ashrrev_i32_e32 v23, 31, v22
	v_lshl_add_u64 v[22:23], v[22:23], 1, v[20:21]
	v_cvt_pk_bf16_f32 v17, v27, v29
	v_cvt_pk_bf16_f32 v18, v31, v33
	v_cvt_pk_bf16_f32 v19, v35, v37
	global_store_dwordx4 v[22:23], v[16:19], off
	ds_read2_b32 v[22:23], v8 offset0:16 offset1:24
	ds_read2_b32 v[24:25], v8 offset0:49 offset1:57
	ds_read2_b32 v[26:27], v8 offset0:82 offset1:90
	ds_read2_b32 v[28:29], v8 offset0:115 offset1:123
	ds_read2_b32 v[30:31], v8 offset0:148 offset1:156
	ds_read2_b32 v[32:33], v8 offset0:181 offset1:189
	ds_read2_b32 v[34:35], v8 offset0:214 offset1:222
	ds_read2_b32 v[36:37], v8 offset0:247 offset1:255
	s_waitcnt lgkmcnt(6)
	v_cvt_pk_bf16_f32 v16, v22, v24
	v_lshl_add_u64 v[40:41], v[40:41], 1, v[20:21]
	v_add_u32_e32 v22, 0x10800, v38
	s_waitcnt lgkmcnt(4)
	v_cvt_pk_bf16_f32 v17, v26, v28
	s_waitcnt lgkmcnt(2)
	v_cvt_pk_bf16_f32 v18, v30, v32
	s_waitcnt lgkmcnt(0)
	v_cvt_pk_bf16_f32 v19, v34, v36
	global_store_dwordx4 v[40:41], v[16:19], off
	s_nop 1
	v_cvt_pk_bf16_f32 v16, v23, v25
	v_ashrrev_i32_e32 v23, 31, v22
	v_lshl_add_u64 v[20:21], v[22:23], 1, v[20:21]
	v_cvt_pk_bf16_f32 v17, v27, v29
	v_cvt_pk_bf16_f32 v18, v31, v33
	v_cvt_pk_bf16_f32 v19, v35, v37
	global_store_dwordx4 v[20:21], v[16:19], off
	s_waitcnt lgkmcnt(0)
	s_cbranch_scc0 .LBB0_218
	s_branch .LBB0_213

; template <class Map>
; __device__ __forceinline__ void transpose_item(const float* W, int K, int N, bf16_t* WT, float* scr, int item, int nblk, int lane, Map srccol) {
;     const int kb = item / nblk, nb = item % nblk, k0 = 64 * kb, n0 = 32 * nb;
;     const int sc = srccol(n0 + (lane & 31));
;     float tv[32];
;     const float* wp = W + (size_t)(k0 + (lane >> 5)) * N + (sc >= 0 ? sc : 0);
; #pragma unroll
;     for (int i = 0; i < 32; ++i) tv[i] = wp[(size_t)(2 * i) * N];
; #pragma unroll
;     for (int i = 0; i < 32; ++i) { const int kk = 2 * i + (lane >> 5); scr[kk * 33 + (lane & 31)] = sc >= 0 ? tv[i] : 0.f; }
.LBB0_227:
	s_ashr_i32 s6, s13, 31
	s_lshr_b32 s6, s6, 27
	s_add_i32 s6, s13, s6
	s_ashr_i32 s15, s6, 5
	s_lshl_b32 s7, s15, 10
	v_subrev_u32_e32 v0, s7, v12
	s_andn2_b32 s6, s6, 31
	s_lshl_b32 s8, s15, 6
	v_and_b32_e32 v14, 24, v13
	v_and_b32_e32 v0, 0xffffffe3, v0
	s_sub_i32 s6, s13, s6
	v_or3_b32 v0, v0, v8, v14
	v_or_b32_e32 v14, s8, v6
	v_ashrrev_i32_e32 v15, 31, v14
	s_cmp_gt_i32 s6, -1
	v_lshlrev_b64 v[14:15], 12, v[14:15]
	s_cselect_b64 vcc, -1, 0
	v_lshl_add_u64 v[14:15], s[2:3], 0, v[14:15]
	v_cndmask_b32_e32 v0, 0, v0, vcc
	v_lshl_add_u64 v[40:41], v[0:1], 2, v[14:15]
	v_add_co_u32_e64 v14, s[6:7], s63, v40
	global_load_dword v39, v[40:41], off
	s_nop 0
	v_addc_co_u32_e64 v15, s[6:7], 0, v41, s[6:7]
	global_load_dword v44, v[14:15], off
	v_add_co_u32_e64 v14, s[6:7], s22, v40
	s_mul_i32 s15, s15, 0xffd40000
	s_nop 0
	v_addc_co_u32_e64 v15, s[6:7], 0, v41, s[6:7]
	global_load_dword v45, v[14:15], off
	v_add_co_u32_e64 v14, s[6:7], s58, v40
	s_ashr_i32 s9, s8, 31
	s_nop 0
	v_addc_co_u32_e64 v15, s[6:7], 0, v41, s[6:7]
	global_load_dword v46, v[14:15], off
	v_add_co_u32_e64 v14, s[6:7], s60, v40
	s_add_i32 s13, s13, s4
	s_nop 0
	v_addc_co_u32_e64 v15, s[6:7], 0, v41, s[6:7]
	global_load_dword v47, v[14:15], off
	v_add_co_u32_e64 v14, s[6:7], s18, v40
	v_add_u32_e32 v12, s97, v12
	s_nop 0
	v_addc_co_u32_e64 v15, s[6:7], 0, v41, s[6:7]
	global_load_dword v48, v[14:15], off
	v_add_co_u32_e64 v14, s[6:7], s21, v40
	v_add_u32_e32 v13, s14, v13
	s_nop 0
	v_addc_co_u32_e64 v15, s[6:7], 0, v41, s[6:7]
	global_load_dword v35, v[14:15], off
	v_add_co_u32_e64 v14, s[6:7], s23, v40
	s_cmpk_gt_i32 s13, 0x57f
	s_nop 0
	v_addc_co_u32_e64 v15, s[6:7], 0, v41, s[6:7]
	global_load_dword v36, v[14:15], off
	v_add_co_u32_e64 v14, s[6:7], s16, v40
	s_waitcnt vmcnt(7)
	v_cndmask_b32_e32 v39, 0, v39, vcc
	v_addc_co_u32_e64 v15, s[6:7], 0, v41, s[6:7]
	global_load_dword v37, v[14:15], off
	v_add_co_u32_e64 v14, s[6:7], s55, v40
	s_waitcnt vmcnt(2)
	v_cndmask_b32_e32 v35, 0, v35, vcc
	v_addc_co_u32_e64 v15, s[6:7], 0, v41, s[6:7]
	global_load_dword v38, v[14:15], off
	v_add_co_u32_e64 v14, s[6:7], s56, v40
	s_waitcnt vmcnt(2)
	v_cndmask_b32_e32 v36, 0, v36, vcc
	v_addc_co_u32_e64 v15, s[6:7], 0, v41, s[6:7]
	global_load_dword v31, v[14:15], off
	v_add_co_u32_e64 v14, s[6:7], s57, v40
	s_waitcnt vmcnt(0)
	v_cndmask_b32_e32 v31, 0, v31, vcc
	v_addc_co_u32_e64 v15, s[6:7], 0, v41, s[6:7]
	global_load_dword v32, v[14:15], off
	v_add_co_u32_e64 v14, s[6:7], s59, v40
	s_waitcnt vmcnt(0)
	v_cndmask_b32_e32 v32, 0, v32, vcc
	v_addc_co_u32_e64 v15, s[6:7], 0, v41, s[6:7]
	global_load_dword v33, v[14:15], off
	v_add_co_u32_e64 v14, s[6:7], s17, v40
	s_nop 1
	v_addc_co_u32_e64 v15, s[6:7], 0, v41, s[6:7]
	global_load_dword v34, v[14:15], off
	v_add_co_u32_e64 v14, s[6:7], s19, v40
	s_nop 1
	v_addc_co_u32_e64 v15, s[6:7], 0, v41, s[6:7]
	global_load_dword v27, v[14:15], off
	v_add_co_u32_e64 v14, s[6:7], s20, v40
	s_waitcnt vmcnt(0)
	v_cndmask_b32_e32 v27, 0, v27, vcc
	v_addc_co_u32_e64 v15, s[6:7], 0, v41, s[6:7]
	global_load_dword v28, v[14:15], off
	v_add_co_u32_e64 v14, s[6:7], s24, v40
	s_waitcnt vmcnt(0)
	v_cndmask_b32_e32 v28, 0, v28, vcc
	v_addc_co_u32_e64 v15, s[6:7], 0, v41, s[6:7]
	global_load_dword v29, v[14:15], off
	v_add_co_u32_e64 v14, s[6:7], s25, v40
	s_nop 1
	v_addc_co_u32_e64 v15, s[6:7], 0, v41, s[6:7]
	global_load_dword v30, v[14:15], off
	v_add_co_u32_e64 v14, s[6:7], s26, v40
	s_nop 1
	v_addc_co_u32_e64 v15, s[6:7], 0, v41, s[6:7]
	global_load_dword v23, v[14:15], off
	v_add_co_u32_e64 v14, s[6:7], s1, v40
	s_waitcnt vmcnt(0)
	v_cndmask_b32_e32 v23, 0, v23, vcc
	v_addc_co_u32_e64 v15, s[6:7], 0, v41, s[6:7]
	global_load_dword v24, v[14:15], off
	v_add_co_u32_e64 v14, s[6:7], s27, v40
	s_waitcnt vmcnt(0)
	v_cndmask_b32_e32 v24, 0, v24, vcc
	v_addc_co_u32_e64 v15, s[6:7], 0, v41, s[6:7]
	global_load_dword v25, v[14:15], off
	v_add_co_u32_e64 v14, s[6:7], s28, v40
	s_nop 1
	v_addc_co_u32_e64 v15, s[6:7], 0, v41, s[6:7]
	global_load_dword v26, v[14:15], off
	v_add_co_u32_e64 v14, s[6:7], s33, v40
	s_nop 1
	v_addc_co_u32_e64 v15, s[6:7], 0, v41, s[6:7]
	global_load_dword v19, v[14:15], off
	v_add_co_u32_e64 v14, s[6:7], s29, v40
	s_waitcnt vmcnt(0)
	v_cndmask_b32_e32 v19, 0, v19, vcc
	v_addc_co_u32_e64 v15, s[6:7], 0, v41, s[6:7]
	global_load_dword v20, v[14:15], off
	v_add_co_u32_e64 v14, s[6:7], s0, v40
	s_waitcnt vmcnt(0)
	v_cndmask_b32_e32 v20, 0, v20, vcc
	v_addc_co_u32_e64 v15, s[6:7], 0, v41, s[6:7]
	global_load_dword v21, v[14:15], off
	v_add_co_u32_e64 v14, s[6:7], s30, v40
	s_nop 1
	v_addc_co_u32_e64 v15, s[6:7], 0, v41, s[6:7]
	global_load_dword v22, v[14:15], off
	v_add_co_u32_e64 v14, s[6:7], s31, v40
	s_nop 1
	v_addc_co_u32_e64 v15, s[6:7], 0, v41, s[6:7]
	v_add_co_u32_e64 v16, s[6:7], s34, v40
	global_load_dword v15, v[14:15], off
	s_nop 0
	v_addc_co_u32_e64 v17, s[6:7], 0, v41, s[6:7]
	v_add_co_u32_e64 v42, s[6:7], s35, v40
	global_load_dword v16, v[16:17], off
	s_nop 0
	v_addc_co_u32_e64 v43, s[6:7], 0, v41, s[6:7]
	global_load_dword v17, v[42:43], off
	v_add_co_u32_e64 v42, s[6:7], s40, v40
	s_waitcnt vmcnt(2)
; __device__ __forceinline__ unsigned pk2(float lo, float hi) { unsigned r; asm("v_cvt_pk_bf16_f32 %0, %1, %2" : "=v"(r) : "v"(lo), "v"(hi)); return r; }
; template <class Map>
; __device__ __forceinline__ void transpose_item(const float* W, int K, int N, bf16_t* WT, float* scr, int item, int nblk, int lane, Map srccol) {
;     ...
;     for (int i = 0; i < 32; ++i) { const int kk = 2 * i + (lane >> 5); scr[kk * 33 + (lane & 31)] = sc >= 0 ? tv[i] : 0.f; }
;     __builtin_amdgcn_s_waitcnt(0); asm volatile("" ::: "memory");
;     const int c = lane & 7;
; #pragma unroll
;     for (int j = 0; j < 4; ++j) { const int n = (lane >> 3) + 8 * j; const float* s = scr + (8 * c) * 33 + n;
;         u32x4 o; o.x = pk2(s[0 * 33], s[1 * 33]); o.y = pk2(s[2 * 33], s[3 * 33]); o.z = pk2(s[4 * 33], s[5 * 33]); o.w = pk2(s[6 * 33], s[7 * 33]);
;         *(u32x4*)(WT + (size_t)(n0 + n) * K + k0 + 8 * c) = o; }
;     __builtin_amdgcn_s_waitcnt(0); asm volatile("" ::: "memory");
	v_cndmask_b32_e32 v15, 0, v15, vcc
	v_addc_co_u32_e64 v43, s[6:7], 0, v41, s[6:7]
	global_load_dword v18, v[42:43], off
	v_add_co_u32_e64 v42, s[6:7], s41, v40
	s_waitcnt vmcnt(2)
	v_cndmask_b32_e32 v16, 0, v16, vcc
	v_addc_co_u32_e64 v43, s[6:7], 0, v41, s[6:7]
	v_add_co_u32_e64 v40, s[6:7], s44, v40
	global_load_dword v0, v[42:43], off
	s_nop 0
	v_addc_co_u32_e64 v41, s[6:7], 0, v41, s[6:7]
	global_load_dword v14, v[40:41], off
	v_add_u32_e32 v41, 0x400, v7
	ds_write2_b32 v41, v35, v36 offset0:140 offset1:206
	v_cndmask_b32_e32 v35, 0, v37, vcc
	v_add_u32_e32 v37, 0x800, v7
	ds_write2_b32 v37, v31, v32 offset0:148 offset1:214
	v_cndmask_b32_e32 v31, 0, v33, vcc
	v_add_u32_e32 v33, 0xc00, v7
	ds_write2_b32 v33, v27, v28 offset0:156 offset1:222
	v_cndmask_b32_e32 v27, 0, v29, vcc
	v_add_u32_e32 v29, 0x1000, v7
	v_cndmask_b32_e32 v40, 0, v44, vcc
	ds_write2_b32 v29, v23, v24 offset0:164 offset1:230
	v_cndmask_b32_e32 v23, 0, v25, vcc
	v_add_u32_e32 v25, 0x1400, v7
	ds_write2_b32 v7, v39, v40 offset1:66
	v_cndmask_b32_e32 v39, 0, v45, vcc
	v_cndmask_b32_e32 v40, 0, v46, vcc
	ds_write2_b32 v25, v19, v20 offset0:172 offset1:238
	v_cndmask_b32_e32 v19, 0, v21, vcc
	v_add_u32_e32 v21, 0x1800, v7
	ds_write2_b32 v7, v39, v40 offset0:132 offset1:198
	v_cndmask_b32_e32 v39, 0, v47, vcc
	v_cndmask_b32_e32 v40, 0, v48, vcc
	v_cndmask_b32_e32 v36, 0, v38, vcc
	v_cndmask_b32_e32 v32, 0, v34, vcc
	v_cndmask_b32_e32 v28, 0, v30, vcc
	v_cndmask_b32_e32 v24, 0, v26, vcc
	v_cndmask_b32_e32 v20, 0, v22, vcc
	ds_write2_b32 v21, v15, v16 offset0:180 offset1:246
	s_waitcnt vmcnt(3)
	v_cndmask_b32_e32 v15, 0, v17, vcc
	v_add_u32_e32 v17, 0x1c00, v7
	ds_write2_b32 v41, v39, v40 offset0:8 offset1:74
	ds_write2_b32 v37, v35, v36 offset0:16 offset1:82
	ds_write2_b32 v33, v31, v32 offset0:24 offset1:90
	ds_write2_b32 v29, v27, v28 offset0:32 offset1:98
	ds_write2_b32 v25, v23, v24 offset0:40 offset1:106
	ds_write2_b32 v21, v19, v20 offset0:48 offset1:114
	v_add_u32_e32 v36, s15, v11
	v_ashrrev_i32_e32 v37, 31, v36
	s_mul_i32 s6, s4, 0x16000
	v_add_u32_e32 v11, s6, v11
	s_waitcnt vmcnt(2)
	v_cndmask_b32_e32 v16, 0, v18, vcc
	ds_write2_b32 v17, v15, v16 offset0:56 offset1:122
	v_lshl_add_u64 v[18:19], s[8:9], 1, v[2:3]
	v_lshl_add_u64 v[38:39], v[36:37], 1, v[18:19]
	s_waitcnt vmcnt(1)
	v_cndmask_b32_e32 v0, 0, v0, vcc
	s_waitcnt vmcnt(0)
	v_cndmask_b32_e32 v14, 0, v14, vcc
	ds_write2_b32 v17, v0, v14 offset0:188 offset1:254
	s_waitcnt vmcnt(0) expcnt(0) lgkmcnt(0)
	ds_read2_b32 v[20:21], v4 offset0:33 offset1:41
	ds_read2_b32 v[22:23], v4 offset1:8
	ds_read2_b32 v[24:25], v4 offset0:66 offset1:74
	ds_read2_b32 v[26:27], v4 offset0:99 offset1:107
	ds_read2_b32 v[28:29], v4 offset0:132 offset1:140
	ds_read2_b32 v[30:31], v4 offset0:165 offset1:173
	ds_read2_b32 v[32:33], v4 offset0:198 offset1:206
	ds_read2_b32 v[34:35], v4 offset0:231 offset1:239
	s_waitcnt lgkmcnt(6)
	v_cvt_pk_bf16_f32 v14, v22, v20
	v_add_u32_e32 v20, 0x5800, v36
	s_waitcnt lgkmcnt(4)
	v_cvt_pk_bf16_f32 v15, v24, v26
	s_waitcnt lgkmcnt(2)
	v_cvt_pk_bf16_f32 v16, v28, v30
	s_waitcnt lgkmcnt(0)
	v_cvt_pk_bf16_f32 v17, v32, v34
	global_store_dwordx4 v[38:39], v[14:17], off
	v_add_u32_e32 v38, 0xb000, v36
	v_ashrrev_i32_e32 v39, 31, v38
	v_cvt_pk_bf16_f32 v14, v23, v21
	v_ashrrev_i32_e32 v21, 31, v20
	v_lshl_add_u64 v[20:21], v[20:21], 1, v[18:19]
	v_cvt_pk_bf16_f32 v15, v25, v27
	v_cvt_pk_bf16_f32 v16, v29, v31
	v_cvt_pk_bf16_f32 v17, v33, v35
	global_store_dwordx4 v[20:21], v[14:17], off
	ds_read2_b32 v[20:21], v4 offset0:16 offset1:24
	ds_read2_b32 v[22:23], v4 offset0:49 offset1:57
	ds_read2_b32 v[24:25], v4 offset0:82 offset1:90
	ds_read2_b32 v[26:27], v4 offset0:115 offset1:123
	ds_read2_b32 v[28:29], v4 offset0:148 offset1:156
	ds_read2_b32 v[30:31], v4 offset0:181 offset1:189
	ds_read2_b32 v[32:33], v4 offset0:214 offset1:222
	ds_read2_b32 v[34:35], v4 offset0:247 offset1:255
	s_waitcnt lgkmcnt(6)
	v_cvt_pk_bf16_f32 v14, v20, v22
	v_lshl_add_u64 v[38:39], v[38:39], 1, v[18:19]
	v_add_u32_e32 v20, 0x10800, v36
	s_waitcnt lgkmcnt(4)
	v_cvt_pk_bf16_f32 v15, v24, v26
	s_waitcnt lgkmcnt(2)
	v_cvt_pk_bf16_f32 v16, v28, v30
	s_waitcnt lgkmcnt(0)
	v_cvt_pk_bf16_f32 v17, v32, v34
	global_store_dwordx4 v[38:39], v[14:17], off
	s_nop 1
	v_cvt_pk_bf16_f32 v14, v21, v23
	v_ashrrev_i32_e32 v21, 31, v20
	v_lshl_add_u64 v[18:19], v[20:21], 1, v[18:19]
	v_cvt_pk_bf16_f32 v15, v25, v27
	v_cvt_pk_bf16_f32 v16, v29, v31
	v_cvt_pk_bf16_f32 v17, v33, v35
	global_store_dwordx4 v[18:19], v[14:17], off
	s_waitcnt lgkmcnt(0)
	s_cbranch_scc0 .LBB0_227
	s_branch .LBB0_222

; template <class Map>
; __device__ __forceinline__ void transpose_item(const float* W, int K, int N, bf16_t* WT, float* scr, int item, int nblk, int lane, Map srccol) {
;     const int kb = item / nblk, nb = item % nblk, k0 = 64 * kb, n0 = 32 * nb;
;     const int sc = srccol(n0 + (lane & 31));
;     float tv[32];
;     const float* wp = W + (size_t)(k0 + (lane >> 5)) * N + (sc >= 0 ? sc : 0);
; #pragma unroll
;     for (int i = 0; i < 32; ++i) tv[i] = wp[(size_t)(2 * i) * N];
; #pragma unroll
;     for (int i = 0; i < 32; ++i) { const int kk = 2 * i + (lane >> 5); scr[kk * 33 + (lane & 31)] = sc >= 0 ? tv[i] : 0.f; }
; __device__ __forceinline__ void mat_item(const P& p, float* scr, int mat, int r, int lane) {
;     if (mat < 4) transpose_item(p.w_up + (size_t)mat * DM * 2 * DFF, DM, 2 * DFF, (bf16_t*)(p.ws + WS_WUP) + (size_t)mat * 2 * DFF * DM, scr, r, 176, lane, MapUp());
;     else if (mat < 8) transpose_item(p.w_dn + (size_t)(mat - 4) * DFF * DM, DFF, DM, (bf16_t*)(p.ws + WS_WDN) + (size_t)(mat - 4) * DM * DFF, scr, r, 32, lane, MapPerm8());
;     else if (mat == 8) transpose_item(p.e_in, DM, 3600, (bf16_t*)(p.ws + WS_WEIN), scr, r, 120, lane, MapEin());
;     else if (mat == 9) transpose_item(p.e_out, DM, DM, (bf16_t*)(p.ws + WS_WEOUT), scr, r, 32, lane, MapPerm8());
;     else if (mat == 10) transpose_item(p.o_in, DM, 1536, (bf16_t*)(p.ws + WS_WOIN), scr, r, 48, lane, MapId());
;     else transpose_item(p.o_out, DM, DM, (bf16_t*)(p.ws + WS_WOOUT), scr, r, 32, lane, MapPerm8());
.LBB0_876:
	s_mov_b64 s[6:7], -1
	s_and_b64 vcc, exec, s[8:9]
	s_cbranch_vccz .LBB0_896
	s_and_b64 vcc, exec, s[2:3]
	s_cbranch_vccz .LBB0_893
	s_cmp_lt_i32 s41, 9
	s_cbranch_scc1 .LBB0_888
	s_cmp_lt_i32 s41, 10
	s_cbranch_scc1 .LBB0_885
	s_cmp_lg_u32 s41, 10
	s_cbranch_scc0 .LBB0_882
	s_ashr_i32 s6, s43, 31
	s_lshr_b32 s6, s6, 27
	s_add_i32 s6, s43, s6
	s_ashr_i32 s7, s6, 5
	s_lshl_b32 s28, s7, 6
	s_lshl_b32 s7, s7, 10
	s_sub_i32 s47, s44, s7
	v_add_u32_e32 v0, s47, v21
	s_andn2_b32 s6, s6, 31
	v_and_b32_e32 v18, 24, v37
	v_and_b32_e32 v0, 0xffffffe3, v0
	s_sub_i32 s6, s43, s6
	v_or3_b32 v0, v0, v18, v29
	v_or_b32_e32 v18, s28, v22
	v_ashrrev_i32_e32 v19, 31, v18
	s_cmp_gt_i32 s6, -1
	v_lshlrev_b64 v[18:19], 12, v[18:19]
	s_cselect_b64 vcc, -1, 0
	v_lshl_add_u64 v[18:19], s[22:23], 0, v[18:19]
	v_cndmask_b32_e32 v0, 0, v0, vcc
	v_lshl_add_u64 v[18:19], v[0:1], 2, v[18:19]
	v_add_co_u32_e64 v38, s[6:7], s63, v18
	global_load_dword v0, v[18:19], off
	s_nop 0
	v_addc_co_u32_e64 v39, s[6:7], 0, v19, s[6:7]
	global_load_dword v40, v[38:39], off
	v_add_co_u32_e64 v38, s[6:7], s96, v18
	s_ashr_i32 s29, s28, 31
	s_nop 0
	v_addc_co_u32_e64 v39, s[6:7], 0, v19, s[6:7]
	global_load_dword v41, v[38:39], off
	v_add_co_u32_e64 v38, s[6:7], s58, v18
	s_waitcnt vmcnt(2)
	v_cndmask_b32_e32 v0, 0, v0, vcc
	v_addc_co_u32_e64 v39, s[6:7], 0, v19, s[6:7]
	global_load_dword v42, v[38:39], off
	v_add_co_u32_e64 v38, s[6:7], s60, v18
	s_nop 1
	v_addc_co_u32_e64 v39, s[6:7], 0, v19, s[6:7]
	global_load_dword v43, v[38:39], off
	v_add_co_u32_e64 v38, s[6:7], s54, v18
	s_nop 1
	v_addc_co_u32_e64 v39, s[6:7], 0, v19, s[6:7]
	global_load_dword v44, v[38:39], off
	v_add_co_u32_e64 v38, s[6:7], s71, v18
	s_nop 1
	v_addc_co_u32_e64 v39, s[6:7], 0, v19, s[6:7]
	global_load_dword v45, v[38:39], off
	v_add_co_u32_e64 v38, s[6:7], s72, v18
	s_nop 1
	v_addc_co_u32_e64 v39, s[6:7], 0, v19, s[6:7]
	global_load_dword v46, v[38:39], off
	v_add_co_u32_e64 v38, s[6:7], s50, v18
	s_nop 1
	v_addc_co_u32_e64 v39, s[6:7], 0, v19, s[6:7]
	global_load_dword v47, v[38:39], off
	v_add_co_u32_e64 v38, s[6:7], s55, v18
	s_nop 1
	v_addc_co_u32_e64 v39, s[6:7], 0, v19, s[6:7]
	global_load_dword v48, v[38:39], off
	v_add_co_u32_e64 v38, s[6:7], s56, v18
	s_nop 1
	v_addc_co_u32_e64 v39, s[6:7], 0, v19, s[6:7]
	global_load_dword v49, v[38:39], off
	v_add_co_u32_e64 v38, s[6:7], s57, v18
	s_nop 1
	v_addc_co_u32_e64 v39, s[6:7], 0, v19, s[6:7]
	global_load_dword v50, v[38:39], off
	v_add_co_u32_e64 v38, s[6:7], s59, v18
	s_nop 1
	v_addc_co_u32_e64 v39, s[6:7], 0, v19, s[6:7]
	global_load_dword v51, v[38:39], off
	v_add_co_u32_e64 v38, s[6:7], s52, v18
	s_nop 1
	v_addc_co_u32_e64 v39, s[6:7], 0, v19, s[6:7]
	global_load_dword v52, v[38:39], off
	v_add_co_u32_e64 v38, s[6:7], s62, v18
	s_nop 1
	v_addc_co_u32_e64 v39, s[6:7], 0, v19, s[6:7]
	global_load_dword v53, v[38:39], off
	v_add_co_u32_e64 v38, s[6:7], s64, v18
	s_nop 1
	v_addc_co_u32_e64 v39, s[6:7], 0, v19, s[6:7]
	global_load_dword v54, v[38:39], off
	v_add_co_u32_e64 v38, s[6:7], s73, v18
	s_nop 1
	v_addc_co_u32_e64 v39, s[6:7], 0, v19, s[6:7]
	global_load_dword v55, v[38:39], off
	v_add_co_u32_e64 v38, s[6:7], s74, v18
	s_nop 1
	v_addc_co_u32_e64 v39, s[6:7], 0, v19, s[6:7]
	global_load_dword v56, v[38:39], off
	v_add_co_u32_e64 v38, s[6:7], s75, v18
	s_nop 1
	v_addc_co_u32_e64 v39, s[6:7], 0, v19, s[6:7]
	global_load_dword v57, v[38:39], off
	v_add_co_u32_e64 v38, s[6:7], s1, v18
	s_nop 1
	v_addc_co_u32_e64 v39, s[6:7], 0, v19, s[6:7]
	global_load_dword v58, v[38:39], off
	v_add_co_u32_e64 v38, s[6:7], s76, v18
	s_nop 1
	v_addc_co_u32_e64 v39, s[6:7], 0, v19, s[6:7]
	global_load_dword v59, v[38:39], off
	v_add_co_u32_e64 v38, s[6:7], s77, v18
	s_nop 1
	v_addc_co_u32_e64 v39, s[6:7], 0, v19, s[6:7]
	global_load_dword v60, v[38:39], off
	v_add_co_u32_e64 v38, s[6:7], s33, v18
	s_nop 1
	v_addc_co_u32_e64 v39, s[6:7], 0, v19, s[6:7]
	global_load_dword v61, v[38:39], off
	v_add_co_u32_e64 v38, s[6:7], s80, v18
	s_nop 1
	v_addc_co_u32_e64 v39, s[6:7], 0, v19, s[6:7]
	global_load_dword v62, v[38:39], off
	v_add_co_u32_e64 v38, s[6:7], s0, v18
	s_nop 1
	v_addc_co_u32_e64 v39, s[6:7], 0, v19, s[6:7]
	global_load_dword v63, v[38:39], off
	v_add_co_u32_e64 v38, s[6:7], s81, v18
	s_nop 1
	v_addc_co_u32_e64 v39, s[6:7], 0, v19, s[6:7]
	global_load_dword v64, v[38:39], off
	v_add_co_u32_e64 v38, s[6:7], s82, v18
	s_nop 1
	v_addc_co_u32_e64 v39, s[6:7], 0, v19, s[6:7]
	global_load_dword v65, v[38:39], off
	v_add_co_u32_e64 v38, s[6:7], s83, v18
	s_nop 1
	v_addc_co_u32_e64 v39, s[6:7], 0, v19, s[6:7]
	global_load_dword v66, v[38:39], off
	v_add_co_u32_e64 v38, s[6:7], s84, v18
	s_nop 1
	v_addc_co_u32_e64 v39, s[6:7], 0, v19, s[6:7]
	global_load_dword v67, v[38:39], off
	v_add_co_u32_e64 v38, s[6:7], s85, v18
	s_nop 1
	v_addc_co_u32_e64 v39, s[6:7], 0, v19, s[6:7]
	global_load_dword v68, v[38:39], off
	v_add_co_u32_e64 v38, s[6:7], s86, v18
	s_nop 1
	v_addc_co_u32_e64 v39, s[6:7], 0, v19, s[6:7]
	v_add_co_u32_e64 v18, s[6:7], s87, v18
	global_load_dword v38, v[38:39], off
	s_nop 0
	v_addc_co_u32_e64 v19, s[6:7], 0, v19, s[6:7]
	global_load_dword v18, v[18:19], off
	s_waitcnt vmcnt(30)
	v_cndmask_b32_e32 v19, 0, v40, vcc
	ds_write2_b32 v23, v0, v19 offset1:66
	s_waitcnt vmcnt(29)
	v_cndmask_b32_e32 v0, 0, v41, vcc
	s_waitcnt vmcnt(28)
	v_cndmask_b32_e32 v19, 0, v42, vcc
	ds_write2_b32 v23, v0, v19 offset0:132 offset1:198
	s_waitcnt vmcnt(27)
	v_cndmask_b32_e32 v0, 0, v43, vcc
	s_waitcnt vmcnt(26)
	v_cndmask_b32_e32 v19, 0, v44, vcc
	v_add_u32_e32 v39, 0x400, v23
	ds_write2_b32 v39, v0, v19 offset0:8 offset1:74
	s_waitcnt vmcnt(25)
; __device__ __forceinline__ unsigned pk2(float lo, float hi) { unsigned r; asm("v_cvt_pk_bf16_f32 %0, %1, %2" : "=v"(r) : "v"(lo), "v"(hi)); return r; }
; template <class Map>
; __device__ __forceinline__ void transpose_item(const float* W, int K, int N, bf16_t* WT, float* scr, int item, int nblk, int lane, Map srccol) {
;     ...
;     for (int i = 0; i < 32; ++i) { const int kk = 2 * i + (lane >> 5); scr[kk * 33 + (lane & 31)] = sc >= 0 ? tv[i] : 0.f; }
;     __builtin_amdgcn_s_waitcnt(0); asm volatile("" ::: "memory");
;     const int c = lane & 7;
; #pragma unroll
;     for (int j = 0; j < 4; ++j) { const int n = (lane >> 3) + 8 * j; const float* s = scr + (8 * c) * 33 + n;
;         u32x4 o; o.x = pk2(s[0 * 33], s[1 * 33]); o.y = pk2(s[2 * 33], s[3 * 33]); o.z = pk2(s[4 * 33], s[5 * 33]); o.w = pk2(s[6 * 33], s[7 * 33]);
;         *(u32x4*)(WT + (size_t)(n0 + n) * K + k0 + 8 * c) = o; }
;     __builtin_amdgcn_s_waitcnt(0); asm volatile("" ::: "memory");
	v_cndmask_b32_e32 v0, 0, v45, vcc
	s_waitcnt vmcnt(24)
	v_cndmask_b32_e32 v19, 0, v46, vcc
	ds_write2_b32 v39, v0, v19 offset0:140 offset1:206
	s_waitcnt vmcnt(23)
	v_cndmask_b32_e32 v0, 0, v47, vcc
	s_waitcnt vmcnt(22)
	v_cndmask_b32_e32 v19, 0, v48, vcc
	v_add_u32_e32 v39, 0x800, v23
	ds_write2_b32 v39, v0, v19 offset0:16 offset1:82
	s_waitcnt vmcnt(21)
	v_cndmask_b32_e32 v0, 0, v49, vcc
	s_waitcnt vmcnt(20)
	v_cndmask_b32_e32 v19, 0, v50, vcc
	ds_write2_b32 v39, v0, v19 offset0:148 offset1:214
	s_waitcnt vmcnt(19)
	v_cndmask_b32_e32 v0, 0, v51, vcc
	s_waitcnt vmcnt(18)
	v_cndmask_b32_e32 v19, 0, v52, vcc
	v_add_u32_e32 v39, 0xc00, v23
	ds_write2_b32 v39, v0, v19 offset0:24 offset1:90
	s_waitcnt vmcnt(17)
	v_cndmask_b32_e32 v0, 0, v53, vcc
	s_waitcnt vmcnt(16)
	v_cndmask_b32_e32 v19, 0, v54, vcc
	ds_write2_b32 v39, v0, v19 offset0:156 offset1:222
	s_waitcnt vmcnt(15)
	v_cndmask_b32_e32 v0, 0, v55, vcc
	s_waitcnt vmcnt(14)
	v_cndmask_b32_e32 v19, 0, v56, vcc
	v_add_u32_e32 v39, 0x1000, v23
	ds_write2_b32 v39, v0, v19 offset0:32 offset1:98
	s_waitcnt vmcnt(13)
	v_cndmask_b32_e32 v0, 0, v57, vcc
	s_waitcnt vmcnt(12)
	v_cndmask_b32_e32 v19, 0, v58, vcc
	ds_write2_b32 v39, v0, v19 offset0:164 offset1:230
	s_waitcnt vmcnt(11)
	v_cndmask_b32_e32 v0, 0, v59, vcc
	s_waitcnt vmcnt(10)
	v_cndmask_b32_e32 v19, 0, v60, vcc
	v_add_u32_e32 v39, 0x1400, v23
	ds_write2_b32 v39, v0, v19 offset0:40 offset1:106
	s_waitcnt vmcnt(9)
	v_cndmask_b32_e32 v0, 0, v61, vcc
	s_waitcnt vmcnt(8)
	v_cndmask_b32_e32 v19, 0, v62, vcc
	ds_write2_b32 v39, v0, v19 offset0:172 offset1:238
	s_waitcnt vmcnt(7)
	v_cndmask_b32_e32 v0, 0, v63, vcc
	v_add_u32_e32 v39, 0x1800, v23
	v_add_u32_e32 v58, s47, v24
	v_ashrrev_i32_e32 v59, 31, v58
	s_waitcnt vmcnt(6)
	v_cndmask_b32_e32 v19, 0, v64, vcc
	ds_write2_b32 v39, v0, v19 offset0:48 offset1:114
	v_lshlrev_b64 v[60:61], 11, v[58:59]
	s_mov_b64 s[6:7], 0
	s_waitcnt vmcnt(5)
	v_cndmask_b32_e32 v0, 0, v65, vcc
	s_waitcnt vmcnt(4)
	v_cndmask_b32_e32 v19, 0, v66, vcc
	ds_write2_b32 v39, v0, v19 offset0:180 offset1:246
	v_add_u32_e32 v39, 0x1c00, v23
	s_waitcnt vmcnt(3)
	v_cndmask_b32_e32 v0, 0, v67, vcc
	s_waitcnt vmcnt(2)
	v_cndmask_b32_e32 v19, 0, v68, vcc
	ds_write2_b32 v39, v0, v19 offset0:56 offset1:122
	s_waitcnt vmcnt(1)
	v_cndmask_b32_e32 v0, 0, v38, vcc
	s_waitcnt vmcnt(0)
	v_cndmask_b32_e32 v18, 0, v18, vcc
	ds_write2_b32 v39, v0, v18 offset0:188 offset1:254
	s_waitcnt vmcnt(0) expcnt(0) lgkmcnt(0)
	ds_read2_b32 v[42:43], v25 offset0:33 offset1:41
	ds_read2_b32 v[44:45], v25 offset1:8
	ds_read2_b32 v[46:47], v25 offset0:66 offset1:74
	ds_read2_b32 v[48:49], v25 offset0:99 offset1:107
	ds_read2_b32 v[50:51], v25 offset0:132 offset1:140
	ds_read2_b32 v[52:53], v25 offset0:165 offset1:173
	ds_read2_b32 v[54:55], v25 offset0:198 offset1:206
	ds_read2_b32 v[56:57], v25 offset0:231 offset1:239
	v_lshl_add_u64 v[18:19], s[28:29], 1, v[8:9]
	s_waitcnt lgkmcnt(6)
	v_cvt_pk_bf16_f32 v38, v44, v42
	v_lshl_add_u64 v[60:61], v[18:19], 0, v[60:61]
	v_add_u32_e32 v42, 8, v58
	s_waitcnt lgkmcnt(4)
	v_cvt_pk_bf16_f32 v39, v46, v48
	s_waitcnt lgkmcnt(2)
	v_cvt_pk_bf16_f32 v40, v50, v52
	s_waitcnt lgkmcnt(0)
	v_cvt_pk_bf16_f32 v41, v54, v56
	global_store_dwordx4 v[60:61], v[38:41], off
	v_add_u32_e32 v60, 16, v58
	v_ashrrev_i32_e32 v61, 31, v60
	v_cvt_pk_bf16_f32 v38, v45, v43
	v_ashrrev_i32_e32 v43, 31, v42
	v_lshlrev_b64 v[42:43], 11, v[42:43]
	v_lshl_add_u64 v[42:43], v[18:19], 0, v[42:43]
	v_cvt_pk_bf16_f32 v39, v47, v49
	v_cvt_pk_bf16_f32 v40, v51, v53
	v_cvt_pk_bf16_f32 v41, v55, v57
	global_store_dwordx4 v[42:43], v[38:41], off
	ds_read2_b32 v[42:43], v25 offset0:16 offset1:24
	ds_read2_b32 v[44:45], v25 offset0:49 offset1:57
	ds_read2_b32 v[46:47], v25 offset0:82 offset1:90
	ds_read2_b32 v[48:49], v25 offset0:115 offset1:123
	ds_read2_b32 v[50:51], v25 offset0:148 offset1:156
	ds_read2_b32 v[52:53], v25 offset0:181 offset1:189
	ds_read2_b32 v[54:55], v25 offset0:214 offset1:222
	ds_read2_b32 v[56:57], v25 offset0:247 offset1:255
	v_lshlrev_b64 v[60:61], 11, v[60:61]
	s_waitcnt lgkmcnt(6)
	v_cvt_pk_bf16_f32 v38, v42, v44
	v_lshl_add_u64 v[60:61], v[18:19], 0, v[60:61]
	v_add_u32_e32 v42, 24, v58
	s_waitcnt lgkmcnt(4)
	v_cvt_pk_bf16_f32 v39, v46, v48
	s_waitcnt lgkmcnt(2)
	v_cvt_pk_bf16_f32 v40, v50, v52
	s_waitcnt lgkmcnt(0)
	v_cvt_pk_bf16_f32 v41, v54, v56
	global_store_dwordx4 v[60:61], v[38:41], off
	s_nop 1
	v_cvt_pk_bf16_f32 v38, v43, v45
	v_ashrrev_i32_e32 v43, 31, v42
	v_lshlrev_b64 v[42:43], 11, v[42:43]
	v_lshl_add_u64 v[18:19], v[18:19], 0, v[42:43]
	v_cvt_pk_bf16_f32 v39, v47, v49
	v_cvt_pk_bf16_f32 v40, v51, v53
	v_cvt_pk_bf16_f32 v41, v55, v57
	global_store_dwordx4 v[18:19], v[38:41], off
	s_waitcnt lgkmcnt(0)
; template <class Map>
; __device__ __forceinline__ void transpose_item(const float* W, int K, int N, bf16_t* WT, float* scr, int item, int nblk, int lane, Map srccol) {
;     const int kb = item / nblk, nb = item % nblk, k0 = 64 * kb, n0 = 32 * nb;
;     const int sc = srccol(n0 + (lane & 31));
;     float tv[32];
;     const float* wp = W + (size_t)(k0 + (lane >> 5)) * N + (sc >= 0 ? sc : 0);
; #pragma unroll
;     for (int i = 0; i < 32; ++i) tv[i] = wp[(size_t)(2 * i) * N];
; #pragma unroll
;     for (int i = 0; i < 32; ++i) { const int kk = 2 * i + (lane >> 5); scr[kk * 33 + (lane & 31)] = sc >= 0 ? tv[i] : 0.f; }
.LBB0_882:
	s_andn2_b64 vcc, exec, s[6:7]
	s_cbranch_vccnz .LBB0_884
	s_mul_hi_i32 s6, s43, 0x2aaaaaab
	s_lshr_b32 s7, s6, 31
	s_ashr_i32 s6, s6, 3
	s_add_i32 s6, s6, s7
	s_mul_i32 s7, s6, 0xffffffd0
	s_mul_i32 s47, s6, 0xfffffa00
	s_add_i32 s29, s43, s7
	s_lshl_b32 s28, s6, 6
	s_add_i32 s47, s47, s44
	s_cmp_gt_i32 s29, -1
	v_add_u32_e32 v0, s47, v21
	v_or_b32_e32 v38, s28, v22
	v_mov_b64_e32 v[18:19], s[20:21]
	s_movk_i32 s6, 0x1800
	s_cselect_b64 vcc, -1, 0
	v_mad_i64_i32 v[18:19], s[6:7], v38, s6, v[18:19]
	v_cndmask_b32_e32 v0, 0, v0, vcc
	v_lshl_add_u64 v[18:19], v[0:1], 2, v[18:19]
	s_movk_i32 s6, 0x3000
	v_add_co_u32_e64 v38, s[6:7], s6, v18
	global_load_dword v0, v[18:19], off
	s_nop 0
	v_addc_co_u32_e64 v39, s[6:7], 0, v19, s[6:7]
	global_load_dword v40, v[38:39], off
	v_add_co_u32_e64 v38, s[6:7], s58, v18
	s_ashr_i32 s29, s28, 31
	s_nop 0
	v_addc_co_u32_e64 v39, s[6:7], 0, v19, s[6:7]
	s_mov_b32 s6, 0x9000
	global_load_dword v41, v[38:39], off
	v_add_co_u32_e64 v38, s[6:7], s6, v18
	s_waitcnt vmcnt(2)
	v_cndmask_b32_e32 v0, 0, v0, vcc
	v_addc_co_u32_e64 v39, s[6:7], 0, v19, s[6:7]
	global_load_dword v42, v[38:39], off
	v_add_co_u32_e64 v38, s[6:7], s71, v18
	s_nop 1
	v_addc_co_u32_e64 v39, s[6:7], 0, v19, s[6:7]
	s_mov_b32 s6, 0xf000
	global_load_dword v43, v[38:39], off
	v_add_co_u32_e64 v38, s[6:7], s6, v18
	s_nop 1
	v_addc_co_u32_e64 v39, s[6:7], 0, v19, s[6:7]
	global_load_dword v44, v[38:39], off
	v_add_co_u32_e64 v38, s[6:7], s55, v18
	s_nop 1
	v_addc_co_u32_e64 v39, s[6:7], 0, v19, s[6:7]
	s_mov_b32 s6, 0x15000
	global_load_dword v45, v[38:39], off
	v_add_co_u32_e64 v38, s[6:7], s6, v18
	s_nop 1
	v_addc_co_u32_e64 v39, s[6:7], 0, v19, s[6:7]
	global_load_dword v46, v[38:39], off
	v_add_co_u32_e64 v38, s[6:7], s59, v18
	s_nop 1
	v_addc_co_u32_e64 v39, s[6:7], 0, v19, s[6:7]
	s_mov_b32 s6, 0x1b000
	global_load_dword v47, v[38:39], off
	v_add_co_u32_e64 v38, s[6:7], s6, v18
	s_nop 1
	v_addc_co_u32_e64 v39, s[6:7], 0, v19, s[6:7]
	global_load_dword v48, v[38:39], off
	v_add_co_u32_e64 v38, s[6:7], s64, v18
	s_nop 1
	v_addc_co_u32_e64 v39, s[6:7], 0, v19, s[6:7]
	s_mov_b32 s6, 0x21000
	global_load_dword v49, v[38:39], off
	v_add_co_u32_e64 v38, s[6:7], s6, v18
	s_nop 1
	v_addc_co_u32_e64 v39, s[6:7], 0, v19, s[6:7]
	global_load_dword v50, v[38:39], off
	v_add_co_u32_e64 v38, s[6:7], s75, v18
	s_nop 1
	v_addc_co_u32_e64 v39, s[6:7], 0, v19, s[6:7]
	s_mov_b32 s6, 0x27000
	global_load_dword v51, v[38:39], off
	v_add_co_u32_e64 v38, s[6:7], s6, v18
	s_nop 1
	v_addc_co_u32_e64 v39, s[6:7], 0, v19, s[6:7]
	global_load_dword v52, v[38:39], off
	v_add_co_u32_e64 v38, s[6:7], s77, v18
	s_nop 1
	v_addc_co_u32_e64 v39, s[6:7], 0, v19, s[6:7]
	s_mov_b32 s6, 0x2d000
	global_load_dword v53, v[38:39], off
	v_add_co_u32_e64 v38, s[6:7], s6, v18
	s_nop 1
	v_addc_co_u32_e64 v39, s[6:7], 0, v19, s[6:7]
	global_load_dword v54, v[38:39], off
	v_add_co_u32_e64 v38, s[6:7], s0, v18
	s_nop 1
	v_addc_co_u32_e64 v39, s[6:7], 0, v19, s[6:7]
	s_mov_b32 s6, 0x33000
	global_load_dword v55, v[38:39], off
	v_add_co_u32_e64 v38, s[6:7], s6, v18
	s_nop 1
	v_addc_co_u32_e64 v39, s[6:7], 0, v19, s[6:7]
	global_load_dword v56, v[38:39], off
	v_add_co_u32_e64 v38, s[6:7], s83, v18
	s_nop 1
	v_addc_co_u32_e64 v39, s[6:7], 0, v19, s[6:7]
	s_mov_b32 s6, 0x39000
	global_load_dword v57, v[38:39], off
	v_add_co_u32_e64 v38, s[6:7], s6, v18
	s_nop 1
	v_addc_co_u32_e64 v39, s[6:7], 0, v19, s[6:7]
	global_load_dword v58, v[38:39], off
	v_add_co_u32_e64 v38, s[6:7], s86, v18
	s_nop 1
	v_addc_co_u32_e64 v39, s[6:7], 0, v19, s[6:7]
	s_mov_b32 s6, 0x3f000
	global_load_dword v59, v[38:39], off
	v_add_co_u32_e64 v38, s[6:7], s6, v18
	s_nop 1
	v_addc_co_u32_e64 v39, s[6:7], 0, v19, s[6:7]
	s_mov_b32 s6, 0x42000
	global_load_dword v60, v[38:39], off
	v_add_co_u32_e64 v38, s[6:7], s6, v18
	s_nop 1
	v_addc_co_u32_e64 v39, s[6:7], 0, v19, s[6:7]
	s_mov_b32 s6, 0x45000
	global_load_dword v61, v[38:39], off
	v_add_co_u32_e64 v38, s[6:7], s6, v18
	s_nop 1
	v_addc_co_u32_e64 v39, s[6:7], 0, v19, s[6:7]
	s_mov_b32 s6, 0x48000
	global_load_dword v62, v[38:39], off
	v_add_co_u32_e64 v38, s[6:7], s6, v18
	s_nop 1
	v_addc_co_u32_e64 v39, s[6:7], 0, v19, s[6:7]
	s_mov_b32 s6, 0x4b000
	global_load_dword v63, v[38:39], off
	v_add_co_u32_e64 v38, s[6:7], s6, v18
	s_nop 1
	v_addc_co_u32_e64 v39, s[6:7], 0, v19, s[6:7]
	s_mov_b32 s6, 0x4e000
	global_load_dword v64, v[38:39], off
	v_add_co_u32_e64 v38, s[6:7], s6, v18
	s_nop 1
	v_addc_co_u32_e64 v39, s[6:7], 0, v19, s[6:7]
	s_mov_b32 s6, 0x51000
	global_load_dword v65, v[38:39], off
	v_add_co_u32_e64 v38, s[6:7], s6, v18
	s_nop 1
	v_addc_co_u32_e64 v39, s[6:7], 0, v19, s[6:7]
	s_mov_b32 s6, 0x54000
	global_load_dword v66, v[38:39], off
	v_add_co_u32_e64 v38, s[6:7], s6, v18
	s_nop 1
	v_addc_co_u32_e64 v39, s[6:7], 0, v19, s[6:7]
	s_mov_b32 s6, 0x57000
	global_load_dword v67, v[38:39], off
	v_add_co_u32_e64 v38, s[6:7], s6, v18
	s_nop 1
	v_addc_co_u32_e64 v39, s[6:7], 0, v19, s[6:7]
	s_mov_b32 s6, 0x5a000
	global_load_dword v68, v[38:39], off
	v_add_co_u32_e64 v38, s[6:7], s6, v18
	s_nop 1
	v_addc_co_u32_e64 v39, s[6:7], 0, v19, s[6:7]
	s_mov_b32 s6, 0x5d000
	s_nop 0
	v_add_co_u32_e64 v18, s[6:7], s6, v18
	global_load_dword v38, v[38:39], off
	s_nop 0
	v_addc_co_u32_e64 v19, s[6:7], 0, v19, s[6:7]
	global_load_dword v18, v[18:19], off
	s_waitcnt vmcnt(30)
; __device__ __forceinline__ unsigned pk2(float lo, float hi) { unsigned r; asm("v_cvt_pk_bf16_f32 %0, %1, %2" : "=v"(r) : "v"(lo), "v"(hi)); return r; }
; template <class Map>
; __device__ __forceinline__ void transpose_item(const float* W, int K, int N, bf16_t* WT, float* scr, int item, int nblk, int lane, Map srccol) {
;     ...
;     for (int i = 0; i < 32; ++i) { const int kk = 2 * i + (lane >> 5); scr[kk * 33 + (lane & 31)] = sc >= 0 ? tv[i] : 0.f; }
;     __builtin_amdgcn_s_waitcnt(0); asm volatile("" ::: "memory");
;     const int c = lane & 7;
; #pragma unroll
;     for (int j = 0; j < 4; ++j) { const int n = (lane >> 3) + 8 * j; const float* s = scr + (8 * c) * 33 + n;
;         u32x4 o; o.x = pk2(s[0 * 33], s[1 * 33]); o.y = pk2(s[2 * 33], s[3 * 33]); o.z = pk2(s[4 * 33], s[5 * 33]); o.w = pk2(s[6 * 33], s[7 * 33]);
;         *(u32x4*)(WT + (size_t)(n0 + n) * K + k0 + 8 * c) = o; }
;     __builtin_amdgcn_s_waitcnt(0); asm volatile("" ::: "memory");
	v_cndmask_b32_e32 v19, 0, v40, vcc
	ds_write2_b32 v23, v0, v19 offset1:66
	s_waitcnt vmcnt(29)
	v_cndmask_b32_e32 v0, 0, v41, vcc
	s_waitcnt vmcnt(28)
	v_cndmask_b32_e32 v19, 0, v42, vcc
	ds_write2_b32 v23, v0, v19 offset0:132 offset1:198
	s_waitcnt vmcnt(27)
	v_cndmask_b32_e32 v0, 0, v43, vcc
	s_waitcnt vmcnt(26)
	v_cndmask_b32_e32 v19, 0, v44, vcc
	v_add_u32_e32 v39, 0x400, v23
	ds_write2_b32 v39, v0, v19 offset0:8 offset1:74
	s_waitcnt vmcnt(25)
	v_cndmask_b32_e32 v0, 0, v45, vcc
	s_waitcnt vmcnt(24)
	v_cndmask_b32_e32 v19, 0, v46, vcc
	ds_write2_b32 v39, v0, v19 offset0:140 offset1:206
	s_waitcnt vmcnt(23)
	v_cndmask_b32_e32 v0, 0, v47, vcc
	s_waitcnt vmcnt(22)
	v_cndmask_b32_e32 v19, 0, v48, vcc
	v_add_u32_e32 v39, 0x800, v23
	ds_write2_b32 v39, v0, v19 offset0:16 offset1:82
	s_waitcnt vmcnt(21)
	v_cndmask_b32_e32 v0, 0, v49, vcc
	s_waitcnt vmcnt(20)
	v_cndmask_b32_e32 v19, 0, v50, vcc
	ds_write2_b32 v39, v0, v19 offset0:148 offset1:214
	s_waitcnt vmcnt(19)
	v_cndmask_b32_e32 v0, 0, v51, vcc
	s_waitcnt vmcnt(18)
	v_cndmask_b32_e32 v19, 0, v52, vcc
	v_add_u32_e32 v39, 0xc00, v23
	ds_write2_b32 v39, v0, v19 offset0:24 offset1:90
	s_waitcnt vmcnt(17)
	v_cndmask_b32_e32 v0, 0, v53, vcc
	s_waitcnt vmcnt(16)
	v_cndmask_b32_e32 v19, 0, v54, vcc
	ds_write2_b32 v39, v0, v19 offset0:156 offset1:222
	s_waitcnt vmcnt(15)
	v_cndmask_b32_e32 v0, 0, v55, vcc
	s_waitcnt vmcnt(14)
	v_cndmask_b32_e32 v19, 0, v56, vcc
	v_add_u32_e32 v39, 0x1000, v23
	ds_write2_b32 v39, v0, v19 offset0:32 offset1:98
	s_waitcnt vmcnt(13)
	v_cndmask_b32_e32 v0, 0, v57, vcc
	s_waitcnt vmcnt(12)
	v_cndmask_b32_e32 v19, 0, v58, vcc
	ds_write2_b32 v39, v0, v19 offset0:164 offset1:230
	s_waitcnt vmcnt(11)
	v_cndmask_b32_e32 v0, 0, v59, vcc
	s_waitcnt vmcnt(10)
	v_cndmask_b32_e32 v19, 0, v60, vcc
	v_add_u32_e32 v39, 0x1400, v23
	ds_write2_b32 v39, v0, v19 offset0:40 offset1:106
	s_waitcnt vmcnt(9)
	v_cndmask_b32_e32 v0, 0, v61, vcc
	s_waitcnt vmcnt(8)
	v_cndmask_b32_e32 v19, 0, v62, vcc
	ds_write2_b32 v39, v0, v19 offset0:172 offset1:238
	s_waitcnt vmcnt(7)
	v_cndmask_b32_e32 v0, 0, v63, vcc
	s_waitcnt vmcnt(6)
	v_cndmask_b32_e32 v19, 0, v64, vcc
	v_add_u32_e32 v39, 0x1800, v23
	ds_write2_b32 v39, v0, v19 offset0:48 offset1:114
	v_add_u32_e32 v58, s47, v24
	v_ashrrev_i32_e32 v59, 31, v58
	s_waitcnt vmcnt(5)
	v_cndmask_b32_e32 v0, 0, v65, vcc
	v_lshlrev_b64 v[60:61], 11, v[58:59]
	s_waitcnt vmcnt(4)
	v_cndmask_b32_e32 v19, 0, v66, vcc
	ds_write2_b32 v39, v0, v19 offset0:180 offset1:246
	v_add_u32_e32 v39, 0x1c00, v23
	s_waitcnt vmcnt(3)
	v_cndmask_b32_e32 v0, 0, v67, vcc
	s_waitcnt vmcnt(2)
	v_cndmask_b32_e32 v19, 0, v68, vcc
	ds_write2_b32 v39, v0, v19 offset0:56 offset1:122
	s_waitcnt vmcnt(1)
	v_cndmask_b32_e32 v0, 0, v38, vcc
	s_waitcnt vmcnt(0)
	v_cndmask_b32_e32 v18, 0, v18, vcc
	ds_write2_b32 v39, v0, v18 offset0:188 offset1:254
	s_waitcnt vmcnt(0) expcnt(0) lgkmcnt(0)
	ds_read2_b32 v[42:43], v25 offset0:33 offset1:41
	ds_read2_b32 v[44:45], v25 offset1:8
	ds_read2_b32 v[46:47], v25 offset0:66 offset1:74
	ds_read2_b32 v[48:49], v25 offset0:99 offset1:107
	ds_read2_b32 v[50:51], v25 offset0:132 offset1:140
	ds_read2_b32 v[52:53], v25 offset0:165 offset1:173
	ds_read2_b32 v[54:55], v25 offset0:198 offset1:206
	ds_read2_b32 v[56:57], v25 offset0:231 offset1:239
	v_lshl_add_u64 v[18:19], s[28:29], 1, v[2:3]
	s_waitcnt lgkmcnt(6)
	v_cvt_pk_bf16_f32 v38, v44, v42
	v_lshl_add_u64 v[60:61], v[18:19], 0, v[60:61]
	v_add_u32_e32 v42, 8, v58
	s_waitcnt lgkmcnt(4)
	v_cvt_pk_bf16_f32 v39, v46, v48
	s_waitcnt lgkmcnt(2)
	v_cvt_pk_bf16_f32 v40, v50, v52
	s_waitcnt lgkmcnt(0)
	v_cvt_pk_bf16_f32 v41, v54, v56
	global_store_dwordx4 v[60:61], v[38:41], off
	v_add_u32_e32 v60, 16, v58
	v_ashrrev_i32_e32 v61, 31, v60
	v_cvt_pk_bf16_f32 v38, v45, v43
	v_ashrrev_i32_e32 v43, 31, v42
	v_lshlrev_b64 v[42:43], 11, v[42:43]
	v_lshl_add_u64 v[42:43], v[18:19], 0, v[42:43]
	v_cvt_pk_bf16_f32 v39, v47, v49
	v_cvt_pk_bf16_f32 v40, v51, v53
	v_cvt_pk_bf16_f32 v41, v55, v57
	global_store_dwordx4 v[42:43], v[38:41], off
	ds_read2_b32 v[42:43], v25 offset0:16 offset1:24
	ds_read2_b32 v[44:45], v25 offset0:49 offset1:57
	ds_read2_b32 v[46:47], v25 offset0:82 offset1:90
	ds_read2_b32 v[48:49], v25 offset0:115 offset1:123
	ds_read2_b32 v[50:51], v25 offset0:148 offset1:156
	ds_read2_b32 v[52:53], v25 offset0:181 offset1:189
	ds_read2_b32 v[54:55], v25 offset0:214 offset1:222
	ds_read2_b32 v[56:57], v25 offset0:247 offset1:255
	v_lshlrev_b64 v[60:61], 11, v[60:61]
	s_waitcnt lgkmcnt(6)
	v_cvt_pk_bf16_f32 v38, v42, v44
	v_lshl_add_u64 v[60:61], v[18:19], 0, v[60:61]
	v_add_u32_e32 v42, 24, v58
	s_waitcnt lgkmcnt(4)
	v_cvt_pk_bf16_f32 v39, v46, v48
	s_waitcnt lgkmcnt(2)
	v_cvt_pk_bf16_f32 v40, v50, v52
	s_waitcnt lgkmcnt(0)
	v_cvt_pk_bf16_f32 v41, v54, v56
	global_store_dwordx4 v[60:61], v[38:41], off
	s_nop 1
	v_cvt_pk_bf16_f32 v38, v43, v45
	v_ashrrev_i32_e32 v43, 31, v42
	v_lshlrev_b64 v[42:43], 11, v[42:43]
	v_lshl_add_u64 v[18:19], v[18:19], 0, v[42:43]
	v_cvt_pk_bf16_f32 v39, v47, v49
	v_cvt_pk_bf16_f32 v40, v51, v53
	v_cvt_pk_bf16_f32 v41, v55, v57
	global_store_dwordx4 v[18:19], v[38:41], off
	s_waitcnt lgkmcnt(0)

; template <class Map>
; __device__ __forceinline__ void transpose_item(const float* W, int K, int N, bf16_t* WT, float* scr, int item, int nblk, int lane, Map srccol) {
;     const int kb = item / nblk, nb = item % nblk, k0 = 64 * kb, n0 = 32 * nb;
;     const int sc = srccol(n0 + (lane & 31));
;     float tv[32];
;     const float* wp = W + (size_t)(k0 + (lane >> 5)) * N + (sc >= 0 ? sc : 0);
; #pragma unroll
;     for (int i = 0; i < 32; ++i) tv[i] = wp[(size_t)(2 * i) * N];
; #pragma unroll
;     for (int i = 0; i < 32; ++i) { const int kk = 2 * i + (lane >> 5); scr[kk * 33 + (lane & 31)] = sc >= 0 ? tv[i] : 0.f; }
.LBB0_885:
	s_andn2_b64 vcc, exec, s[6:7]
	s_cbranch_vccnz .LBB0_887
	s_ashr_i32 s6, s43, 31
	s_lshr_b32 s6, s6, 27
	s_add_i32 s6, s43, s6
	s_and_b32 s7, s6, 0xffffffe0
	s_sub_i32 s7, s43, s7
	s_lshl_b32 s6, s6, 1
	s_lshl_b32 s47, s7, 5
	s_and_b32 s28, s6, 0xffffffc0
	v_and_b32_e32 v0, 24, v36
	v_bitop3_b32 v18, s47, v206, v21 bitop3:0xc8
	v_or3_b32 v0, v18, v0, v29
	v_or_b32_e32 v18, s28, v22
	v_ashrrev_i32_e32 v19, 31, v18
	s_cmp_gt_i32 s7, -1
	v_lshlrev_b64 v[18:19], 12, v[18:19]
	s_cselect_b64 vcc, -1, 0
	v_lshl_add_u64 v[18:19], s[18:19], 0, v[18:19]
	v_cndmask_b32_e32 v0, 0, v0, vcc
	v_lshl_add_u64 v[18:19], v[0:1], 2, v[18:19]
	v_add_co_u32_e64 v38, s[6:7], s63, v18
	global_load_dword v0, v[18:19], off
	s_nop 0
	v_addc_co_u32_e64 v39, s[6:7], 0, v19, s[6:7]
	global_load_dword v40, v[38:39], off
	v_add_co_u32_e64 v38, s[6:7], s96, v18
	s_ashr_i32 s29, s28, 31
	s_nop 0
	v_addc_co_u32_e64 v39, s[6:7], 0, v19, s[6:7]
	global_load_dword v41, v[38:39], off
	v_add_co_u32_e64 v38, s[6:7], s58, v18
	s_waitcnt vmcnt(2)
	v_cndmask_b32_e32 v0, 0, v0, vcc
	v_addc_co_u32_e64 v39, s[6:7], 0, v19, s[6:7]
	global_load_dword v42, v[38:39], off
	v_add_co_u32_e64 v38, s[6:7], s60, v18
	s_nop 1
	v_addc_co_u32_e64 v39, s[6:7], 0, v19, s[6:7]
	global_load_dword v43, v[38:39], off
	v_add_co_u32_e64 v38, s[6:7], s54, v18
	s_nop 1
	v_addc_co_u32_e64 v39, s[6:7], 0, v19, s[6:7]
	global_load_dword v44, v[38:39], off
	v_add_co_u32_e64 v38, s[6:7], s71, v18
	s_nop 1
	v_addc_co_u32_e64 v39, s[6:7], 0, v19, s[6:7]
	global_load_dword v45, v[38:39], off
	v_add_co_u32_e64 v38, s[6:7], s72, v18
	s_nop 1
	v_addc_co_u32_e64 v39, s[6:7], 0, v19, s[6:7]
	global_load_dword v46, v[38:39], off
	v_add_co_u32_e64 v38, s[6:7], s50, v18
	s_nop 1
	v_addc_co_u32_e64 v39, s[6:7], 0, v19, s[6:7]
	global_load_dword v47, v[38:39], off
	v_add_co_u32_e64 v38, s[6:7], s55, v18
	s_nop 1
	v_addc_co_u32_e64 v39, s[6:7], 0, v19, s[6:7]
	global_load_dword v48, v[38:39], off
	v_add_co_u32_e64 v38, s[6:7], s56, v18
	s_nop 1
	v_addc_co_u32_e64 v39, s[6:7], 0, v19, s[6:7]
	global_load_dword v49, v[38:39], off
	v_add_co_u32_e64 v38, s[6:7], s57, v18
	s_nop 1
	v_addc_co_u32_e64 v39, s[6:7], 0, v19, s[6:7]
	global_load_dword v50, v[38:39], off
	v_add_co_u32_e64 v38, s[6:7], s59, v18
	s_nop 1
	v_addc_co_u32_e64 v39, s[6:7], 0, v19, s[6:7]
	global_load_dword v51, v[38:39], off
	v_add_co_u32_e64 v38, s[6:7], s52, v18
	s_nop 1
	v_addc_co_u32_e64 v39, s[6:7], 0, v19, s[6:7]
	global_load_dword v52, v[38:39], off
	v_add_co_u32_e64 v38, s[6:7], s62, v18
	s_nop 1
	v_addc_co_u32_e64 v39, s[6:7], 0, v19, s[6:7]
	global_load_dword v53, v[38:39], off
	v_add_co_u32_e64 v38, s[6:7], s64, v18
	s_nop 1
	v_addc_co_u32_e64 v39, s[6:7], 0, v19, s[6:7]
	global_load_dword v54, v[38:39], off
	v_add_co_u32_e64 v38, s[6:7], s73, v18
	s_nop 1
	v_addc_co_u32_e64 v39, s[6:7], 0, v19, s[6:7]
	global_load_dword v55, v[38:39], off
	v_add_co_u32_e64 v38, s[6:7], s74, v18
	s_nop 1
	v_addc_co_u32_e64 v39, s[6:7], 0, v19, s[6:7]
	global_load_dword v56, v[38:39], off
	v_add_co_u32_e64 v38, s[6:7], s75, v18
	s_nop 1
	v_addc_co_u32_e64 v39, s[6:7], 0, v19, s[6:7]
	global_load_dword v57, v[38:39], off
	v_add_co_u32_e64 v38, s[6:7], s1, v18
	s_nop 1
	v_addc_co_u32_e64 v39, s[6:7], 0, v19, s[6:7]
	global_load_dword v58, v[38:39], off
	v_add_co_u32_e64 v38, s[6:7], s76, v18
	s_nop 1
	v_addc_co_u32_e64 v39, s[6:7], 0, v19, s[6:7]
	global_load_dword v59, v[38:39], off
	v_add_co_u32_e64 v38, s[6:7], s77, v18
	s_nop 1
	v_addc_co_u32_e64 v39, s[6:7], 0, v19, s[6:7]
	global_load_dword v60, v[38:39], off
	v_add_co_u32_e64 v38, s[6:7], s33, v18
	s_nop 1
	v_addc_co_u32_e64 v39, s[6:7], 0, v19, s[6:7]
	global_load_dword v61, v[38:39], off
	v_add_co_u32_e64 v38, s[6:7], s80, v18
	s_nop 1
	v_addc_co_u32_e64 v39, s[6:7], 0, v19, s[6:7]
	global_load_dword v62, v[38:39], off
	v_add_co_u32_e64 v38, s[6:7], s0, v18
	s_nop 1
	v_addc_co_u32_e64 v39, s[6:7], 0, v19, s[6:7]
	global_load_dword v63, v[38:39], off
	v_add_co_u32_e64 v38, s[6:7], s81, v18
	s_nop 1
	v_addc_co_u32_e64 v39, s[6:7], 0, v19, s[6:7]
	global_load_dword v64, v[38:39], off
	v_add_co_u32_e64 v38, s[6:7], s82, v18
	s_nop 1
	v_addc_co_u32_e64 v39, s[6:7], 0, v19, s[6:7]
	global_load_dword v65, v[38:39], off
	v_add_co_u32_e64 v38, s[6:7], s83, v18
	s_nop 1
	v_addc_co_u32_e64 v39, s[6:7], 0, v19, s[6:7]
	global_load_dword v66, v[38:39], off
	v_add_co_u32_e64 v38, s[6:7], s84, v18
	s_nop 1
	v_addc_co_u32_e64 v39, s[6:7], 0, v19, s[6:7]
	global_load_dword v67, v[38:39], off
	v_add_co_u32_e64 v38, s[6:7], s85, v18
	s_nop 1
	v_addc_co_u32_e64 v39, s[6:7], 0, v19, s[6:7]
	global_load_dword v68, v[38:39], off
	v_add_co_u32_e64 v38, s[6:7], s86, v18
	s_nop 1
	v_addc_co_u32_e64 v39, s[6:7], 0, v19, s[6:7]
	v_add_co_u32_e64 v18, s[6:7], s87, v18
	global_load_dword v38, v[38:39], off
	s_nop 0
	v_addc_co_u32_e64 v19, s[6:7], 0, v19, s[6:7]
	global_load_dword v18, v[18:19], off
	s_waitcnt vmcnt(30)
	v_cndmask_b32_e32 v19, 0, v40, vcc
	ds_write2_b32 v23, v0, v19 offset1:66
	s_waitcnt vmcnt(29)
; __device__ __forceinline__ unsigned pk2(float lo, float hi) { unsigned r; asm("v_cvt_pk_bf16_f32 %0, %1, %2" : "=v"(r) : "v"(lo), "v"(hi)); return r; }
; template <class Map>
; __device__ __forceinline__ void transpose_item(const float* W, int K, int N, bf16_t* WT, float* scr, int item, int nblk, int lane, Map srccol) {
;     ...
;     for (int i = 0; i < 32; ++i) { const int kk = 2 * i + (lane >> 5); scr[kk * 33 + (lane & 31)] = sc >= 0 ? tv[i] : 0.f; }
;     __builtin_amdgcn_s_waitcnt(0); asm volatile("" ::: "memory");
;     const int c = lane & 7;
; #pragma unroll
;     for (int j = 0; j < 4; ++j) { const int n = (lane >> 3) + 8 * j; const float* s = scr + (8 * c) * 33 + n;
;         u32x4 o; o.x = pk2(s[0 * 33], s[1 * 33]); o.y = pk2(s[2 * 33], s[3 * 33]); o.z = pk2(s[4 * 33], s[5 * 33]); o.w = pk2(s[6 * 33], s[7 * 33]);
;         *(u32x4*)(WT + (size_t)(n0 + n) * K + k0 + 8 * c) = o; }
;     __builtin_amdgcn_s_waitcnt(0); asm volatile("" ::: "memory");
	v_cndmask_b32_e32 v0, 0, v41, vcc
	s_waitcnt vmcnt(28)
	v_cndmask_b32_e32 v19, 0, v42, vcc
	ds_write2_b32 v23, v0, v19 offset0:132 offset1:198
	s_waitcnt vmcnt(27)
	v_cndmask_b32_e32 v0, 0, v43, vcc
	s_waitcnt vmcnt(26)
	v_cndmask_b32_e32 v19, 0, v44, vcc
	v_add_u32_e32 v39, 0x400, v23
	ds_write2_b32 v39, v0, v19 offset0:8 offset1:74
	s_waitcnt vmcnt(25)
	v_cndmask_b32_e32 v0, 0, v45, vcc
	s_waitcnt vmcnt(24)
	v_cndmask_b32_e32 v19, 0, v46, vcc
	ds_write2_b32 v39, v0, v19 offset0:140 offset1:206
	s_waitcnt vmcnt(23)
	v_cndmask_b32_e32 v0, 0, v47, vcc
	s_waitcnt vmcnt(22)
	v_cndmask_b32_e32 v19, 0, v48, vcc
	v_add_u32_e32 v39, 0x800, v23
	ds_write2_b32 v39, v0, v19 offset0:16 offset1:82
	s_waitcnt vmcnt(21)
	v_cndmask_b32_e32 v0, 0, v49, vcc
	s_waitcnt vmcnt(20)
	v_cndmask_b32_e32 v19, 0, v50, vcc
	ds_write2_b32 v39, v0, v19 offset0:148 offset1:214
	s_waitcnt vmcnt(19)
	v_cndmask_b32_e32 v0, 0, v51, vcc
	s_waitcnt vmcnt(18)
	v_cndmask_b32_e32 v19, 0, v52, vcc
	v_add_u32_e32 v39, 0xc00, v23
	ds_write2_b32 v39, v0, v19 offset0:24 offset1:90
	s_waitcnt vmcnt(17)
	v_cndmask_b32_e32 v0, 0, v53, vcc
	s_waitcnt vmcnt(16)
	v_cndmask_b32_e32 v19, 0, v54, vcc
	ds_write2_b32 v39, v0, v19 offset0:156 offset1:222
	s_waitcnt vmcnt(15)
	v_cndmask_b32_e32 v0, 0, v55, vcc
	s_waitcnt vmcnt(14)
	v_cndmask_b32_e32 v19, 0, v56, vcc
	v_add_u32_e32 v39, 0x1000, v23
	ds_write2_b32 v39, v0, v19 offset0:32 offset1:98
	s_waitcnt vmcnt(13)
	v_cndmask_b32_e32 v0, 0, v57, vcc
	s_waitcnt vmcnt(12)
	v_cndmask_b32_e32 v19, 0, v58, vcc
	ds_write2_b32 v39, v0, v19 offset0:164 offset1:230
	s_waitcnt vmcnt(11)
	v_cndmask_b32_e32 v0, 0, v59, vcc
	s_waitcnt vmcnt(10)
	v_cndmask_b32_e32 v19, 0, v60, vcc
	v_add_u32_e32 v39, 0x1400, v23
	ds_write2_b32 v39, v0, v19 offset0:40 offset1:106
	s_waitcnt vmcnt(9)
	v_cndmask_b32_e32 v0, 0, v61, vcc
	s_waitcnt vmcnt(8)
	v_cndmask_b32_e32 v19, 0, v62, vcc
	ds_write2_b32 v39, v0, v19 offset0:172 offset1:238
	s_waitcnt vmcnt(7)
	v_cndmask_b32_e32 v0, 0, v63, vcc
	v_add_u32_e32 v39, 0x1800, v23
	v_or_b32_e32 v58, s47, v24
	v_ashrrev_i32_e32 v59, 31, v58
	s_waitcnt vmcnt(6)
	v_cndmask_b32_e32 v19, 0, v64, vcc
	ds_write2_b32 v39, v0, v19 offset0:48 offset1:114
	v_lshlrev_b64 v[58:59], 11, v[58:59]
	s_waitcnt vmcnt(5)
	v_cndmask_b32_e32 v0, 0, v65, vcc
	s_waitcnt vmcnt(4)
	v_cndmask_b32_e32 v19, 0, v66, vcc
	ds_write2_b32 v39, v0, v19 offset0:180 offset1:246
	v_add_u32_e32 v39, 0x1c00, v23
	s_waitcnt vmcnt(3)
	v_cndmask_b32_e32 v0, 0, v67, vcc
	s_waitcnt vmcnt(2)
	v_cndmask_b32_e32 v19, 0, v68, vcc
	ds_write2_b32 v39, v0, v19 offset0:56 offset1:122
	s_waitcnt vmcnt(1)
	v_cndmask_b32_e32 v0, 0, v38, vcc
	s_waitcnt vmcnt(0)
	v_cndmask_b32_e32 v18, 0, v18, vcc
	ds_write2_b32 v39, v0, v18 offset0:188 offset1:254
	s_waitcnt vmcnt(0) expcnt(0) lgkmcnt(0)
	ds_read2_b32 v[42:43], v25 offset0:33 offset1:41
	ds_read2_b32 v[44:45], v25 offset1:8
	ds_read2_b32 v[46:47], v25 offset0:66 offset1:74
	ds_read2_b32 v[48:49], v25 offset0:99 offset1:107
	ds_read2_b32 v[50:51], v25 offset0:132 offset1:140
	ds_read2_b32 v[52:53], v25 offset0:165 offset1:173
	ds_read2_b32 v[54:55], v25 offset0:198 offset1:206
	ds_read2_b32 v[56:57], v25 offset0:231 offset1:239
	v_lshl_add_u64 v[18:19], s[28:29], 1, v[4:5]
	s_waitcnt lgkmcnt(6)
	v_cvt_pk_bf16_f32 v38, v44, v42
	v_lshl_add_u64 v[58:59], v[18:19], 0, v[58:59]
	v_or_b32_e32 v42, s47, v26
	s_waitcnt lgkmcnt(4)
	v_cvt_pk_bf16_f32 v39, v46, v48
	s_waitcnt lgkmcnt(2)
	v_cvt_pk_bf16_f32 v40, v50, v52
	s_waitcnt lgkmcnt(0)
	v_cvt_pk_bf16_f32 v41, v54, v56
	global_store_dwordx4 v[58:59], v[38:41], off
	v_or_b32_e32 v58, s47, v27
	v_ashrrev_i32_e32 v59, 31, v58
	v_cvt_pk_bf16_f32 v38, v45, v43
	v_ashrrev_i32_e32 v43, 31, v42
	v_lshlrev_b64 v[42:43], 11, v[42:43]
	v_lshl_add_u64 v[42:43], v[18:19], 0, v[42:43]
	v_cvt_pk_bf16_f32 v39, v47, v49
	v_cvt_pk_bf16_f32 v40, v51, v53
	v_cvt_pk_bf16_f32 v41, v55, v57
	global_store_dwordx4 v[42:43], v[38:41], off
	ds_read2_b32 v[42:43], v25 offset0:16 offset1:24
	ds_read2_b32 v[44:45], v25 offset0:49 offset1:57
	ds_read2_b32 v[46:47], v25 offset0:82 offset1:90
	ds_read2_b32 v[48:49], v25 offset0:115 offset1:123
	ds_read2_b32 v[50:51], v25 offset0:148 offset1:156
	ds_read2_b32 v[52:53], v25 offset0:181 offset1:189
	ds_read2_b32 v[54:55], v25 offset0:214 offset1:222
	ds_read2_b32 v[56:57], v25 offset0:247 offset1:255
	v_lshlrev_b64 v[58:59], 11, v[58:59]
	s_waitcnt lgkmcnt(6)
	v_cvt_pk_bf16_f32 v38, v42, v44
	v_lshl_add_u64 v[58:59], v[18:19], 0, v[58:59]
	v_or_b32_e32 v42, s47, v28
	s_waitcnt lgkmcnt(4)
	v_cvt_pk_bf16_f32 v39, v46, v48
	s_waitcnt lgkmcnt(2)
	v_cvt_pk_bf16_f32 v40, v50, v52
	s_waitcnt lgkmcnt(0)
	v_cvt_pk_bf16_f32 v41, v54, v56
	global_store_dwordx4 v[58:59], v[38:41], off
	s_nop 1
	v_cvt_pk_bf16_f32 v38, v43, v45
	v_ashrrev_i32_e32 v43, 31, v42
	v_lshlrev_b64 v[42:43], 11, v[42:43]
	v_lshl_add_u64 v[18:19], v[18:19], 0, v[42:43]
	v_cvt_pk_bf16_f32 v39, v47, v49
	v_cvt_pk_bf16_f32 v40, v51, v53
	v_cvt_pk_bf16_f32 v41, v55, v57
	global_store_dwordx4 v[18:19], v[38:41], off
	s_waitcnt lgkmcnt(0)

; template <class Map>
; __device__ __forceinline__ void transpose_item(const float* W, int K, int N, bf16_t* WT, float* scr, int item, int nblk, int lane, Map srccol) {
;     const int kb = item / nblk, nb = item % nblk, k0 = 64 * kb, n0 = 32 * nb;
;     const int sc = srccol(n0 + (lane & 31));
;     float tv[32];
;     const float* wp = W + (size_t)(k0 + (lane >> 5)) * N + (sc >= 0 ? sc : 0);
; #pragma unroll
;     for (int i = 0; i < 32; ++i) tv[i] = wp[(size_t)(2 * i) * N];
; #pragma unroll
;     for (int i = 0; i < 32; ++i) { const int kk = 2 * i + (lane >> 5); scr[kk * 33 + (lane & 31)] = sc >= 0 ? tv[i] : 0.f; }
.LBB0_891:
	s_or_b64 exec, exec, s[6:7]
	s_lshl_b32 s28, s28, 6
	v_or_b32_e32 v0, s28, v22
	v_mov_b64_e32 v[38:39], s[16:17]
	s_movk_i32 s6, 0x3840
	v_mad_i64_i32 v[38:39], s[6:7], v0, s6, v[38:39]
	v_cmp_lt_i32_e64 s[6:7], -1, v18
	s_mov_b32 s29, 0x15000
	s_nop 0
	v_cndmask_b32_e64 v0, 0, v18, s[6:7]
	v_lshl_add_u64 v[18:19], v[0:1], 2, v[38:39]
	v_add_co_u32_e32 v38, vcc, 0x7000, v18
	global_load_dword v0, v[18:19], off
	s_nop 0
	v_addc_co_u32_e32 v39, vcc, 0, v19, vcc
	global_load_dword v40, v[38:39], off offset:128
	v_add_co_u32_e32 v38, vcc, s72, v18
	s_waitcnt vmcnt(1)
	v_cndmask_b32_e64 v0, 0, v0, s[6:7]
	v_addc_co_u32_e32 v39, vcc, 0, v19, vcc
	global_load_dword v41, v[38:39], off offset:256
	v_add_co_u32_e32 v38, vcc, s29, v18
	s_mov_b32 s29, 0x23000
	s_nop 0
	v_addc_co_u32_e32 v39, vcc, 0, v19, vcc
	global_load_dword v42, v[38:39], off offset:384
	v_add_co_u32_e32 v38, vcc, s62, v18
	ds_write_b32 v30, v0
	s_nop 0
	v_addc_co_u32_e32 v39, vcc, 0, v19, vcc
	global_load_dword v43, v[38:39], off offset:512
	v_add_co_u32_e32 v38, vcc, s29, v18
	s_mov_b32 s29, 0x31000
	s_nop 0
	v_addc_co_u32_e32 v39, vcc, 0, v19, vcc
	global_load_dword v44, v[38:39], off offset:640
	v_add_co_u32_e32 v38, vcc, s77, v18
	s_waitcnt vmcnt(4)
	v_cndmask_b32_e64 v0, 0, v40, s[6:7]
	v_addc_co_u32_e32 v39, vcc, 0, v19, vcc
	global_load_dword v45, v[38:39], off offset:768
	v_add_co_u32_e32 v38, vcc, s29, v18
	s_mov_b32 s29, 0x3f000
	s_nop 0
	v_addc_co_u32_e32 v39, vcc, 0, v19, vcc
	global_load_dword v46, v[38:39], off offset:896
	v_add_co_u32_e32 v38, vcc, s84, v18
	s_nop 1
	v_addc_co_u32_e32 v39, vcc, 0, v19, vcc
	global_load_dword v47, v[38:39], off offset:1024
	v_add_co_u32_e32 v38, vcc, s29, v18
	s_mov_b32 s29, 0x46000
	s_nop 0
	v_addc_co_u32_e32 v39, vcc, 0, v19, vcc
	global_load_dword v48, v[38:39], off offset:1152
	v_add_co_u32_e32 v38, vcc, s29, v18
	s_mov_b32 s29, 0x4d000
	s_nop 0
	v_addc_co_u32_e32 v39, vcc, 0, v19, vcc
	global_load_dword v49, v[38:39], off offset:1280
	v_add_co_u32_e32 v38, vcc, s29, v18
	s_mov_b32 s29, 0x54000
	s_nop 0
	v_addc_co_u32_e32 v39, vcc, 0, v19, vcc
	global_load_dword v50, v[38:39], off offset:1408
	v_add_co_u32_e32 v38, vcc, s29, v18
	s_mov_b32 s29, 0x5b000
	s_nop 0
	v_addc_co_u32_e32 v39, vcc, 0, v19, vcc
	global_load_dword v51, v[38:39], off offset:1536
	v_add_co_u32_e32 v38, vcc, s29, v18
	s_mov_b32 s29, 0x62000
	s_nop 0
	v_addc_co_u32_e32 v39, vcc, 0, v19, vcc
	global_load_dword v52, v[38:39], off offset:1664
	v_add_co_u32_e32 v38, vcc, s29, v18
	s_mov_b32 s29, 0x69000
	s_nop 0
	v_addc_co_u32_e32 v39, vcc, 0, v19, vcc
	global_load_dword v53, v[38:39], off offset:1792
	v_add_co_u32_e32 v38, vcc, s29, v18
	s_mov_b32 s29, 0x70000
	s_nop 0
	v_addc_co_u32_e32 v39, vcc, 0, v19, vcc
	global_load_dword v54, v[38:39], off offset:1920
	v_add_co_u32_e32 v38, vcc, s29, v18
	s_mov_b32 s29, 0x77000
	s_nop 0
	v_addc_co_u32_e32 v39, vcc, 0, v19, vcc
	global_load_dword v55, v[38:39], off offset:2048
	v_add_co_u32_e32 v38, vcc, s29, v18
	s_mov_b32 s29, 0x7e000
	s_nop 0
	v_addc_co_u32_e32 v39, vcc, 0, v19, vcc
	global_load_dword v56, v[38:39], off offset:2176
	v_add_co_u32_e32 v38, vcc, s29, v18
	s_mov_b32 s29, 0x85000
	s_nop 0
	v_addc_co_u32_e32 v39, vcc, 0, v19, vcc
	global_load_dword v57, v[38:39], off offset:2304
	v_add_co_u32_e32 v38, vcc, s29, v18
	s_mov_b32 s29, 0x8c000
	s_nop 0
	v_addc_co_u32_e32 v39, vcc, 0, v19, vcc
	global_load_dword v58, v[38:39], off offset:2432
	v_add_co_u32_e32 v38, vcc, s29, v18
	s_mov_b32 s29, 0x93000
	s_nop 0
	v_addc_co_u32_e32 v39, vcc, 0, v19, vcc
	global_load_dword v59, v[38:39], off offset:2560
	v_add_co_u32_e32 v38, vcc, s29, v18
	s_mov_b32 s29, 0x9a000
	s_nop 0
	v_addc_co_u32_e32 v39, vcc, 0, v19, vcc
	global_load_dword v60, v[38:39], off offset:2688
	v_add_co_u32_e32 v38, vcc, s29, v18
	s_mov_b32 s29, 0xa1000
	s_nop 0
	v_addc_co_u32_e32 v39, vcc, 0, v19, vcc
	global_load_dword v61, v[38:39], off offset:2816
	v_add_co_u32_e32 v38, vcc, s29, v18
	s_mov_b32 s29, 0xa8000
	s_nop 0
	v_addc_co_u32_e32 v39, vcc, 0, v19, vcc
	global_load_dword v62, v[38:39], off offset:2944
	v_add_co_u32_e32 v38, vcc, s29, v18
	s_mov_b32 s29, 0xaf000
	s_nop 0
	v_addc_co_u32_e32 v39, vcc, 0, v19, vcc
	global_load_dword v63, v[38:39], off offset:3072
	v_add_co_u32_e32 v38, vcc, s29, v18
	s_mov_b32 s29, 0xb6000
	s_nop 0
	v_addc_co_u32_e32 v39, vcc, 0, v19, vcc
	global_load_dword v64, v[38:39], off offset:3200
	v_add_co_u32_e32 v38, vcc, s29, v18
	s_mov_b32 s29, 0xbd000
	s_nop 0
	v_addc_co_u32_e32 v39, vcc, 0, v19, vcc
	global_load_dword v65, v[38:39], off offset:3328
	v_add_co_u32_e32 v38, vcc, s29, v18
	s_mov_b32 s29, 0xc4000
	s_nop 0
	v_addc_co_u32_e32 v39, vcc, 0, v19, vcc
	global_load_dword v66, v[38:39], off offset:3456
	v_add_co_u32_e32 v38, vcc, s29, v18
	s_mov_b32 s29, 0xcb000
	s_nop 0
	v_addc_co_u32_e32 v39, vcc, 0, v19, vcc
	global_load_dword v67, v[38:39], off offset:3584
	v_add_co_u32_e32 v38, vcc, s29, v18
	s_mov_b32 s29, 0xd2000
	s_nop 0
	v_addc_co_u32_e32 v39, vcc, 0, v19, vcc
	global_load_dword v68, v[38:39], off offset:3712
	v_add_co_u32_e32 v38, vcc, s29, v18
	s_mov_b32 s29, 0xd9000
	s_nop 0
	v_addc_co_u32_e32 v39, vcc, 0, v19, vcc
	v_add_co_u32_e32 v18, vcc, s29, v18
	global_load_dword v38, v[38:39], off offset:3840
	s_nop 0
	v_addc_co_u32_e32 v19, vcc, 0, v19, vcc
	global_load_dword v18, v[18:19], off offset:3968
	s_waitcnt vmcnt(29)
; __device__ __forceinline__ unsigned pk2(float lo, float hi) { unsigned r; asm("v_cvt_pk_bf16_f32 %0, %1, %2" : "=v"(r) : "v"(lo), "v"(hi)); return r; }
; template <class Map>
; __device__ __forceinline__ void transpose_item(const float* W, int K, int N, bf16_t* WT, float* scr, int item, int nblk, int lane, Map srccol) {
;     ...
;     for (int i = 0; i < 32; ++i) { const int kk = 2 * i + (lane >> 5); scr[kk * 33 + (lane & 31)] = sc >= 0 ? tv[i] : 0.f; }
;     __builtin_amdgcn_s_waitcnt(0); asm volatile("" ::: "memory");
;     const int c = lane & 7;
; #pragma unroll
;     for (int j = 0; j < 4; ++j) { const int n = (lane >> 3) + 8 * j; const float* s = scr + (8 * c) * 33 + n;
;         u32x4 o; o.x = pk2(s[0 * 33], s[1 * 33]); o.y = pk2(s[2 * 33], s[3 * 33]); o.z = pk2(s[4 * 33], s[5 * 33]); o.w = pk2(s[6 * 33], s[7 * 33]);
;         *(u32x4*)(WT + (size_t)(n0 + n) * K + k0 + 8 * c) = o; }
;     __builtin_amdgcn_s_waitcnt(0); asm volatile("" ::: "memory");
	v_cndmask_b32_e64 v19, 0, v41, s[6:7]
	ds_write2_b32 v31, v0, v19 offset0:66 offset1:132
	s_waitcnt vmcnt(28)
	v_cndmask_b32_e64 v0, 0, v42, s[6:7]
	s_waitcnt vmcnt(27)
	v_cndmask_b32_e64 v19, 0, v43, s[6:7]
	v_add_u32_e32 v39, 0x200, v31
	ds_write2_b32 v39, v0, v19 offset0:70 offset1:136
	s_waitcnt vmcnt(26)
	v_cndmask_b32_e64 v0, 0, v44, s[6:7]
	s_waitcnt vmcnt(25)
	v_cndmask_b32_e64 v19, 0, v45, s[6:7]
	v_add_u32_e32 v39, 0x400, v31
	ds_write2_b32 v39, v0, v19 offset0:74 offset1:140
	s_waitcnt vmcnt(24)
	v_cndmask_b32_e64 v0, 0, v46, s[6:7]
	s_waitcnt vmcnt(23)
	v_cndmask_b32_e64 v19, 0, v47, s[6:7]
	v_add_u32_e32 v39, 0x600, v31
	ds_write2_b32 v39, v0, v19 offset0:78 offset1:144
	s_waitcnt vmcnt(22)
	v_cndmask_b32_e64 v0, 0, v48, s[6:7]
	s_waitcnt vmcnt(21)
	v_cndmask_b32_e64 v19, 0, v49, s[6:7]
	v_add_u32_e32 v39, 0x800, v31
	ds_write2_b32 v39, v0, v19 offset0:82 offset1:148
	s_waitcnt vmcnt(20)
	v_cndmask_b32_e64 v0, 0, v50, s[6:7]
	s_waitcnt vmcnt(19)
	v_cndmask_b32_e64 v19, 0, v51, s[6:7]
	v_add_u32_e32 v39, 0xa00, v31
	ds_write2_b32 v39, v0, v19 offset0:86 offset1:152
	s_waitcnt vmcnt(18)
	v_cndmask_b32_e64 v0, 0, v52, s[6:7]
	s_waitcnt vmcnt(17)
	v_cndmask_b32_e64 v19, 0, v53, s[6:7]
	v_add_u32_e32 v39, 0xc00, v31
	ds_write2_b32 v39, v0, v19 offset0:90 offset1:156
	s_waitcnt vmcnt(15)
	v_cndmask_b32_e64 v19, 0, v55, s[6:7]
	v_cndmask_b32_e64 v0, 0, v54, s[6:7]
	ds_write_b32 v32, v19
	s_waitcnt vmcnt(14)
	v_cndmask_b32_e64 v19, 0, v56, s[6:7]
	v_add_u32_e32 v39, 0xe00, v31
	ds_write2_b32 v39, v0, v19 offset0:94 offset1:226
	s_waitcnt vmcnt(13)
	v_cndmask_b32_e64 v0, 0, v57, s[6:7]
	s_waitcnt vmcnt(12)
	v_cndmask_b32_e64 v19, 0, v58, s[6:7]
	v_add_u32_e32 v39, 0x1000, v31
	ds_write2_b32 v39, v0, v19 offset0:164 offset1:230
	s_waitcnt vmcnt(11)
	v_cndmask_b32_e64 v0, 0, v59, s[6:7]
	s_waitcnt vmcnt(10)
	v_cndmask_b32_e64 v19, 0, v60, s[6:7]
	v_add_u32_e32 v39, 0x1400, v31
	ds_write2_b32 v39, v0, v19 offset0:40 offset1:106
	s_waitcnt vmcnt(9)
	v_cndmask_b32_e64 v0, 0, v61, s[6:7]
	s_waitcnt vmcnt(8)
	v_cndmask_b32_e64 v19, 0, v62, s[6:7]
	ds_write2_b32 v39, v0, v19 offset0:172 offset1:238
	s_waitcnt vmcnt(7)
	v_cndmask_b32_e64 v0, 0, v63, s[6:7]
	s_waitcnt vmcnt(6)
	v_cndmask_b32_e64 v19, 0, v64, s[6:7]
	v_add_u32_e32 v39, 0x1800, v31
	ds_write2_b32 v39, v0, v19 offset0:48 offset1:114
	v_add_u32_e32 v58, s47, v24
	s_ashr_i32 s29, s28, 31
	v_ashrrev_i32_e32 v59, 31, v58
	s_waitcnt vmcnt(5)
	v_cndmask_b32_e64 v0, 0, v65, s[6:7]
	v_lshlrev_b64 v[60:61], 11, v[58:59]
	s_waitcnt vmcnt(4)
	v_cndmask_b32_e64 v19, 0, v66, s[6:7]
	ds_write2_b32 v39, v0, v19 offset0:180 offset1:246
	v_add_u32_e32 v39, 0x1c00, v31
	s_waitcnt vmcnt(3)
	v_cndmask_b32_e64 v0, 0, v67, s[6:7]
	s_waitcnt vmcnt(2)
	v_cndmask_b32_e64 v19, 0, v68, s[6:7]
	ds_write2_b32 v39, v0, v19 offset0:56 offset1:122
	s_waitcnt vmcnt(1)
	v_cndmask_b32_e64 v0, 0, v38, s[6:7]
	s_waitcnt vmcnt(0)
	v_cndmask_b32_e64 v18, 0, v18, s[6:7]
	ds_write2_b32 v39, v0, v18 offset0:188 offset1:254
	s_waitcnt vmcnt(0) expcnt(0) lgkmcnt(0)
	ds_read2_b32 v[42:43], v25 offset0:33 offset1:41
	ds_read2_b32 v[44:45], v25 offset1:8
	ds_read2_b32 v[46:47], v25 offset0:66 offset1:74
	ds_read2_b32 v[48:49], v25 offset0:99 offset1:107
	ds_read2_b32 v[50:51], v25 offset0:132 offset1:140
	ds_read2_b32 v[52:53], v25 offset0:165 offset1:173
	ds_read2_b32 v[54:55], v25 offset0:198 offset1:206
	ds_read2_b32 v[56:57], v25 offset0:231 offset1:239
	v_lshl_add_u64 v[18:19], s[28:29], 1, v[6:7]
	s_waitcnt lgkmcnt(6)
	v_cvt_pk_bf16_f32 v38, v44, v42
	v_lshl_add_u64 v[60:61], v[18:19], 0, v[60:61]
	v_add_u32_e32 v42, 8, v58
	s_waitcnt lgkmcnt(4)
	v_cvt_pk_bf16_f32 v39, v46, v48
	s_waitcnt lgkmcnt(2)
	v_cvt_pk_bf16_f32 v40, v50, v52
	s_waitcnt lgkmcnt(0)
	v_cvt_pk_bf16_f32 v41, v54, v56
	global_store_dwordx4 v[60:61], v[38:41], off
	v_add_u32_e32 v60, 16, v58
	v_ashrrev_i32_e32 v61, 31, v60
	v_cvt_pk_bf16_f32 v38, v45, v43
	v_ashrrev_i32_e32 v43, 31, v42
	v_lshlrev_b64 v[42:43], 11, v[42:43]
	v_lshl_add_u64 v[42:43], v[18:19], 0, v[42:43]
	v_cvt_pk_bf16_f32 v39, v47, v49
	v_cvt_pk_bf16_f32 v40, v51, v53
	v_cvt_pk_bf16_f32 v41, v55, v57
	global_store_dwordx4 v[42:43], v[38:41], off
	ds_read2_b32 v[42:43], v25 offset0:16 offset1:24
	ds_read2_b32 v[44:45], v25 offset0:49 offset1:57
	ds_read2_b32 v[46:47], v25 offset0:82 offset1:90
	ds_read2_b32 v[48:49], v25 offset0:115 offset1:123
	ds_read2_b32 v[50:51], v25 offset0:148 offset1:156
	ds_read2_b32 v[52:53], v25 offset0:181 offset1:189
	ds_read2_b32 v[54:55], v25 offset0:214 offset1:222
	ds_read2_b32 v[56:57], v25 offset0:247 offset1:255
	v_lshlrev_b64 v[60:61], 11, v[60:61]
	s_waitcnt lgkmcnt(6)
	v_cvt_pk_bf16_f32 v38, v42, v44
	v_lshl_add_u64 v[60:61], v[18:19], 0, v[60:61]
	v_add_u32_e32 v42, 24, v58
	s_waitcnt lgkmcnt(4)
	v_cvt_pk_bf16_f32 v39, v46, v48
	s_waitcnt lgkmcnt(2)
	v_cvt_pk_bf16_f32 v40, v50, v52
	s_waitcnt lgkmcnt(0)
	v_cvt_pk_bf16_f32 v41, v54, v56
	global_store_dwordx4 v[60:61], v[38:41], off
	s_nop 1
	v_cvt_pk_bf16_f32 v38, v43, v45
	v_ashrrev_i32_e32 v43, 31, v42
	v_lshlrev_b64 v[42:43], 11, v[42:43]
	v_lshl_add_u64 v[18:19], v[18:19], 0, v[42:43]
	v_cvt_pk_bf16_f32 v39, v47, v49
	v_cvt_pk_bf16_f32 v40, v51, v53
	v_cvt_pk_bf16_f32 v41, v55, v57
	global_store_dwordx4 v[18:19], v[38:41], off
	s_waitcnt lgkmcnt(0)

; template <class Map>
; __device__ __forceinline__ void transpose_item(const float* W, int K, int N, bf16_t* WT, float* scr, int item, int nblk, int lane, Map srccol) {
;     const int kb = item / nblk, nb = item % nblk, k0 = 64 * kb, n0 = 32 * nb;
;     const int sc = srccol(n0 + (lane & 31));
;     float tv[32];
;     const float* wp = W + (size_t)(k0 + (lane >> 5)) * N + (sc >= 0 ? sc : 0);
; #pragma unroll
;     for (int i = 0; i < 32; ++i) tv[i] = wp[(size_t)(2 * i) * N];
; #pragma unroll
;     for (int i = 0; i < 32; ++i) { const int kk = 2 * i + (lane >> 5); scr[kk * 33 + (lane & 31)] = sc >= 0 ? tv[i] : 0.f; }
.LBB0_893:
	s_and_b64 vcc, exec, s[6:7]
	s_cbranch_vccz .LBB0_895
	s_ashr_i32 s6, s43, 31
	s_lshr_b32 s6, s6, 27
	s_add_i32 s6, s43, s6
	s_and_b32 s7, s6, 0xffffffe0
	s_sub_i32 s7, s43, s7
	s_lshl_b32 s6, s6, 1
	s_lshl_b32 s47, s7, 5
	s_and_b32 s28, s6, 0xffffffc0
	v_and_b32_e32 v0, 24, v36
	v_bitop3_b32 v18, s47, v206, v21 bitop3:0xc8
	v_or3_b32 v0, v18, v0, v29
	v_or_b32_e32 v18, s28, v22
	v_ashrrev_i32_e32 v19, 31, v18
	s_cmp_gt_i32 s7, -1
	v_lshlrev_b64 v[18:19], 12, v[18:19]
	s_cselect_b64 vcc, -1, 0
	v_lshl_add_u64 v[18:19], s[10:11], 0, v[18:19]
	v_cndmask_b32_e32 v0, 0, v0, vcc
	v_lshl_add_u64 v[18:19], v[0:1], 2, v[18:19]
	v_add_co_u32_e64 v38, s[6:7], s63, v18
	global_load_dword v0, v[18:19], off
	s_nop 0
	v_addc_co_u32_e64 v39, s[6:7], 0, v19, s[6:7]
	global_load_dword v40, v[38:39], off
	v_add_co_u32_e64 v38, s[6:7], s96, v18
	s_ashr_i32 s29, s28, 31
	s_nop 0
	v_addc_co_u32_e64 v39, s[6:7], 0, v19, s[6:7]
	global_load_dword v41, v[38:39], off
	v_add_co_u32_e64 v38, s[6:7], s58, v18
	s_waitcnt vmcnt(2)
	v_cndmask_b32_e32 v0, 0, v0, vcc
	v_addc_co_u32_e64 v39, s[6:7], 0, v19, s[6:7]
	global_load_dword v42, v[38:39], off
	v_add_co_u32_e64 v38, s[6:7], s60, v18
	s_nop 1
	v_addc_co_u32_e64 v39, s[6:7], 0, v19, s[6:7]
	global_load_dword v43, v[38:39], off
	v_add_co_u32_e64 v38, s[6:7], s54, v18
	s_nop 1
	v_addc_co_u32_e64 v39, s[6:7], 0, v19, s[6:7]
	global_load_dword v44, v[38:39], off
	v_add_co_u32_e64 v38, s[6:7], s71, v18
	s_nop 1
	v_addc_co_u32_e64 v39, s[6:7], 0, v19, s[6:7]
	global_load_dword v45, v[38:39], off
	v_add_co_u32_e64 v38, s[6:7], s72, v18
	s_nop 1
	v_addc_co_u32_e64 v39, s[6:7], 0, v19, s[6:7]
	global_load_dword v46, v[38:39], off
	v_add_co_u32_e64 v38, s[6:7], s50, v18
	s_nop 1
	v_addc_co_u32_e64 v39, s[6:7], 0, v19, s[6:7]
	global_load_dword v47, v[38:39], off
	v_add_co_u32_e64 v38, s[6:7], s55, v18
	s_nop 1
	v_addc_co_u32_e64 v39, s[6:7], 0, v19, s[6:7]
	global_load_dword v48, v[38:39], off
	v_add_co_u32_e64 v38, s[6:7], s56, v18
	s_nop 1
	v_addc_co_u32_e64 v39, s[6:7], 0, v19, s[6:7]
	global_load_dword v49, v[38:39], off
	v_add_co_u32_e64 v38, s[6:7], s57, v18
	s_nop 1
	v_addc_co_u32_e64 v39, s[6:7], 0, v19, s[6:7]
	global_load_dword v50, v[38:39], off
	v_add_co_u32_e64 v38, s[6:7], s59, v18
	s_nop 1
	v_addc_co_u32_e64 v39, s[6:7], 0, v19, s[6:7]
	global_load_dword v51, v[38:39], off
	v_add_co_u32_e64 v38, s[6:7], s52, v18
	s_nop 1
	v_addc_co_u32_e64 v39, s[6:7], 0, v19, s[6:7]
	global_load_dword v52, v[38:39], off
	v_add_co_u32_e64 v38, s[6:7], s62, v18
	s_nop 1
	v_addc_co_u32_e64 v39, s[6:7], 0, v19, s[6:7]
	global_load_dword v53, v[38:39], off
	v_add_co_u32_e64 v38, s[6:7], s64, v18
	s_nop 1
	v_addc_co_u32_e64 v39, s[6:7], 0, v19, s[6:7]
	global_load_dword v54, v[38:39], off
	v_add_co_u32_e64 v38, s[6:7], s73, v18
	s_nop 1
	v_addc_co_u32_e64 v39, s[6:7], 0, v19, s[6:7]
	global_load_dword v55, v[38:39], off
	v_add_co_u32_e64 v38, s[6:7], s74, v18
	s_nop 1
	v_addc_co_u32_e64 v39, s[6:7], 0, v19, s[6:7]
	global_load_dword v56, v[38:39], off
	v_add_co_u32_e64 v38, s[6:7], s75, v18
	s_nop 1
	v_addc_co_u32_e64 v39, s[6:7], 0, v19, s[6:7]
	global_load_dword v57, v[38:39], off
	v_add_co_u32_e64 v38, s[6:7], s1, v18
	s_nop 1
	v_addc_co_u32_e64 v39, s[6:7], 0, v19, s[6:7]
	global_load_dword v58, v[38:39], off
	v_add_co_u32_e64 v38, s[6:7], s76, v18
	s_nop 1
	v_addc_co_u32_e64 v39, s[6:7], 0, v19, s[6:7]
	global_load_dword v59, v[38:39], off
	v_add_co_u32_e64 v38, s[6:7], s77, v18
	s_nop 1
	v_addc_co_u32_e64 v39, s[6:7], 0, v19, s[6:7]
	global_load_dword v60, v[38:39], off
	v_add_co_u32_e64 v38, s[6:7], s33, v18
	s_nop 1
	v_addc_co_u32_e64 v39, s[6:7], 0, v19, s[6:7]
	global_load_dword v61, v[38:39], off
	v_add_co_u32_e64 v38, s[6:7], s80, v18
	s_nop 1
	v_addc_co_u32_e64 v39, s[6:7], 0, v19, s[6:7]
	global_load_dword v62, v[38:39], off
	v_add_co_u32_e64 v38, s[6:7], s0, v18
	s_nop 1
	v_addc_co_u32_e64 v39, s[6:7], 0, v19, s[6:7]
	global_load_dword v63, v[38:39], off
	v_add_co_u32_e64 v38, s[6:7], s81, v18
	s_nop 1
	v_addc_co_u32_e64 v39, s[6:7], 0, v19, s[6:7]
	global_load_dword v64, v[38:39], off
	v_add_co_u32_e64 v38, s[6:7], s82, v18
	s_nop 1
	v_addc_co_u32_e64 v39, s[6:7], 0, v19, s[6:7]
	global_load_dword v65, v[38:39], off
	v_add_co_u32_e64 v38, s[6:7], s83, v18
	s_nop 1
	v_addc_co_u32_e64 v39, s[6:7], 0, v19, s[6:7]
	global_load_dword v66, v[38:39], off
	v_add_co_u32_e64 v38, s[6:7], s84, v18
	s_nop 1
	v_addc_co_u32_e64 v39, s[6:7], 0, v19, s[6:7]
	global_load_dword v67, v[38:39], off
	v_add_co_u32_e64 v38, s[6:7], s85, v18
	s_nop 1
	v_addc_co_u32_e64 v39, s[6:7], 0, v19, s[6:7]
	global_load_dword v68, v[38:39], off
	v_add_co_u32_e64 v38, s[6:7], s86, v18
	s_nop 1
	v_addc_co_u32_e64 v39, s[6:7], 0, v19, s[6:7]
	v_add_co_u32_e64 v18, s[6:7], s87, v18
	global_load_dword v38, v[38:39], off
	s_nop 0
	v_addc_co_u32_e64 v19, s[6:7], 0, v19, s[6:7]
	global_load_dword v18, v[18:19], off
	s_waitcnt vmcnt(30)
	v_cndmask_b32_e32 v19, 0, v40, vcc
	ds_write2_b32 v23, v0, v19 offset1:66
	s_waitcnt vmcnt(29)
; __device__ __forceinline__ unsigned pk2(float lo, float hi) { unsigned r; asm("v_cvt_pk_bf16_f32 %0, %1, %2" : "=v"(r) : "v"(lo), "v"(hi)); return r; }
; template <class Map>
; __device__ __forceinline__ void transpose_item(const float* W, int K, int N, bf16_t* WT, float* scr, int item, int nblk, int lane, Map srccol) {
;     ...
;     for (int i = 0; i < 32; ++i) { const int kk = 2 * i + (lane >> 5); scr[kk * 33 + (lane & 31)] = sc >= 0 ? tv[i] : 0.f; }
;     __builtin_amdgcn_s_waitcnt(0); asm volatile("" ::: "memory");
;     const int c = lane & 7;
; #pragma unroll
;     for (int j = 0; j < 4; ++j) { const int n = (lane >> 3) + 8 * j; const float* s = scr + (8 * c) * 33 + n;
;         u32x4 o; o.x = pk2(s[0 * 33], s[1 * 33]); o.y = pk2(s[2 * 33], s[3 * 33]); o.z = pk2(s[4 * 33], s[5 * 33]); o.w = pk2(s[6 * 33], s[7 * 33]);
;         *(u32x4*)(WT + (size_t)(n0 + n) * K + k0 + 8 * c) = o; }
;     __builtin_amdgcn_s_waitcnt(0); asm volatile("" ::: "memory");
	v_cndmask_b32_e32 v0, 0, v41, vcc
	s_waitcnt vmcnt(28)
	v_cndmask_b32_e32 v19, 0, v42, vcc
	ds_write2_b32 v23, v0, v19 offset0:132 offset1:198
	s_waitcnt vmcnt(27)
	v_cndmask_b32_e32 v0, 0, v43, vcc
	s_waitcnt vmcnt(26)
	v_cndmask_b32_e32 v19, 0, v44, vcc
	v_add_u32_e32 v39, 0x400, v23
	ds_write2_b32 v39, v0, v19 offset0:8 offset1:74
	s_waitcnt vmcnt(25)
	v_cndmask_b32_e32 v0, 0, v45, vcc
	s_waitcnt vmcnt(24)
	v_cndmask_b32_e32 v19, 0, v46, vcc
	ds_write2_b32 v39, v0, v19 offset0:140 offset1:206
	s_waitcnt vmcnt(23)
	v_cndmask_b32_e32 v0, 0, v47, vcc
	s_waitcnt vmcnt(22)
	v_cndmask_b32_e32 v19, 0, v48, vcc
	v_add_u32_e32 v39, 0x800, v23
	ds_write2_b32 v39, v0, v19 offset0:16 offset1:82
	s_waitcnt vmcnt(21)
	v_cndmask_b32_e32 v0, 0, v49, vcc
	s_waitcnt vmcnt(20)
	v_cndmask_b32_e32 v19, 0, v50, vcc
	ds_write2_b32 v39, v0, v19 offset0:148 offset1:214
	s_waitcnt vmcnt(19)
	v_cndmask_b32_e32 v0, 0, v51, vcc
	s_waitcnt vmcnt(18)
	v_cndmask_b32_e32 v19, 0, v52, vcc
	v_add_u32_e32 v39, 0xc00, v23
	ds_write2_b32 v39, v0, v19 offset0:24 offset1:90
	s_waitcnt vmcnt(17)
	v_cndmask_b32_e32 v0, 0, v53, vcc
	s_waitcnt vmcnt(16)
	v_cndmask_b32_e32 v19, 0, v54, vcc
	ds_write2_b32 v39, v0, v19 offset0:156 offset1:222
	s_waitcnt vmcnt(15)
	v_cndmask_b32_e32 v0, 0, v55, vcc
	s_waitcnt vmcnt(14)
	v_cndmask_b32_e32 v19, 0, v56, vcc
	v_add_u32_e32 v39, 0x1000, v23
	ds_write2_b32 v39, v0, v19 offset0:32 offset1:98
	s_waitcnt vmcnt(13)
	v_cndmask_b32_e32 v0, 0, v57, vcc
	s_waitcnt vmcnt(12)
	v_cndmask_b32_e32 v19, 0, v58, vcc
	ds_write2_b32 v39, v0, v19 offset0:164 offset1:230
	s_waitcnt vmcnt(11)
	v_cndmask_b32_e32 v0, 0, v59, vcc
	s_waitcnt vmcnt(10)
	v_cndmask_b32_e32 v19, 0, v60, vcc
	v_add_u32_e32 v39, 0x1400, v23
	ds_write2_b32 v39, v0, v19 offset0:40 offset1:106
	s_waitcnt vmcnt(9)
	v_cndmask_b32_e32 v0, 0, v61, vcc
	s_waitcnt vmcnt(8)
	v_cndmask_b32_e32 v19, 0, v62, vcc
	ds_write2_b32 v39, v0, v19 offset0:172 offset1:238
	s_waitcnt vmcnt(7)
	v_cndmask_b32_e32 v0, 0, v63, vcc
	v_add_u32_e32 v39, 0x1800, v23
	s_waitcnt vmcnt(6)
	v_cndmask_b32_e32 v19, 0, v64, vcc
	ds_write2_b32 v39, v0, v19 offset0:48 offset1:114
	s_waitcnt vmcnt(5)
	v_cndmask_b32_e32 v0, 0, v65, vcc
	s_waitcnt vmcnt(4)
	v_cndmask_b32_e32 v19, 0, v66, vcc
	ds_write2_b32 v39, v0, v19 offset0:180 offset1:246
	v_add_u32_e32 v39, 0x1c00, v23
	s_waitcnt vmcnt(3)
	v_cndmask_b32_e32 v0, 0, v67, vcc
	s_waitcnt vmcnt(2)
	v_cndmask_b32_e32 v19, 0, v68, vcc
	ds_write2_b32 v39, v0, v19 offset0:56 offset1:122
	s_waitcnt vmcnt(1)
	v_cndmask_b32_e32 v0, 0, v38, vcc
	s_waitcnt vmcnt(0)
	v_cndmask_b32_e32 v18, 0, v18, vcc
	ds_write2_b32 v39, v0, v18 offset0:188 offset1:254
	s_waitcnt vmcnt(0) expcnt(0) lgkmcnt(0)
	ds_read2_b32 v[42:43], v25 offset0:33 offset1:41
	ds_read2_b32 v[44:45], v25 offset1:8
	ds_read2_b32 v[46:47], v25 offset0:66 offset1:74
	ds_read2_b32 v[48:49], v25 offset0:99 offset1:107
	ds_read2_b32 v[50:51], v25 offset0:132 offset1:140
	ds_read2_b32 v[52:53], v25 offset0:165 offset1:173
	ds_read2_b32 v[54:55], v25 offset0:198 offset1:206
	ds_read2_b32 v[56:57], v25 offset0:231 offset1:239
	v_or_b32_e32 v0, s47, v24
	v_mul_i32_i24_e32 v58, 0xb00, v0
	v_lshl_add_u64 v[18:19], s[28:29], 1, v[14:15]
	v_ashrrev_i32_e32 v59, 31, v58
	v_or_b32_e32 v0, s47, v26
	s_waitcnt lgkmcnt(6)
	v_cvt_pk_bf16_f32 v38, v44, v42
	v_lshl_add_u64 v[58:59], v[58:59], 1, v[18:19]
	v_mul_i32_i24_e32 v42, 0xb00, v0
	s_waitcnt lgkmcnt(4)
	v_cvt_pk_bf16_f32 v39, v46, v48
	s_waitcnt lgkmcnt(2)
	v_cvt_pk_bf16_f32 v40, v50, v52
	s_waitcnt lgkmcnt(0)
	v_cvt_pk_bf16_f32 v41, v54, v56
	global_store_dwordx4 v[58:59], v[38:41], off
	v_or_b32_e32 v0, s47, v27
	v_mul_i32_i24_e32 v58, 0xb00, v0
	v_cvt_pk_bf16_f32 v38, v45, v43
	v_ashrrev_i32_e32 v43, 31, v42
	v_lshl_add_u64 v[42:43], v[42:43], 1, v[18:19]
	v_cvt_pk_bf16_f32 v39, v47, v49
	v_cvt_pk_bf16_f32 v40, v51, v53
	v_cvt_pk_bf16_f32 v41, v55, v57
	global_store_dwordx4 v[42:43], v[38:41], off
	ds_read2_b32 v[42:43], v25 offset0:16 offset1:24
	ds_read2_b32 v[44:45], v25 offset0:49 offset1:57
	ds_read2_b32 v[46:47], v25 offset0:82 offset1:90
	ds_read2_b32 v[48:49], v25 offset0:115 offset1:123
	ds_read2_b32 v[50:51], v25 offset0:148 offset1:156
	ds_read2_b32 v[52:53], v25 offset0:181 offset1:189
	ds_read2_b32 v[54:55], v25 offset0:214 offset1:222
	ds_read2_b32 v[56:57], v25 offset0:247 offset1:255
	v_ashrrev_i32_e32 v59, 31, v58
	v_or_b32_e32 v0, s47, v28
	s_waitcnt lgkmcnt(6)
	v_cvt_pk_bf16_f32 v38, v42, v44
	v_lshl_add_u64 v[58:59], v[58:59], 1, v[18:19]
	v_mul_i32_i24_e32 v42, 0xb00, v0
	s_waitcnt lgkmcnt(4)
	v_cvt_pk_bf16_f32 v39, v46, v48
	s_waitcnt lgkmcnt(2)
	v_cvt_pk_bf16_f32 v40, v50, v52
	s_waitcnt lgkmcnt(0)
	v_cvt_pk_bf16_f32 v41, v54, v56
	global_store_dwordx4 v[58:59], v[38:41], off
	s_nop 1
	v_cvt_pk_bf16_f32 v38, v43, v45
	v_ashrrev_i32_e32 v43, 31, v42
	v_lshl_add_u64 v[18:19], v[42:43], 1, v[18:19]
	v_cvt_pk_bf16_f32 v39, v47, v49
	v_cvt_pk_bf16_f32 v40, v51, v53
	v_cvt_pk_bf16_f32 v41, v55, v57
	global_store_dwordx4 v[18:19], v[38:41], off
	s_waitcnt lgkmcnt(0)

; template <class Map>
; __device__ __forceinline__ void transpose_item(const float* W, int K, int N, bf16_t* WT, float* scr, int item, int nblk, int lane, Map srccol) {
;     const int kb = item / nblk, nb = item % nblk, k0 = 64 * kb, n0 = 32 * nb;
;     const int sc = srccol(n0 + (lane & 31));
;     float tv[32];
;     const float* wp = W + (size_t)(k0 + (lane >> 5)) * N + (sc >= 0 ? sc : 0);
; #pragma unroll
;     for (int i = 0; i < 32; ++i) tv[i] = wp[(size_t)(2 * i) * N];
; #pragma unroll
;     for (int i = 0; i < 32; ++i) { const int kk = 2 * i + (lane >> 5); scr[kk * 33 + (lane & 31)] = sc >= 0 ? tv[i] : 0.f; }
.LBB0_896:
	s_andn2_b64 vcc, exec, s[6:7]
	s_cbranch_vccnz .LBB0_875
	s_mul_hi_i32 s6, s43, 0x2e8ba2e9
	s_lshr_b32 s7, s6, 31
	s_ashr_i32 s6, s6, 5
	s_add_i32 s6, s6, s7
	s_lshl_b32 s28, s6, 6
	s_mul_i32 s7, s6, 0xffffea00
	s_mulk_i32 s6, 0xf500
	s_add_i32 s47, s44, s7
	s_add_i32 s6, s45, s6
	v_or_b32_e32 v0, s47, v20
	s_and_b32 s6, s6, 0xffffff80
	v_add_u32_e32 v38, s6, v33
	s_and_b32 s6, s47, 0x60
	v_lshlrev_b32_e32 v0, 1, v0
	v_and_or_b32 v18, s43, 4, v34
	v_and_b32_e32 v0, 24, v0
	v_or_b32_e32 v18, s6, v18
	v_or3_b32 v0, v18, v0, v38
	v_or_b32_e32 v39, s28, v22
	v_mov_b64_e32 v[18:19], s[24:25]
	s_movk_i32 s6, 0x5800
	v_cmp_lt_i32_e32 vcc, -1, v38
	v_mad_i64_i32 v[18:19], s[6:7], v39, s6, v[18:19]
	s_nop 0
	v_cndmask_b32_e32 v0, 0, v0, vcc
	v_lshl_add_u64 v[18:19], v[0:1], 2, v[18:19]
	s_mov_b32 s6, 0xb000
	v_add_co_u32_e64 v38, s[6:7], s6, v18
	global_load_dword v0, v[18:19], off
	s_nop 0
	v_addc_co_u32_e64 v39, s[6:7], 0, v19, s[6:7]
	global_load_dword v40, v[38:39], off
	v_add_co_u32_e64 v38, s[6:7], s57, v18
	s_ashr_i32 s29, s28, 31
	s_nop 0
	v_addc_co_u32_e64 v39, s[6:7], 0, v19, s[6:7]
	s_mov_b32 s6, 0x21000
	global_load_dword v41, v[38:39], off
	v_add_co_u32_e64 v38, s[6:7], s6, v18
	s_waitcnt vmcnt(2)
	v_cndmask_b32_e32 v0, 0, v0, vcc
	v_addc_co_u32_e64 v39, s[6:7], 0, v19, s[6:7]
	global_load_dword v42, v[38:39], off
	v_add_co_u32_e64 v38, s[6:7], s33, v18
	s_nop 1
	v_addc_co_u32_e64 v39, s[6:7], 0, v19, s[6:7]
	s_mov_b32 s6, 0x37000
	global_load_dword v43, v[38:39], off
	v_add_co_u32_e64 v38, s[6:7], s6, v18
	s_nop 1
	v_addc_co_u32_e64 v39, s[6:7], 0, v19, s[6:7]
	s_mov_b32 s6, 0x42000
	global_load_dword v44, v[38:39], off
	v_add_co_u32_e64 v38, s[6:7], s6, v18
	s_nop 1
	v_addc_co_u32_e64 v39, s[6:7], 0, v19, s[6:7]
	s_mov_b32 s6, 0x4d000
	global_load_dword v45, v[38:39], off
	v_add_co_u32_e64 v38, s[6:7], s6, v18
	s_nop 1
	v_addc_co_u32_e64 v39, s[6:7], 0, v19, s[6:7]
	s_mov_b32 s6, 0x58000
	global_load_dword v46, v[38:39], off
	v_add_co_u32_e64 v38, s[6:7], s6, v18
	s_nop 1
	v_addc_co_u32_e64 v39, s[6:7], 0, v19, s[6:7]
	s_mov_b32 s6, 0x63000
	global_load_dword v47, v[38:39], off
	v_add_co_u32_e64 v38, s[6:7], s6, v18
	s_nop 1
	v_addc_co_u32_e64 v39, s[6:7], 0, v19, s[6:7]
	s_mov_b32 s6, 0x6e000
	global_load_dword v48, v[38:39], off
	v_add_co_u32_e64 v38, s[6:7], s6, v18
	s_nop 1
	v_addc_co_u32_e64 v39, s[6:7], 0, v19, s[6:7]
	s_mov_b32 s6, 0x79000
	global_load_dword v49, v[38:39], off
	v_add_co_u32_e64 v38, s[6:7], s6, v18
	s_nop 1
	v_addc_co_u32_e64 v39, s[6:7], 0, v19, s[6:7]
	s_mov_b32 s6, 0x84000
	global_load_dword v50, v[38:39], off
	v_add_co_u32_e64 v38, s[6:7], s6, v18
	s_nop 1
	v_addc_co_u32_e64 v39, s[6:7], 0, v19, s[6:7]
	s_mov_b32 s6, 0x8f000
	global_load_dword v51, v[38:39], off
	v_add_co_u32_e64 v38, s[6:7], s6, v18
	s_nop 1
	v_addc_co_u32_e64 v39, s[6:7], 0, v19, s[6:7]
	s_mov_b32 s6, 0x9a000
	global_load_dword v52, v[38:39], off
	v_add_co_u32_e64 v38, s[6:7], s6, v18
	s_nop 1
	v_addc_co_u32_e64 v39, s[6:7], 0, v19, s[6:7]
	s_mov_b32 s6, 0xa5000
	global_load_dword v53, v[38:39], off
	v_add_co_u32_e64 v38, s[6:7], s6, v18
	s_nop 1
	v_addc_co_u32_e64 v39, s[6:7], 0, v19, s[6:7]
	global_load_dword v54, v[38:39], off
	v_add_co_u32_e64 v38, s[6:7], s61, v18
	s_nop 1
	v_addc_co_u32_e64 v39, s[6:7], 0, v19, s[6:7]
	s_mov_b32 s6, 0xbb000
	global_load_dword v55, v[38:39], off
	v_add_co_u32_e64 v38, s[6:7], s6, v18
	s_nop 1
	v_addc_co_u32_e64 v39, s[6:7], 0, v19, s[6:7]
	s_mov_b32 s6, 0xc6000
	global_load_dword v56, v[38:39], off
	v_add_co_u32_e64 v38, s[6:7], s6, v18
	s_nop 1
	v_addc_co_u32_e64 v39, s[6:7], 0, v19, s[6:7]
	s_mov_b32 s6, 0xd1000
	global_load_dword v57, v[38:39], off
	v_add_co_u32_e64 v38, s[6:7], s6, v18
	s_nop 1
	v_addc_co_u32_e64 v39, s[6:7], 0, v19, s[6:7]
	s_mov_b32 s6, 0xdc000
	global_load_dword v58, v[38:39], off
	v_add_co_u32_e64 v38, s[6:7], s6, v18
	s_nop 1
	v_addc_co_u32_e64 v39, s[6:7], 0, v19, s[6:7]
	s_mov_b32 s6, 0xe7000
	global_load_dword v59, v[38:39], off
	v_add_co_u32_e64 v38, s[6:7], s6, v18
	s_nop 1
	v_addc_co_u32_e64 v39, s[6:7], 0, v19, s[6:7]
	s_mov_b32 s6, 0xf2000
	global_load_dword v60, v[38:39], off
	v_add_co_u32_e64 v38, s[6:7], s6, v18
	s_nop 1
	v_addc_co_u32_e64 v39, s[6:7], 0, v19, s[6:7]
	s_mov_b32 s6, 0xfd000
	global_load_dword v61, v[38:39], off
	v_add_co_u32_e64 v38, s[6:7], s6, v18
	s_nop 1
	v_addc_co_u32_e64 v39, s[6:7], 0, v19, s[6:7]
	s_mov_b32 s6, 0x108000
	global_load_dword v62, v[38:39], off
	v_add_co_u32_e64 v38, s[6:7], s6, v18
	s_nop 1
	v_addc_co_u32_e64 v39, s[6:7], 0, v19, s[6:7]
	s_mov_b32 s6, 0x113000
	global_load_dword v63, v[38:39], off
	v_add_co_u32_e64 v38, s[6:7], s6, v18
	s_nop 1
	v_addc_co_u32_e64 v39, s[6:7], 0, v19, s[6:7]
	s_mov_b32 s6, 0x11e000
	global_load_dword v64, v[38:39], off
	v_add_co_u32_e64 v38, s[6:7], s6, v18
	s_nop 1
	v_addc_co_u32_e64 v39, s[6:7], 0, v19, s[6:7]
	s_mov_b32 s6, 0x129000
	global_load_dword v65, v[38:39], off
	v_add_co_u32_e64 v38, s[6:7], s6, v18
	s_nop 1
	v_addc_co_u32_e64 v39, s[6:7], 0, v19, s[6:7]
	s_mov_b32 s6, 0x134000
	global_load_dword v66, v[38:39], off
	v_add_co_u32_e64 v38, s[6:7], s6, v18
	s_nop 1
	v_addc_co_u32_e64 v39, s[6:7], 0, v19, s[6:7]
	s_mov_b32 s6, 0x13f000
	global_load_dword v67, v[38:39], off
	v_add_co_u32_e64 v38, s[6:7], s6, v18
	s_nop 1
	v_addc_co_u32_e64 v39, s[6:7], 0, v19, s[6:7]
	s_mov_b32 s6, 0x14a000
	global_load_dword v68, v[38:39], off
	v_add_co_u32_e64 v38, s[6:7], s6, v18
	s_nop 1
	v_addc_co_u32_e64 v39, s[6:7], 0, v19, s[6:7]
	s_mov_b32 s6, 0x155000
	s_nop 0
	v_add_co_u32_e64 v18, s[6:7], s6, v18
	global_load_dword v38, v[38:39], off
	s_nop 0
	v_addc_co_u32_e64 v19, s[6:7], 0, v19, s[6:7]
	global_load_dword v18, v[18:19], off
	s_waitcnt vmcnt(30)
; __device__ __forceinline__ unsigned pk2(float lo, float hi) { unsigned r; asm("v_cvt_pk_bf16_f32 %0, %1, %2" : "=v"(r) : "v"(lo), "v"(hi)); return r; }
; template <class Map>
; __device__ __forceinline__ void transpose_item(const float* W, int K, int N, bf16_t* WT, float* scr, int item, int nblk, int lane, Map srccol) {
;     ...
;     for (int i = 0; i < 32; ++i) { const int kk = 2 * i + (lane >> 5); scr[kk * 33 + (lane & 31)] = sc >= 0 ? tv[i] : 0.f; }
;     __builtin_amdgcn_s_waitcnt(0); asm volatile("" ::: "memory");
;     const int c = lane & 7;
; #pragma unroll
;     for (int j = 0; j < 4; ++j) { const int n = (lane >> 3) + 8 * j; const float* s = scr + (8 * c) * 33 + n;
;         u32x4 o; o.x = pk2(s[0 * 33], s[1 * 33]); o.y = pk2(s[2 * 33], s[3 * 33]); o.z = pk2(s[4 * 33], s[5 * 33]); o.w = pk2(s[6 * 33], s[7 * 33]);
;         *(u32x4*)(WT + (size_t)(n0 + n) * K + k0 + 8 * c) = o; }
;     __builtin_amdgcn_s_waitcnt(0); asm volatile("" ::: "memory");
	v_cndmask_b32_e32 v19, 0, v40, vcc
	ds_write2_b32 v35, v0, v19 offset1:66
	s_waitcnt vmcnt(29)
	v_cndmask_b32_e32 v0, 0, v41, vcc
	s_waitcnt vmcnt(28)
	v_cndmask_b32_e32 v19, 0, v42, vcc
	ds_write2_b32 v35, v0, v19 offset0:132 offset1:198
	s_waitcnt vmcnt(27)
	v_cndmask_b32_e32 v0, 0, v43, vcc
	s_waitcnt vmcnt(26)
	v_cndmask_b32_e32 v19, 0, v44, vcc
	v_add_u32_e32 v39, 0x400, v35
	ds_write2_b32 v39, v0, v19 offset0:8 offset1:74
	s_waitcnt vmcnt(25)
	v_cndmask_b32_e32 v0, 0, v45, vcc
	s_waitcnt vmcnt(24)
	v_cndmask_b32_e32 v19, 0, v46, vcc
	ds_write2_b32 v39, v0, v19 offset0:140 offset1:206
	s_waitcnt vmcnt(23)
	v_cndmask_b32_e32 v0, 0, v47, vcc
	s_waitcnt vmcnt(22)
	v_cndmask_b32_e32 v19, 0, v48, vcc
	v_add_u32_e32 v39, 0x800, v35
	ds_write2_b32 v39, v0, v19 offset0:16 offset1:82
	s_waitcnt vmcnt(21)
	v_cndmask_b32_e32 v0, 0, v49, vcc
	s_waitcnt vmcnt(20)
	v_cndmask_b32_e32 v19, 0, v50, vcc
	ds_write2_b32 v39, v0, v19 offset0:148 offset1:214
	s_waitcnt vmcnt(19)
	v_cndmask_b32_e32 v0, 0, v51, vcc
	s_waitcnt vmcnt(18)
	v_cndmask_b32_e32 v19, 0, v52, vcc
	v_add_u32_e32 v39, 0xc00, v35
	ds_write2_b32 v39, v0, v19 offset0:24 offset1:90
	s_waitcnt vmcnt(17)
	v_cndmask_b32_e32 v0, 0, v53, vcc
	s_waitcnt vmcnt(16)
	v_cndmask_b32_e32 v19, 0, v54, vcc
	ds_write2_b32 v39, v0, v19 offset0:156 offset1:222
	s_waitcnt vmcnt(15)
	v_cndmask_b32_e32 v0, 0, v55, vcc
	s_waitcnt vmcnt(14)
	v_cndmask_b32_e32 v19, 0, v56, vcc
	v_add_u32_e32 v39, 0x1000, v35
	ds_write2_b32 v39, v0, v19 offset0:32 offset1:98
	s_waitcnt vmcnt(13)
	v_cndmask_b32_e32 v0, 0, v57, vcc
	s_waitcnt vmcnt(12)
	v_cndmask_b32_e32 v19, 0, v58, vcc
	ds_write2_b32 v39, v0, v19 offset0:164 offset1:230
	s_waitcnt vmcnt(11)
	v_cndmask_b32_e32 v0, 0, v59, vcc
	s_waitcnt vmcnt(10)
	v_cndmask_b32_e32 v19, 0, v60, vcc
	v_add_u32_e32 v39, 0x1400, v35
	ds_write2_b32 v39, v0, v19 offset0:40 offset1:106
	s_waitcnt vmcnt(9)
	v_cndmask_b32_e32 v0, 0, v61, vcc
	s_waitcnt vmcnt(8)
	v_cndmask_b32_e32 v19, 0, v62, vcc
	ds_write2_b32 v39, v0, v19 offset0:172 offset1:238
	s_waitcnt vmcnt(7)
	v_cndmask_b32_e32 v0, 0, v63, vcc
	s_waitcnt vmcnt(6)
	v_cndmask_b32_e32 v19, 0, v64, vcc
	v_add_u32_e32 v39, 0x1800, v35
	ds_write2_b32 v39, v0, v19 offset0:48 offset1:114
	v_add_u32_e32 v58, s47, v24
	v_ashrrev_i32_e32 v59, 31, v58
	s_waitcnt vmcnt(5)
	v_cndmask_b32_e32 v0, 0, v65, vcc
	v_lshlrev_b64 v[60:61], 11, v[58:59]
	s_waitcnt vmcnt(4)
	v_cndmask_b32_e32 v19, 0, v66, vcc
	ds_write2_b32 v39, v0, v19 offset0:180 offset1:246
	v_add_u32_e32 v39, 0x1c00, v35
	s_waitcnt vmcnt(3)
	v_cndmask_b32_e32 v0, 0, v67, vcc
	s_waitcnt vmcnt(2)
	v_cndmask_b32_e32 v19, 0, v68, vcc
	ds_write2_b32 v39, v0, v19 offset0:56 offset1:122
	s_waitcnt vmcnt(1)
	v_cndmask_b32_e32 v0, 0, v38, vcc
	s_waitcnt vmcnt(0)
	v_cndmask_b32_e32 v18, 0, v18, vcc
	ds_write2_b32 v39, v0, v18 offset0:188 offset1:254
	s_waitcnt vmcnt(0) expcnt(0) lgkmcnt(0)
	ds_read2_b32 v[42:43], v25 offset0:33 offset1:41
	ds_read2_b32 v[44:45], v25 offset1:8
	ds_read2_b32 v[46:47], v25 offset0:66 offset1:74
	ds_read2_b32 v[48:49], v25 offset0:99 offset1:107
	ds_read2_b32 v[50:51], v25 offset0:132 offset1:140
	ds_read2_b32 v[52:53], v25 offset0:165 offset1:173
	ds_read2_b32 v[54:55], v25 offset0:198 offset1:206
	ds_read2_b32 v[56:57], v25 offset0:231 offset1:239
	v_lshl_add_u64 v[18:19], s[28:29], 1, v[16:17]
	s_waitcnt lgkmcnt(6)
	v_cvt_pk_bf16_f32 v38, v44, v42
	v_lshl_add_u64 v[60:61], v[18:19], 0, v[60:61]
	v_add_u32_e32 v42, 8, v58
	s_waitcnt lgkmcnt(4)
	v_cvt_pk_bf16_f32 v39, v46, v48
	s_waitcnt lgkmcnt(2)
	v_cvt_pk_bf16_f32 v40, v50, v52
	s_waitcnt lgkmcnt(0)
	v_cvt_pk_bf16_f32 v41, v54, v56
	global_store_dwordx4 v[60:61], v[38:41], off
	v_add_u32_e32 v60, 16, v58
	v_ashrrev_i32_e32 v61, 31, v60
	v_cvt_pk_bf16_f32 v38, v45, v43
	v_ashrrev_i32_e32 v43, 31, v42
	v_lshlrev_b64 v[42:43], 11, v[42:43]
	v_lshl_add_u64 v[42:43], v[18:19], 0, v[42:43]
	v_cvt_pk_bf16_f32 v39, v47, v49
	v_cvt_pk_bf16_f32 v40, v51, v53
	v_cvt_pk_bf16_f32 v41, v55, v57
	global_store_dwordx4 v[42:43], v[38:41], off
	ds_read2_b32 v[42:43], v25 offset0:16 offset1:24
	ds_read2_b32 v[44:45], v25 offset0:49 offset1:57
	ds_read2_b32 v[46:47], v25 offset0:82 offset1:90
	ds_read2_b32 v[48:49], v25 offset0:115 offset1:123
	ds_read2_b32 v[50:51], v25 offset0:148 offset1:156
	ds_read2_b32 v[52:53], v25 offset0:181 offset1:189
	ds_read2_b32 v[54:55], v25 offset0:214 offset1:222
	ds_read2_b32 v[56:57], v25 offset0:247 offset1:255
	v_lshlrev_b64 v[60:61], 11, v[60:61]
	s_waitcnt lgkmcnt(6)
	v_cvt_pk_bf16_f32 v38, v42, v44
	v_lshl_add_u64 v[60:61], v[18:19], 0, v[60:61]
	v_add_u32_e32 v42, 24, v58
	s_waitcnt lgkmcnt(4)
	v_cvt_pk_bf16_f32 v39, v46, v48
	s_waitcnt lgkmcnt(2)
	v_cvt_pk_bf16_f32 v40, v50, v52
	s_waitcnt lgkmcnt(0)
	v_cvt_pk_bf16_f32 v41, v54, v56
	global_store_dwordx4 v[60:61], v[38:41], off
	s_nop 1
	v_cvt_pk_bf16_f32 v38, v43, v45
	v_ashrrev_i32_e32 v43, 31, v42
	v_lshlrev_b64 v[42:43], 11, v[42:43]
	v_lshl_add_u64 v[18:19], v[18:19], 0, v[42:43]
	v_cvt_pk_bf16_f32 v39, v47, v49
	v_cvt_pk_bf16_f32 v40, v51, v53
	v_cvt_pk_bf16_f32 v41, v55, v57
	global_store_dwordx4 v[18:19], v[38:41], off
	s_waitcnt lgkmcnt(0)
	s_branch .LBB0_875

; template <class Map>
; __device__ __forceinline__ void transpose_item(const float* W, int K, int N, bf16_t* WT, float* scr, int item, int nblk, int lane, Map srccol) {
;     const int kb = item / nblk, nb = item % nblk, k0 = 64 * kb, n0 = 32 * nb;
;     const int sc = srccol(n0 + (lane & 31));
;     float tv[32];
;     const float* wp = W + (size_t)(k0 + (lane >> 5)) * N + (sc >= 0 ? sc : 0);
; #pragma unroll
;     for (int i = 0; i < 32; ++i) tv[i] = wp[(size_t)(2 * i) * N];
; __device__ __forceinline__ void mat_item(const P& p, float* scr, int mat, int r, int lane) {
;     if (mat < 4) transpose_item(p.w_up + (size_t)mat * DM * 2 * DFF, DM, 2 * DFF, (bf16_t*)(p.ws + WS_WUP) + (size_t)mat * 2 * DFF * DM, scr, r, 176, lane, MapUp());
;     else if (mat < 8) transpose_item(p.w_dn + (size_t)(mat - 4) * DFF * DM, DFF, DM, (bf16_t*)(p.ws + WS_WDN) + (size_t)(mat - 4) * DM * DFF, scr, r, 32, lane, MapPerm8());
;     else if (mat == 8) transpose_item(p.e_in, DM, 3600, (bf16_t*)(p.ws + WS_WEIN), scr, r, 120, lane, MapEin());
;     else if (mat == 9) transpose_item(p.e_out, DM, DM, (bf16_t*)(p.ws + WS_WEOUT), scr, r, 32, lane, MapPerm8());
;     else if (mat == 10) transpose_item(p.o_in, DM, 1536, (bf16_t*)(p.ws + WS_WOIN), scr, r, 48, lane, MapId());
;     else transpose_item(p.o_out, DM, DM, (bf16_t*)(p.ws + WS_WOOUT), scr, r, 32, lane, MapPerm8());
; }
.LBB0_907:
	s_mov_b64 s[6:7], -1
	s_and_b64 vcc, exec, s[8:9]
	s_cbranch_vccz .LBB0_927
	s_and_b64 vcc, exec, s[2:3]
	s_cbranch_vccz .LBB0_924
	s_cmp_lt_i32 s35, 9
	s_cbranch_scc1 .LBB0_919
	s_cmp_lt_i32 s35, 10
	s_cbranch_scc1 .LBB0_916
	s_cmp_lg_u32 s35, 10
	s_cbranch_scc0 .LBB0_913
	s_ashr_i32 s6, s41, 31
	s_lshr_b32 s6, s6, 27
	s_add_i32 s6, s41, s6
	s_ashr_i32 s7, s6, 5
	s_lshl_b32 s26, s7, 6
	s_lshl_b32 s7, s7, 10
	s_sub_i32 s47, s42, s7
	v_add_u32_e32 v0, s47, v21
	s_andn2_b32 s6, s6, 31
	v_and_b32_e32 v18, 24, v37
	v_and_b32_e32 v0, 0xffffffe3, v0
	s_sub_i32 s6, s41, s6
	v_or3_b32 v0, v0, v18, v29
	v_or_b32_e32 v18, s26, v22
	v_ashrrev_i32_e32 v19, 31, v18
	s_cmp_gt_i32 s6, -1
	v_lshlrev_b64 v[18:19], 12, v[18:19]
	s_cselect_b64 vcc, -1, 0
	v_lshl_add_u64 v[18:19], s[22:23], 0, v[18:19]
	v_cndmask_b32_e32 v0, 0, v0, vcc
	v_lshl_add_u64 v[18:19], v[0:1], 2, v[18:19]
	v_add_co_u32_e64 v38, s[6:7], s63, v18
	global_load_dword v0, v[18:19], off
	s_nop 0
	v_addc_co_u32_e64 v39, s[6:7], 0, v19, s[6:7]
	global_load_dword v40, v[38:39], off
	v_add_co_u32_e64 v38, s[6:7], s96, v18
	s_ashr_i32 s27, s26, 31
	s_nop 0
	v_addc_co_u32_e64 v39, s[6:7], 0, v19, s[6:7]
	global_load_dword v41, v[38:39], off
	v_add_co_u32_e64 v38, s[6:7], s58, v18
	s_waitcnt vmcnt(2)
	v_cndmask_b32_e32 v0, 0, v0, vcc
	v_addc_co_u32_e64 v39, s[6:7], 0, v19, s[6:7]
	global_load_dword v42, v[38:39], off
	v_add_co_u32_e64 v38, s[6:7], s60, v18
	s_nop 1
	v_addc_co_u32_e64 v39, s[6:7], 0, v19, s[6:7]
	global_load_dword v43, v[38:39], off
	v_add_co_u32_e64 v38, s[6:7], s54, v18
	s_nop 1
	v_addc_co_u32_e64 v39, s[6:7], 0, v19, s[6:7]
	global_load_dword v44, v[38:39], off
	v_add_co_u32_e64 v38, s[6:7], s71, v18
	s_nop 1
	v_addc_co_u32_e64 v39, s[6:7], 0, v19, s[6:7]
	global_load_dword v45, v[38:39], off
	v_add_co_u32_e64 v38, s[6:7], s72, v18
	s_nop 1
	v_addc_co_u32_e64 v39, s[6:7], 0, v19, s[6:7]
	global_load_dword v46, v[38:39], off
	v_add_co_u32_e64 v38, s[6:7], s50, v18
	s_nop 1
	v_addc_co_u32_e64 v39, s[6:7], 0, v19, s[6:7]
	global_load_dword v47, v[38:39], off
	v_add_co_u32_e64 v38, s[6:7], s55, v18
	s_nop 1
	v_addc_co_u32_e64 v39, s[6:7], 0, v19, s[6:7]
	global_load_dword v48, v[38:39], off
	v_add_co_u32_e64 v38, s[6:7], s56, v18
	s_nop 1
	v_addc_co_u32_e64 v39, s[6:7], 0, v19, s[6:7]
	global_load_dword v49, v[38:39], off
	v_add_co_u32_e64 v38, s[6:7], s57, v18
	s_nop 1
	v_addc_co_u32_e64 v39, s[6:7], 0, v19, s[6:7]
	global_load_dword v50, v[38:39], off
	v_add_co_u32_e64 v38, s[6:7], s59, v18
	s_nop 1
	v_addc_co_u32_e64 v39, s[6:7], 0, v19, s[6:7]
	global_load_dword v51, v[38:39], off
	v_add_co_u32_e64 v38, s[6:7], s52, v18
	s_nop 1
	v_addc_co_u32_e64 v39, s[6:7], 0, v19, s[6:7]
	global_load_dword v52, v[38:39], off
	v_add_co_u32_e64 v38, s[6:7], s62, v18
	s_nop 1
	v_addc_co_u32_e64 v39, s[6:7], 0, v19, s[6:7]
	global_load_dword v53, v[38:39], off
	v_add_co_u32_e64 v38, s[6:7], s64, v18
	s_nop 1
	v_addc_co_u32_e64 v39, s[6:7], 0, v19, s[6:7]
	global_load_dword v54, v[38:39], off
	v_add_co_u32_e64 v38, s[6:7], s73, v18
	s_nop 1
	v_addc_co_u32_e64 v39, s[6:7], 0, v19, s[6:7]
	global_load_dword v55, v[38:39], off
	v_add_co_u32_e64 v38, s[6:7], s74, v18
	s_nop 1
	v_addc_co_u32_e64 v39, s[6:7], 0, v19, s[6:7]
	global_load_dword v56, v[38:39], off
	v_add_co_u32_e64 v38, s[6:7], s75, v18
	s_nop 1
	v_addc_co_u32_e64 v39, s[6:7], 0, v19, s[6:7]
	global_load_dword v57, v[38:39], off
	v_add_co_u32_e64 v38, s[6:7], s1, v18
	s_nop 1
	v_addc_co_u32_e64 v39, s[6:7], 0, v19, s[6:7]
	global_load_dword v58, v[38:39], off
	v_add_co_u32_e64 v38, s[6:7], s76, v18
	s_nop 1
	v_addc_co_u32_e64 v39, s[6:7], 0, v19, s[6:7]
	global_load_dword v59, v[38:39], off
	v_add_co_u32_e64 v38, s[6:7], s77, v18
	s_nop 1
	v_addc_co_u32_e64 v39, s[6:7], 0, v19, s[6:7]
	global_load_dword v60, v[38:39], off
	v_add_co_u32_e64 v38, s[6:7], s33, v18
	s_nop 1
	v_addc_co_u32_e64 v39, s[6:7], 0, v19, s[6:7]
	global_load_dword v61, v[38:39], off
	v_add_co_u32_e64 v38, s[6:7], s80, v18
	s_nop 1
	v_addc_co_u32_e64 v39, s[6:7], 0, v19, s[6:7]
	global_load_dword v62, v[38:39], off
	v_add_co_u32_e64 v38, s[6:7], s0, v18
	s_nop 1
	v_addc_co_u32_e64 v39, s[6:7], 0, v19, s[6:7]
	global_load_dword v63, v[38:39], off
	v_add_co_u32_e64 v38, s[6:7], s81, v18
	s_nop 1
	v_addc_co_u32_e64 v39, s[6:7], 0, v19, s[6:7]
	global_load_dword v64, v[38:39], off
	v_add_co_u32_e64 v38, s[6:7], s82, v18
	s_nop 1
	v_addc_co_u32_e64 v39, s[6:7], 0, v19, s[6:7]
	global_load_dword v65, v[38:39], off
	v_add_co_u32_e64 v38, s[6:7], s83, v18
	s_nop 1
	v_addc_co_u32_e64 v39, s[6:7], 0, v19, s[6:7]
	global_load_dword v66, v[38:39], off
	v_add_co_u32_e64 v38, s[6:7], s84, v18
	s_nop 1
	v_addc_co_u32_e64 v39, s[6:7], 0, v19, s[6:7]
	global_load_dword v67, v[38:39], off
	v_add_co_u32_e64 v38, s[6:7], s85, v18
	s_nop 1
	v_addc_co_u32_e64 v39, s[6:7], 0, v19, s[6:7]
	global_load_dword v68, v[38:39], off
	v_add_co_u32_e64 v38, s[6:7], s86, v18
	s_nop 1
	v_addc_co_u32_e64 v39, s[6:7], 0, v19, s[6:7]
	v_add_co_u32_e64 v18, s[6:7], s87, v18
	global_load_dword v38, v[38:39], off
	s_nop 0
	v_addc_co_u32_e64 v19, s[6:7], 0, v19, s[6:7]
	global_load_dword v18, v[18:19], off
	s_waitcnt vmcnt(30)
	v_cndmask_b32_e32 v19, 0, v40, vcc
	ds_write2_b32 v23, v0, v19 offset1:66
	s_waitcnt vmcnt(29)
	v_cndmask_b32_e32 v0, 0, v41, vcc
	s_waitcnt vmcnt(28)
	v_cndmask_b32_e32 v19, 0, v42, vcc
	ds_write2_b32 v23, v0, v19 offset0:132 offset1:198
	s_waitcnt vmcnt(27)
	v_cndmask_b32_e32 v0, 0, v43, vcc
	s_waitcnt vmcnt(26)
	v_cndmask_b32_e32 v19, 0, v44, vcc
	v_add_u32_e32 v39, 0x400, v23
	ds_write2_b32 v39, v0, v19 offset0:8 offset1:74
	s_waitcnt vmcnt(25)
; __device__ __forceinline__ unsigned pk2(float lo, float hi) { unsigned r; asm("v_cvt_pk_bf16_f32 %0, %1, %2" : "=v"(r) : "v"(lo), "v"(hi)); return r; }
; template <class Map>
; __device__ __forceinline__ void transpose_item(const float* W, int K, int N, bf16_t* WT, float* scr, int item, int nblk, int lane, Map srccol) {
;     ...
; #pragma unroll
;     for (int i = 0; i < 32; ++i) { const int kk = 2 * i + (lane >> 5); scr[kk * 33 + (lane & 31)] = sc >= 0 ? tv[i] : 0.f; }
;     __builtin_amdgcn_s_waitcnt(0); asm volatile("" ::: "memory");
;     const int c = lane & 7;
; #pragma unroll
;     for (int j = 0; j < 4; ++j) { const int n = (lane >> 3) + 8 * j; const float* s = scr + (8 * c) * 33 + n;
;         u32x4 o; o.x = pk2(s[0 * 33], s[1 * 33]); o.y = pk2(s[2 * 33], s[3 * 33]); o.z = pk2(s[4 * 33], s[5 * 33]); o.w = pk2(s[6 * 33], s[7 * 33]);
;         *(u32x4*)(WT + (size_t)(n0 + n) * K + k0 + 8 * c) = o; }
;     __builtin_amdgcn_s_waitcnt(0); asm volatile("" ::: "memory");
	v_cndmask_b32_e32 v0, 0, v45, vcc
	s_waitcnt vmcnt(24)
	v_cndmask_b32_e32 v19, 0, v46, vcc
	ds_write2_b32 v39, v0, v19 offset0:140 offset1:206
	s_waitcnt vmcnt(23)
	v_cndmask_b32_e32 v0, 0, v47, vcc
	s_waitcnt vmcnt(22)
	v_cndmask_b32_e32 v19, 0, v48, vcc
	v_add_u32_e32 v39, 0x800, v23
	ds_write2_b32 v39, v0, v19 offset0:16 offset1:82
	s_waitcnt vmcnt(21)
	v_cndmask_b32_e32 v0, 0, v49, vcc
	s_waitcnt vmcnt(20)
	v_cndmask_b32_e32 v19, 0, v50, vcc
	ds_write2_b32 v39, v0, v19 offset0:148 offset1:214
	s_waitcnt vmcnt(19)
	v_cndmask_b32_e32 v0, 0, v51, vcc
	s_waitcnt vmcnt(18)
	v_cndmask_b32_e32 v19, 0, v52, vcc
	v_add_u32_e32 v39, 0xc00, v23
	ds_write2_b32 v39, v0, v19 offset0:24 offset1:90
	s_waitcnt vmcnt(17)
	v_cndmask_b32_e32 v0, 0, v53, vcc
	s_waitcnt vmcnt(16)
	v_cndmask_b32_e32 v19, 0, v54, vcc
	ds_write2_b32 v39, v0, v19 offset0:156 offset1:222
	s_waitcnt vmcnt(15)
	v_cndmask_b32_e32 v0, 0, v55, vcc
	s_waitcnt vmcnt(14)
	v_cndmask_b32_e32 v19, 0, v56, vcc
	v_add_u32_e32 v39, 0x1000, v23
	ds_write2_b32 v39, v0, v19 offset0:32 offset1:98
	s_waitcnt vmcnt(13)
	v_cndmask_b32_e32 v0, 0, v57, vcc
	s_waitcnt vmcnt(12)
	v_cndmask_b32_e32 v19, 0, v58, vcc
	ds_write2_b32 v39, v0, v19 offset0:164 offset1:230
	s_waitcnt vmcnt(11)
	v_cndmask_b32_e32 v0, 0, v59, vcc
	s_waitcnt vmcnt(10)
	v_cndmask_b32_e32 v19, 0, v60, vcc
	v_add_u32_e32 v39, 0x1400, v23
	ds_write2_b32 v39, v0, v19 offset0:40 offset1:106
	s_waitcnt vmcnt(9)
	v_cndmask_b32_e32 v0, 0, v61, vcc
	s_waitcnt vmcnt(8)
	v_cndmask_b32_e32 v19, 0, v62, vcc
	ds_write2_b32 v39, v0, v19 offset0:172 offset1:238
	s_waitcnt vmcnt(7)
	v_cndmask_b32_e32 v0, 0, v63, vcc
	v_add_u32_e32 v39, 0x1800, v23
	v_add_u32_e32 v58, s47, v24
	v_ashrrev_i32_e32 v59, 31, v58
	s_waitcnt vmcnt(6)
	v_cndmask_b32_e32 v19, 0, v64, vcc
	ds_write2_b32 v39, v0, v19 offset0:48 offset1:114
	v_lshlrev_b64 v[60:61], 11, v[58:59]
	s_mov_b64 s[6:7], 0
	s_waitcnt vmcnt(5)
	v_cndmask_b32_e32 v0, 0, v65, vcc
	s_waitcnt vmcnt(4)
	v_cndmask_b32_e32 v19, 0, v66, vcc
	ds_write2_b32 v39, v0, v19 offset0:180 offset1:246
	v_add_u32_e32 v39, 0x1c00, v23
	s_waitcnt vmcnt(3)
	v_cndmask_b32_e32 v0, 0, v67, vcc
	s_waitcnt vmcnt(2)
	v_cndmask_b32_e32 v19, 0, v68, vcc
	ds_write2_b32 v39, v0, v19 offset0:56 offset1:122
	s_waitcnt vmcnt(1)
	v_cndmask_b32_e32 v0, 0, v38, vcc
	s_waitcnt vmcnt(0)
	v_cndmask_b32_e32 v18, 0, v18, vcc
	ds_write2_b32 v39, v0, v18 offset0:188 offset1:254
	s_waitcnt vmcnt(0) expcnt(0) lgkmcnt(0)
	ds_read2_b32 v[42:43], v25 offset0:33 offset1:41
	ds_read2_b32 v[44:45], v25 offset1:8
	ds_read2_b32 v[46:47], v25 offset0:66 offset1:74
	ds_read2_b32 v[48:49], v25 offset0:99 offset1:107
	ds_read2_b32 v[50:51], v25 offset0:132 offset1:140
	ds_read2_b32 v[52:53], v25 offset0:165 offset1:173
	ds_read2_b32 v[54:55], v25 offset0:198 offset1:206
	ds_read2_b32 v[56:57], v25 offset0:231 offset1:239
	v_lshl_add_u64 v[18:19], s[26:27], 1, v[8:9]
	s_waitcnt lgkmcnt(6)
	v_cvt_pk_bf16_f32 v38, v44, v42
	v_lshl_add_u64 v[60:61], v[18:19], 0, v[60:61]
	v_add_u32_e32 v42, 8, v58
	s_waitcnt lgkmcnt(4)
	v_cvt_pk_bf16_f32 v39, v46, v48
	s_waitcnt lgkmcnt(2)
	v_cvt_pk_bf16_f32 v40, v50, v52
	s_waitcnt lgkmcnt(0)
	v_cvt_pk_bf16_f32 v41, v54, v56
	global_store_dwordx4 v[60:61], v[38:41], off
	v_add_u32_e32 v60, 16, v58
	v_ashrrev_i32_e32 v61, 31, v60
	v_cvt_pk_bf16_f32 v38, v45, v43
	v_ashrrev_i32_e32 v43, 31, v42
	v_lshlrev_b64 v[42:43], 11, v[42:43]
	v_lshl_add_u64 v[42:43], v[18:19], 0, v[42:43]
	v_cvt_pk_bf16_f32 v39, v47, v49
	v_cvt_pk_bf16_f32 v40, v51, v53
	v_cvt_pk_bf16_f32 v41, v55, v57
	global_store_dwordx4 v[42:43], v[38:41], off
	ds_read2_b32 v[42:43], v25 offset0:16 offset1:24
	ds_read2_b32 v[44:45], v25 offset0:49 offset1:57
	ds_read2_b32 v[46:47], v25 offset0:82 offset1:90
	ds_read2_b32 v[48:49], v25 offset0:115 offset1:123
	ds_read2_b32 v[50:51], v25 offset0:148 offset1:156
	ds_read2_b32 v[52:53], v25 offset0:181 offset1:189
	ds_read2_b32 v[54:55], v25 offset0:214 offset1:222
	ds_read2_b32 v[56:57], v25 offset0:247 offset1:255
	v_lshlrev_b64 v[60:61], 11, v[60:61]
	s_waitcnt lgkmcnt(6)
	v_cvt_pk_bf16_f32 v38, v42, v44
	v_lshl_add_u64 v[60:61], v[18:19], 0, v[60:61]
	v_add_u32_e32 v42, 24, v58
	s_waitcnt lgkmcnt(4)
	v_cvt_pk_bf16_f32 v39, v46, v48
	s_waitcnt lgkmcnt(2)
	v_cvt_pk_bf16_f32 v40, v50, v52
	s_waitcnt lgkmcnt(0)
	v_cvt_pk_bf16_f32 v41, v54, v56
	global_store_dwordx4 v[60:61], v[38:41], off
	s_nop 1
	v_cvt_pk_bf16_f32 v38, v43, v45
	v_ashrrev_i32_e32 v43, 31, v42
	v_lshlrev_b64 v[42:43], 11, v[42:43]
	v_lshl_add_u64 v[18:19], v[18:19], 0, v[42:43]
	v_cvt_pk_bf16_f32 v39, v47, v49
	v_cvt_pk_bf16_f32 v40, v51, v53
	v_cvt_pk_bf16_f32 v41, v55, v57
	global_store_dwordx4 v[18:19], v[38:41], off
	s_waitcnt lgkmcnt(0)
; template <class Map>
; __device__ __forceinline__ void transpose_item(const float* W, int K, int N, bf16_t* WT, float* scr, int item, int nblk, int lane, Map srccol) {
;     const int kb = item / nblk, nb = item % nblk, k0 = 64 * kb, n0 = 32 * nb;
;     const int sc = srccol(n0 + (lane & 31));
;     float tv[32];
;     const float* wp = W + (size_t)(k0 + (lane >> 5)) * N + (sc >= 0 ? sc : 0);
; #pragma unroll
;     for (int i = 0; i < 32; ++i) tv[i] = wp[(size_t)(2 * i) * N];
.LBB0_913:
	s_andn2_b64 vcc, exec, s[6:7]
	s_cbranch_vccnz .LBB0_915
	s_mul_hi_i32 s6, s41, 0x2aaaaaab
	s_lshr_b32 s7, s6, 31
	s_ashr_i32 s6, s6, 3
	s_add_i32 s6, s6, s7
	s_mul_i32 s7, s6, 0xffffffd0
	s_mul_i32 s47, s6, 0xfffffa00
	s_add_i32 s27, s41, s7
	s_lshl_b32 s26, s6, 6
	s_add_i32 s47, s47, s42
	s_cmp_gt_i32 s27, -1
	v_add_u32_e32 v0, s47, v21
	v_or_b32_e32 v38, s26, v22
	v_mov_b64_e32 v[18:19], s[20:21]
	s_movk_i32 s6, 0x1800
	s_cselect_b64 vcc, -1, 0
	v_mad_i64_i32 v[18:19], s[6:7], v38, s6, v[18:19]
	v_cndmask_b32_e32 v0, 0, v0, vcc
	v_lshl_add_u64 v[18:19], v[0:1], 2, v[18:19]
	s_movk_i32 s6, 0x3000
	v_add_co_u32_e64 v38, s[6:7], s6, v18
	global_load_dword v0, v[18:19], off
	s_nop 0
	v_addc_co_u32_e64 v39, s[6:7], 0, v19, s[6:7]
	global_load_dword v40, v[38:39], off
	v_add_co_u32_e64 v38, s[6:7], s58, v18
	s_ashr_i32 s27, s26, 31
	s_nop 0
	v_addc_co_u32_e64 v39, s[6:7], 0, v19, s[6:7]
	s_mov_b32 s6, 0x9000
	global_load_dword v41, v[38:39], off
	v_add_co_u32_e64 v38, s[6:7], s6, v18
	s_waitcnt vmcnt(2)
	v_cndmask_b32_e32 v0, 0, v0, vcc
	v_addc_co_u32_e64 v39, s[6:7], 0, v19, s[6:7]
	global_load_dword v42, v[38:39], off
	v_add_co_u32_e64 v38, s[6:7], s71, v18
	s_nop 1
	v_addc_co_u32_e64 v39, s[6:7], 0, v19, s[6:7]
	s_mov_b32 s6, 0xf000
	global_load_dword v43, v[38:39], off
	v_add_co_u32_e64 v38, s[6:7], s6, v18
	s_nop 1
	v_addc_co_u32_e64 v39, s[6:7], 0, v19, s[6:7]
	global_load_dword v44, v[38:39], off
	v_add_co_u32_e64 v38, s[6:7], s55, v18
	s_nop 1
	v_addc_co_u32_e64 v39, s[6:7], 0, v19, s[6:7]
	s_mov_b32 s6, 0x15000
	global_load_dword v45, v[38:39], off
	v_add_co_u32_e64 v38, s[6:7], s6, v18
	s_nop 1
	v_addc_co_u32_e64 v39, s[6:7], 0, v19, s[6:7]
	global_load_dword v46, v[38:39], off
	v_add_co_u32_e64 v38, s[6:7], s59, v18
	s_nop 1
	v_addc_co_u32_e64 v39, s[6:7], 0, v19, s[6:7]
	s_mov_b32 s6, 0x1b000
	global_load_dword v47, v[38:39], off
	v_add_co_u32_e64 v38, s[6:7], s6, v18
	s_nop 1
	v_addc_co_u32_e64 v39, s[6:7], 0, v19, s[6:7]
	global_load_dword v48, v[38:39], off
	v_add_co_u32_e64 v38, s[6:7], s64, v18
	s_nop 1
	v_addc_co_u32_e64 v39, s[6:7], 0, v19, s[6:7]
	s_mov_b32 s6, 0x21000
	global_load_dword v49, v[38:39], off
	v_add_co_u32_e64 v38, s[6:7], s6, v18
	s_nop 1
	v_addc_co_u32_e64 v39, s[6:7], 0, v19, s[6:7]
	global_load_dword v50, v[38:39], off
	v_add_co_u32_e64 v38, s[6:7], s75, v18
	s_nop 1
	v_addc_co_u32_e64 v39, s[6:7], 0, v19, s[6:7]
	s_mov_b32 s6, 0x27000
	global_load_dword v51, v[38:39], off
	v_add_co_u32_e64 v38, s[6:7], s6, v18
	s_nop 1
	v_addc_co_u32_e64 v39, s[6:7], 0, v19, s[6:7]
	global_load_dword v52, v[38:39], off
	v_add_co_u32_e64 v38, s[6:7], s77, v18
	s_nop 1
	v_addc_co_u32_e64 v39, s[6:7], 0, v19, s[6:7]
	s_mov_b32 s6, 0x2d000
	global_load_dword v53, v[38:39], off
	v_add_co_u32_e64 v38, s[6:7], s6, v18
	s_nop 1
	v_addc_co_u32_e64 v39, s[6:7], 0, v19, s[6:7]
	global_load_dword v54, v[38:39], off
	v_add_co_u32_e64 v38, s[6:7], s0, v18
	s_nop 1
	v_addc_co_u32_e64 v39, s[6:7], 0, v19, s[6:7]
	s_mov_b32 s6, 0x33000
	global_load_dword v55, v[38:39], off
	v_add_co_u32_e64 v38, s[6:7], s6, v18
	s_nop 1
	v_addc_co_u32_e64 v39, s[6:7], 0, v19, s[6:7]
	global_load_dword v56, v[38:39], off
	v_add_co_u32_e64 v38, s[6:7], s83, v18
	s_nop 1
	v_addc_co_u32_e64 v39, s[6:7], 0, v19, s[6:7]
	s_mov_b32 s6, 0x39000
	global_load_dword v57, v[38:39], off
	v_add_co_u32_e64 v38, s[6:7], s6, v18
	s_nop 1
	v_addc_co_u32_e64 v39, s[6:7], 0, v19, s[6:7]
	global_load_dword v58, v[38:39], off
	v_add_co_u32_e64 v38, s[6:7], s86, v18
	s_nop 1
	v_addc_co_u32_e64 v39, s[6:7], 0, v19, s[6:7]
	s_mov_b32 s6, 0x3f000
	global_load_dword v59, v[38:39], off
	v_add_co_u32_e64 v38, s[6:7], s6, v18
	s_nop 1
	v_addc_co_u32_e64 v39, s[6:7], 0, v19, s[6:7]
	s_mov_b32 s6, 0x42000
	global_load_dword v60, v[38:39], off
	v_add_co_u32_e64 v38, s[6:7], s6, v18
	s_nop 1
	v_addc_co_u32_e64 v39, s[6:7], 0, v19, s[6:7]
	s_mov_b32 s6, 0x45000
	global_load_dword v61, v[38:39], off
	v_add_co_u32_e64 v38, s[6:7], s6, v18
	s_nop 1
	v_addc_co_u32_e64 v39, s[6:7], 0, v19, s[6:7]
	s_mov_b32 s6, 0x48000
	global_load_dword v62, v[38:39], off
	v_add_co_u32_e64 v38, s[6:7], s6, v18
	s_nop 1
	v_addc_co_u32_e64 v39, s[6:7], 0, v19, s[6:7]
	s_mov_b32 s6, 0x4b000
	global_load_dword v63, v[38:39], off
	v_add_co_u32_e64 v38, s[6:7], s6, v18
	s_nop 1
	v_addc_co_u32_e64 v39, s[6:7], 0, v19, s[6:7]
	s_mov_b32 s6, 0x4e000
	global_load_dword v64, v[38:39], off
	v_add_co_u32_e64 v38, s[6:7], s6, v18
	s_nop 1
	v_addc_co_u32_e64 v39, s[6:7], 0, v19, s[6:7]
	s_mov_b32 s6, 0x51000
	global_load_dword v65, v[38:39], off
	v_add_co_u32_e64 v38, s[6:7], s6, v18
	s_nop 1
	v_addc_co_u32_e64 v39, s[6:7], 0, v19, s[6:7]
	s_mov_b32 s6, 0x54000
	global_load_dword v66, v[38:39], off
	v_add_co_u32_e64 v38, s[6:7], s6, v18
	s_nop 1
	v_addc_co_u32_e64 v39, s[6:7], 0, v19, s[6:7]
	s_mov_b32 s6, 0x57000
	global_load_dword v67, v[38:39], off
	v_add_co_u32_e64 v38, s[6:7], s6, v18
	s_nop 1
	v_addc_co_u32_e64 v39, s[6:7], 0, v19, s[6:7]
	s_mov_b32 s6, 0x5a000
	global_load_dword v68, v[38:39], off
	v_add_co_u32_e64 v38, s[6:7], s6, v18
	s_nop 1
	v_addc_co_u32_e64 v39, s[6:7], 0, v19, s[6:7]
	s_mov_b32 s6, 0x5d000
	s_nop 0
	v_add_co_u32_e64 v18, s[6:7], s6, v18
	global_load_dword v38, v[38:39], off
	s_nop 0
	v_addc_co_u32_e64 v19, s[6:7], 0, v19, s[6:7]
	global_load_dword v18, v[18:19], off
	s_waitcnt vmcnt(30)
; __device__ __forceinline__ unsigned pk2(float lo, float hi) { unsigned r; asm("v_cvt_pk_bf16_f32 %0, %1, %2" : "=v"(r) : "v"(lo), "v"(hi)); return r; }
; template <class Map>
; __device__ __forceinline__ void transpose_item(const float* W, int K, int N, bf16_t* WT, float* scr, int item, int nblk, int lane, Map srccol) {
;     ...
; #pragma unroll
;     for (int i = 0; i < 32; ++i) { const int kk = 2 * i + (lane >> 5); scr[kk * 33 + (lane & 31)] = sc >= 0 ? tv[i] : 0.f; }
;     __builtin_amdgcn_s_waitcnt(0); asm volatile("" ::: "memory");
;     const int c = lane & 7;
; #pragma unroll
;     for (int j = 0; j < 4; ++j) { const int n = (lane >> 3) + 8 * j; const float* s = scr + (8 * c) * 33 + n;
;         u32x4 o; o.x = pk2(s[0 * 33], s[1 * 33]); o.y = pk2(s[2 * 33], s[3 * 33]); o.z = pk2(s[4 * 33], s[5 * 33]); o.w = pk2(s[6 * 33], s[7 * 33]);
;         *(u32x4*)(WT + (size_t)(n0 + n) * K + k0 + 8 * c) = o; }
;     __builtin_amdgcn_s_waitcnt(0); asm volatile("" ::: "memory");
	v_cndmask_b32_e32 v19, 0, v40, vcc
	ds_write2_b32 v23, v0, v19 offset1:66
	s_waitcnt vmcnt(29)
	v_cndmask_b32_e32 v0, 0, v41, vcc
	s_waitcnt vmcnt(28)
	v_cndmask_b32_e32 v19, 0, v42, vcc
	ds_write2_b32 v23, v0, v19 offset0:132 offset1:198
	s_waitcnt vmcnt(27)
	v_cndmask_b32_e32 v0, 0, v43, vcc
	s_waitcnt vmcnt(26)
	v_cndmask_b32_e32 v19, 0, v44, vcc
	v_add_u32_e32 v39, 0x400, v23
	ds_write2_b32 v39, v0, v19 offset0:8 offset1:74
	s_waitcnt vmcnt(25)
	v_cndmask_b32_e32 v0, 0, v45, vcc
	s_waitcnt vmcnt(24)
	v_cndmask_b32_e32 v19, 0, v46, vcc
	ds_write2_b32 v39, v0, v19 offset0:140 offset1:206
	s_waitcnt vmcnt(23)
	v_cndmask_b32_e32 v0, 0, v47, vcc
	s_waitcnt vmcnt(22)
	v_cndmask_b32_e32 v19, 0, v48, vcc
	v_add_u32_e32 v39, 0x800, v23
	ds_write2_b32 v39, v0, v19 offset0:16 offset1:82
	s_waitcnt vmcnt(21)
	v_cndmask_b32_e32 v0, 0, v49, vcc
	s_waitcnt vmcnt(20)
	v_cndmask_b32_e32 v19, 0, v50, vcc
	ds_write2_b32 v39, v0, v19 offset0:148 offset1:214
	s_waitcnt vmcnt(19)
	v_cndmask_b32_e32 v0, 0, v51, vcc
	s_waitcnt vmcnt(18)
	v_cndmask_b32_e32 v19, 0, v52, vcc
	v_add_u32_e32 v39, 0xc00, v23
	ds_write2_b32 v39, v0, v19 offset0:24 offset1:90
	s_waitcnt vmcnt(17)
	v_cndmask_b32_e32 v0, 0, v53, vcc
	s_waitcnt vmcnt(16)
	v_cndmask_b32_e32 v19, 0, v54, vcc
	ds_write2_b32 v39, v0, v19 offset0:156 offset1:222
	s_waitcnt vmcnt(15)
	v_cndmask_b32_e32 v0, 0, v55, vcc
	s_waitcnt vmcnt(14)
	v_cndmask_b32_e32 v19, 0, v56, vcc
	v_add_u32_e32 v39, 0x1000, v23
	ds_write2_b32 v39, v0, v19 offset0:32 offset1:98
	s_waitcnt vmcnt(13)
	v_cndmask_b32_e32 v0, 0, v57, vcc
	s_waitcnt vmcnt(12)
	v_cndmask_b32_e32 v19, 0, v58, vcc
	ds_write2_b32 v39, v0, v19 offset0:164 offset1:230
	s_waitcnt vmcnt(11)
	v_cndmask_b32_e32 v0, 0, v59, vcc
	s_waitcnt vmcnt(10)
	v_cndmask_b32_e32 v19, 0, v60, vcc
	v_add_u32_e32 v39, 0x1400, v23
	ds_write2_b32 v39, v0, v19 offset0:40 offset1:106
	s_waitcnt vmcnt(9)
	v_cndmask_b32_e32 v0, 0, v61, vcc
	s_waitcnt vmcnt(8)
	v_cndmask_b32_e32 v19, 0, v62, vcc
	ds_write2_b32 v39, v0, v19 offset0:172 offset1:238
	s_waitcnt vmcnt(7)
	v_cndmask_b32_e32 v0, 0, v63, vcc
	s_waitcnt vmcnt(6)
	v_cndmask_b32_e32 v19, 0, v64, vcc
	v_add_u32_e32 v39, 0x1800, v23
	ds_write2_b32 v39, v0, v19 offset0:48 offset1:114
	v_add_u32_e32 v58, s47, v24
	v_ashrrev_i32_e32 v59, 31, v58
	s_waitcnt vmcnt(5)
	v_cndmask_b32_e32 v0, 0, v65, vcc
	v_lshlrev_b64 v[60:61], 11, v[58:59]
	s_waitcnt vmcnt(4)
	v_cndmask_b32_e32 v19, 0, v66, vcc
	ds_write2_b32 v39, v0, v19 offset0:180 offset1:246
	v_add_u32_e32 v39, 0x1c00, v23
	s_waitcnt vmcnt(3)
	v_cndmask_b32_e32 v0, 0, v67, vcc
	s_waitcnt vmcnt(2)
	v_cndmask_b32_e32 v19, 0, v68, vcc
	ds_write2_b32 v39, v0, v19 offset0:56 offset1:122
	s_waitcnt vmcnt(1)
	v_cndmask_b32_e32 v0, 0, v38, vcc
	s_waitcnt vmcnt(0)
	v_cndmask_b32_e32 v18, 0, v18, vcc
	ds_write2_b32 v39, v0, v18 offset0:188 offset1:254
	s_waitcnt vmcnt(0) expcnt(0) lgkmcnt(0)
	ds_read2_b32 v[42:43], v25 offset0:33 offset1:41
	ds_read2_b32 v[44:45], v25 offset1:8
	ds_read2_b32 v[46:47], v25 offset0:66 offset1:74
	ds_read2_b32 v[48:49], v25 offset0:99 offset1:107
	ds_read2_b32 v[50:51], v25 offset0:132 offset1:140
	ds_read2_b32 v[52:53], v25 offset0:165 offset1:173
	ds_read2_b32 v[54:55], v25 offset0:198 offset1:206
	ds_read2_b32 v[56:57], v25 offset0:231 offset1:239
	v_lshl_add_u64 v[18:19], s[26:27], 1, v[2:3]
	s_waitcnt lgkmcnt(6)
	v_cvt_pk_bf16_f32 v38, v44, v42
	v_lshl_add_u64 v[60:61], v[18:19], 0, v[60:61]
	v_add_u32_e32 v42, 8, v58
	s_waitcnt lgkmcnt(4)
	v_cvt_pk_bf16_f32 v39, v46, v48
	s_waitcnt lgkmcnt(2)
	v_cvt_pk_bf16_f32 v40, v50, v52
	s_waitcnt lgkmcnt(0)
	v_cvt_pk_bf16_f32 v41, v54, v56
	global_store_dwordx4 v[60:61], v[38:41], off
	v_add_u32_e32 v60, 16, v58
	v_ashrrev_i32_e32 v61, 31, v60
	v_cvt_pk_bf16_f32 v38, v45, v43
	v_ashrrev_i32_e32 v43, 31, v42
	v_lshlrev_b64 v[42:43], 11, v[42:43]
	v_lshl_add_u64 v[42:43], v[18:19], 0, v[42:43]
	v_cvt_pk_bf16_f32 v39, v47, v49
	v_cvt_pk_bf16_f32 v40, v51, v53
	v_cvt_pk_bf16_f32 v41, v55, v57
	global_store_dwordx4 v[42:43], v[38:41], off
	ds_read2_b32 v[42:43], v25 offset0:16 offset1:24
	ds_read2_b32 v[44:45], v25 offset0:49 offset1:57
	ds_read2_b32 v[46:47], v25 offset0:82 offset1:90
	ds_read2_b32 v[48:49], v25 offset0:115 offset1:123
	ds_read2_b32 v[50:51], v25 offset0:148 offset1:156
	ds_read2_b32 v[52:53], v25 offset0:181 offset1:189
	ds_read2_b32 v[54:55], v25 offset0:214 offset1:222
	ds_read2_b32 v[56:57], v25 offset0:247 offset1:255
	v_lshlrev_b64 v[60:61], 11, v[60:61]
	s_waitcnt lgkmcnt(6)
	v_cvt_pk_bf16_f32 v38, v42, v44
	v_lshl_add_u64 v[60:61], v[18:19], 0, v[60:61]
	v_add_u32_e32 v42, 24, v58
	s_waitcnt lgkmcnt(4)
	v_cvt_pk_bf16_f32 v39, v46, v48
	s_waitcnt lgkmcnt(2)
	v_cvt_pk_bf16_f32 v40, v50, v52
	s_waitcnt lgkmcnt(0)
	v_cvt_pk_bf16_f32 v41, v54, v56
	global_store_dwordx4 v[60:61], v[38:41], off
	s_nop 1
	v_cvt_pk_bf16_f32 v38, v43, v45
	v_ashrrev_i32_e32 v43, 31, v42
	v_lshlrev_b64 v[42:43], 11, v[42:43]
	v_lshl_add_u64 v[18:19], v[18:19], 0, v[42:43]
	v_cvt_pk_bf16_f32 v39, v47, v49
	v_cvt_pk_bf16_f32 v40, v51, v53
	v_cvt_pk_bf16_f32 v41, v55, v57
	global_store_dwordx4 v[18:19], v[38:41], off
	s_waitcnt lgkmcnt(0)

; template <class Map>
; __device__ __forceinline__ void transpose_item(const float* W, int K, int N, bf16_t* WT, float* scr, int item, int nblk, int lane, Map srccol) {
;     const int kb = item / nblk, nb = item % nblk, k0 = 64 * kb, n0 = 32 * nb;
;     const int sc = srccol(n0 + (lane & 31));
;     float tv[32];
;     const float* wp = W + (size_t)(k0 + (lane >> 5)) * N + (sc >= 0 ? sc : 0);
; #pragma unroll
;     for (int i = 0; i < 32; ++i) tv[i] = wp[(size_t)(2 * i) * N];
.LBB0_916:
	s_andn2_b64 vcc, exec, s[6:7]
	s_cbranch_vccnz .LBB0_918
	s_ashr_i32 s6, s41, 31
	s_lshr_b32 s6, s6, 27
	s_add_i32 s6, s41, s6
	s_and_b32 s7, s6, 0xffffffe0
	s_sub_i32 s7, s41, s7
	s_lshl_b32 s6, s6, 1
	s_lshl_b32 s47, s7, 5
	s_and_b32 s26, s6, 0xffffffc0
	v_and_b32_e32 v0, 24, v36
	v_bitop3_b32 v18, s47, v206, v21 bitop3:0xc8
	v_or3_b32 v0, v18, v0, v29
	v_or_b32_e32 v18, s26, v22
	v_ashrrev_i32_e32 v19, 31, v18
	s_cmp_gt_i32 s7, -1
	v_lshlrev_b64 v[18:19], 12, v[18:19]
	s_cselect_b64 vcc, -1, 0
	v_lshl_add_u64 v[18:19], s[18:19], 0, v[18:19]
	v_cndmask_b32_e32 v0, 0, v0, vcc
	v_lshl_add_u64 v[18:19], v[0:1], 2, v[18:19]
	v_add_co_u32_e64 v38, s[6:7], s63, v18
	global_load_dword v0, v[18:19], off
	s_nop 0
	v_addc_co_u32_e64 v39, s[6:7], 0, v19, s[6:7]
	global_load_dword v40, v[38:39], off
	v_add_co_u32_e64 v38, s[6:7], s96, v18
	s_ashr_i32 s27, s26, 31
	s_nop 0
	v_addc_co_u32_e64 v39, s[6:7], 0, v19, s[6:7]
	global_load_dword v41, v[38:39], off
	v_add_co_u32_e64 v38, s[6:7], s58, v18
	s_waitcnt vmcnt(2)
	v_cndmask_b32_e32 v0, 0, v0, vcc
	v_addc_co_u32_e64 v39, s[6:7], 0, v19, s[6:7]
	global_load_dword v42, v[38:39], off
	v_add_co_u32_e64 v38, s[6:7], s60, v18
	s_nop 1
	v_addc_co_u32_e64 v39, s[6:7], 0, v19, s[6:7]
	global_load_dword v43, v[38:39], off
	v_add_co_u32_e64 v38, s[6:7], s54, v18
	s_nop 1
	v_addc_co_u32_e64 v39, s[6:7], 0, v19, s[6:7]
	global_load_dword v44, v[38:39], off
	v_add_co_u32_e64 v38, s[6:7], s71, v18
	s_nop 1
	v_addc_co_u32_e64 v39, s[6:7], 0, v19, s[6:7]
	global_load_dword v45, v[38:39], off
	v_add_co_u32_e64 v38, s[6:7], s72, v18
	s_nop 1
	v_addc_co_u32_e64 v39, s[6:7], 0, v19, s[6:7]
	global_load_dword v46, v[38:39], off
	v_add_co_u32_e64 v38, s[6:7], s50, v18
	s_nop 1
	v_addc_co_u32_e64 v39, s[6:7], 0, v19, s[6:7]
	global_load_dword v47, v[38:39], off
	v_add_co_u32_e64 v38, s[6:7], s55, v18
	s_nop 1
	v_addc_co_u32_e64 v39, s[6:7], 0, v19, s[6:7]
	global_load_dword v48, v[38:39], off
	v_add_co_u32_e64 v38, s[6:7], s56, v18
	s_nop 1
	v_addc_co_u32_e64 v39, s[6:7], 0, v19, s[6:7]
	global_load_dword v49, v[38:39], off
	v_add_co_u32_e64 v38, s[6:7], s57, v18
	s_nop 1
	v_addc_co_u32_e64 v39, s[6:7], 0, v19, s[6:7]
	global_load_dword v50, v[38:39], off
	v_add_co_u32_e64 v38, s[6:7], s59, v18
	s_nop 1
	v_addc_co_u32_e64 v39, s[6:7], 0, v19, s[6:7]
	global_load_dword v51, v[38:39], off
	v_add_co_u32_e64 v38, s[6:7], s52, v18
	s_nop 1
	v_addc_co_u32_e64 v39, s[6:7], 0, v19, s[6:7]
	global_load_dword v52, v[38:39], off
	v_add_co_u32_e64 v38, s[6:7], s62, v18
	s_nop 1
	v_addc_co_u32_e64 v39, s[6:7], 0, v19, s[6:7]
	global_load_dword v53, v[38:39], off
	v_add_co_u32_e64 v38, s[6:7], s64, v18
	s_nop 1
	v_addc_co_u32_e64 v39, s[6:7], 0, v19, s[6:7]
	global_load_dword v54, v[38:39], off
	v_add_co_u32_e64 v38, s[6:7], s73, v18
	s_nop 1
	v_addc_co_u32_e64 v39, s[6:7], 0, v19, s[6:7]
	global_load_dword v55, v[38:39], off
	v_add_co_u32_e64 v38, s[6:7], s74, v18
	s_nop 1
	v_addc_co_u32_e64 v39, s[6:7], 0, v19, s[6:7]
	global_load_dword v56, v[38:39], off
	v_add_co_u32_e64 v38, s[6:7], s75, v18
	s_nop 1
	v_addc_co_u32_e64 v39, s[6:7], 0, v19, s[6:7]
	global_load_dword v57, v[38:39], off
	v_add_co_u32_e64 v38, s[6:7], s1, v18
	s_nop 1
	v_addc_co_u32_e64 v39, s[6:7], 0, v19, s[6:7]
	global_load_dword v58, v[38:39], off
	v_add_co_u32_e64 v38, s[6:7], s76, v18
	s_nop 1
	v_addc_co_u32_e64 v39, s[6:7], 0, v19, s[6:7]
	global_load_dword v59, v[38:39], off
	v_add_co_u32_e64 v38, s[6:7], s77, v18
	s_nop 1
	v_addc_co_u32_e64 v39, s[6:7], 0, v19, s[6:7]
	global_load_dword v60, v[38:39], off
	v_add_co_u32_e64 v38, s[6:7], s33, v18
	s_nop 1
	v_addc_co_u32_e64 v39, s[6:7], 0, v19, s[6:7]
	global_load_dword v61, v[38:39], off
	v_add_co_u32_e64 v38, s[6:7], s80, v18
	s_nop 1
	v_addc_co_u32_e64 v39, s[6:7], 0, v19, s[6:7]
	global_load_dword v62, v[38:39], off
	v_add_co_u32_e64 v38, s[6:7], s0, v18
	s_nop 1
	v_addc_co_u32_e64 v39, s[6:7], 0, v19, s[6:7]
	global_load_dword v63, v[38:39], off
	v_add_co_u32_e64 v38, s[6:7], s81, v18
	s_nop 1
	v_addc_co_u32_e64 v39, s[6:7], 0, v19, s[6:7]
	global_load_dword v64, v[38:39], off
	v_add_co_u32_e64 v38, s[6:7], s82, v18
	s_nop 1
	v_addc_co_u32_e64 v39, s[6:7], 0, v19, s[6:7]
	global_load_dword v65, v[38:39], off
	v_add_co_u32_e64 v38, s[6:7], s83, v18
	s_nop 1
	v_addc_co_u32_e64 v39, s[6:7], 0, v19, s[6:7]
	global_load_dword v66, v[38:39], off
	v_add_co_u32_e64 v38, s[6:7], s84, v18
	s_nop 1
	v_addc_co_u32_e64 v39, s[6:7], 0, v19, s[6:7]
	global_load_dword v67, v[38:39], off
	v_add_co_u32_e64 v38, s[6:7], s85, v18
	s_nop 1
	v_addc_co_u32_e64 v39, s[6:7], 0, v19, s[6:7]
	global_load_dword v68, v[38:39], off
	v_add_co_u32_e64 v38, s[6:7], s86, v18
	s_nop 1
	v_addc_co_u32_e64 v39, s[6:7], 0, v19, s[6:7]
	v_add_co_u32_e64 v18, s[6:7], s87, v18
	global_load_dword v38, v[38:39], off
	s_nop 0
	v_addc_co_u32_e64 v19, s[6:7], 0, v19, s[6:7]
	global_load_dword v18, v[18:19], off
	s_waitcnt vmcnt(30)
	v_cndmask_b32_e32 v19, 0, v40, vcc
	ds_write2_b32 v23, v0, v19 offset1:66
	s_waitcnt vmcnt(29)
; __device__ __forceinline__ unsigned pk2(float lo, float hi) { unsigned r; asm("v_cvt_pk_bf16_f32 %0, %1, %2" : "=v"(r) : "v"(lo), "v"(hi)); return r; }
; template <class Map>
; __device__ __forceinline__ void transpose_item(const float* W, int K, int N, bf16_t* WT, float* scr, int item, int nblk, int lane, Map srccol) {
;     ...
; #pragma unroll
;     for (int i = 0; i < 32; ++i) { const int kk = 2 * i + (lane >> 5); scr[kk * 33 + (lane & 31)] = sc >= 0 ? tv[i] : 0.f; }
;     __builtin_amdgcn_s_waitcnt(0); asm volatile("" ::: "memory");
;     const int c = lane & 7;
; #pragma unroll
;     for (int j = 0; j < 4; ++j) { const int n = (lane >> 3) + 8 * j; const float* s = scr + (8 * c) * 33 + n;
;         u32x4 o; o.x = pk2(s[0 * 33], s[1 * 33]); o.y = pk2(s[2 * 33], s[3 * 33]); o.z = pk2(s[4 * 33], s[5 * 33]); o.w = pk2(s[6 * 33], s[7 * 33]);
;         *(u32x4*)(WT + (size_t)(n0 + n) * K + k0 + 8 * c) = o; }
;     __builtin_amdgcn_s_waitcnt(0); asm volatile("" ::: "memory");
	v_cndmask_b32_e32 v0, 0, v41, vcc
	s_waitcnt vmcnt(28)
	v_cndmask_b32_e32 v19, 0, v42, vcc
	ds_write2_b32 v23, v0, v19 offset0:132 offset1:198
	s_waitcnt vmcnt(27)
	v_cndmask_b32_e32 v0, 0, v43, vcc
	s_waitcnt vmcnt(26)
	v_cndmask_b32_e32 v19, 0, v44, vcc
	v_add_u32_e32 v39, 0x400, v23
	ds_write2_b32 v39, v0, v19 offset0:8 offset1:74
	s_waitcnt vmcnt(25)
	v_cndmask_b32_e32 v0, 0, v45, vcc
	s_waitcnt vmcnt(24)
	v_cndmask_b32_e32 v19, 0, v46, vcc
	ds_write2_b32 v39, v0, v19 offset0:140 offset1:206
	s_waitcnt vmcnt(23)
	v_cndmask_b32_e32 v0, 0, v47, vcc
	s_waitcnt vmcnt(22)
	v_cndmask_b32_e32 v19, 0, v48, vcc
	v_add_u32_e32 v39, 0x800, v23
	ds_write2_b32 v39, v0, v19 offset0:16 offset1:82
	s_waitcnt vmcnt(21)
	v_cndmask_b32_e32 v0, 0, v49, vcc
	s_waitcnt vmcnt(20)
	v_cndmask_b32_e32 v19, 0, v50, vcc
	ds_write2_b32 v39, v0, v19 offset0:148 offset1:214
	s_waitcnt vmcnt(19)
	v_cndmask_b32_e32 v0, 0, v51, vcc
	s_waitcnt vmcnt(18)
	v_cndmask_b32_e32 v19, 0, v52, vcc
	v_add_u32_e32 v39, 0xc00, v23
	ds_write2_b32 v39, v0, v19 offset0:24 offset1:90
	s_waitcnt vmcnt(17)
	v_cndmask_b32_e32 v0, 0, v53, vcc
	s_waitcnt vmcnt(16)
	v_cndmask_b32_e32 v19, 0, v54, vcc
	ds_write2_b32 v39, v0, v19 offset0:156 offset1:222
	s_waitcnt vmcnt(15)
	v_cndmask_b32_e32 v0, 0, v55, vcc
	s_waitcnt vmcnt(14)
	v_cndmask_b32_e32 v19, 0, v56, vcc
	v_add_u32_e32 v39, 0x1000, v23
	ds_write2_b32 v39, v0, v19 offset0:32 offset1:98
	s_waitcnt vmcnt(13)
	v_cndmask_b32_e32 v0, 0, v57, vcc
	s_waitcnt vmcnt(12)
	v_cndmask_b32_e32 v19, 0, v58, vcc
	ds_write2_b32 v39, v0, v19 offset0:164 offset1:230
	s_waitcnt vmcnt(11)
	v_cndmask_b32_e32 v0, 0, v59, vcc
	s_waitcnt vmcnt(10)
	v_cndmask_b32_e32 v19, 0, v60, vcc
	v_add_u32_e32 v39, 0x1400, v23
	ds_write2_b32 v39, v0, v19 offset0:40 offset1:106
	s_waitcnt vmcnt(9)
	v_cndmask_b32_e32 v0, 0, v61, vcc
	s_waitcnt vmcnt(8)
	v_cndmask_b32_e32 v19, 0, v62, vcc
	ds_write2_b32 v39, v0, v19 offset0:172 offset1:238
	s_waitcnt vmcnt(7)
	v_cndmask_b32_e32 v0, 0, v63, vcc
	v_add_u32_e32 v39, 0x1800, v23
	v_or_b32_e32 v58, s47, v24
	v_ashrrev_i32_e32 v59, 31, v58
	s_waitcnt vmcnt(6)
	v_cndmask_b32_e32 v19, 0, v64, vcc
	ds_write2_b32 v39, v0, v19 offset0:48 offset1:114
	v_lshlrev_b64 v[58:59], 11, v[58:59]
	s_waitcnt vmcnt(5)
	v_cndmask_b32_e32 v0, 0, v65, vcc
	s_waitcnt vmcnt(4)
	v_cndmask_b32_e32 v19, 0, v66, vcc
	ds_write2_b32 v39, v0, v19 offset0:180 offset1:246
	v_add_u32_e32 v39, 0x1c00, v23
	s_waitcnt vmcnt(3)
	v_cndmask_b32_e32 v0, 0, v67, vcc
	s_waitcnt vmcnt(2)
	v_cndmask_b32_e32 v19, 0, v68, vcc
	ds_write2_b32 v39, v0, v19 offset0:56 offset1:122
	s_waitcnt vmcnt(1)
	v_cndmask_b32_e32 v0, 0, v38, vcc
	s_waitcnt vmcnt(0)
	v_cndmask_b32_e32 v18, 0, v18, vcc
	ds_write2_b32 v39, v0, v18 offset0:188 offset1:254
	s_waitcnt vmcnt(0) expcnt(0) lgkmcnt(0)
	ds_read2_b32 v[42:43], v25 offset0:33 offset1:41
	ds_read2_b32 v[44:45], v25 offset1:8
	ds_read2_b32 v[46:47], v25 offset0:66 offset1:74
	ds_read2_b32 v[48:49], v25 offset0:99 offset1:107
	ds_read2_b32 v[50:51], v25 offset0:132 offset1:140
	ds_read2_b32 v[52:53], v25 offset0:165 offset1:173
	ds_read2_b32 v[54:55], v25 offset0:198 offset1:206
	ds_read2_b32 v[56:57], v25 offset0:231 offset1:239
	v_lshl_add_u64 v[18:19], s[26:27], 1, v[4:5]
	s_waitcnt lgkmcnt(6)
	v_cvt_pk_bf16_f32 v38, v44, v42
	v_lshl_add_u64 v[58:59], v[18:19], 0, v[58:59]
	v_or_b32_e32 v42, s47, v26
	s_waitcnt lgkmcnt(4)
	v_cvt_pk_bf16_f32 v39, v46, v48
	s_waitcnt lgkmcnt(2)
	v_cvt_pk_bf16_f32 v40, v50, v52
	s_waitcnt lgkmcnt(0)
	v_cvt_pk_bf16_f32 v41, v54, v56
	global_store_dwordx4 v[58:59], v[38:41], off
	v_or_b32_e32 v58, s47, v27
	v_ashrrev_i32_e32 v59, 31, v58
	v_cvt_pk_bf16_f32 v38, v45, v43
	v_ashrrev_i32_e32 v43, 31, v42
	v_lshlrev_b64 v[42:43], 11, v[42:43]
	v_lshl_add_u64 v[42:43], v[18:19], 0, v[42:43]
	v_cvt_pk_bf16_f32 v39, v47, v49
	v_cvt_pk_bf16_f32 v40, v51, v53
	v_cvt_pk_bf16_f32 v41, v55, v57
	global_store_dwordx4 v[42:43], v[38:41], off
	ds_read2_b32 v[42:43], v25 offset0:16 offset1:24
	ds_read2_b32 v[44:45], v25 offset0:49 offset1:57
	ds_read2_b32 v[46:47], v25 offset0:82 offset1:90
	ds_read2_b32 v[48:49], v25 offset0:115 offset1:123
	ds_read2_b32 v[50:51], v25 offset0:148 offset1:156
	ds_read2_b32 v[52:53], v25 offset0:181 offset1:189
	ds_read2_b32 v[54:55], v25 offset0:214 offset1:222
	ds_read2_b32 v[56:57], v25 offset0:247 offset1:255
	v_lshlrev_b64 v[58:59], 11, v[58:59]
	s_waitcnt lgkmcnt(6)
	v_cvt_pk_bf16_f32 v38, v42, v44
	v_lshl_add_u64 v[58:59], v[18:19], 0, v[58:59]
	v_or_b32_e32 v42, s47, v28
	s_waitcnt lgkmcnt(4)
	v_cvt_pk_bf16_f32 v39, v46, v48
	s_waitcnt lgkmcnt(2)
	v_cvt_pk_bf16_f32 v40, v50, v52
	s_waitcnt lgkmcnt(0)
	v_cvt_pk_bf16_f32 v41, v54, v56
	global_store_dwordx4 v[58:59], v[38:41], off
	s_nop 1
	v_cvt_pk_bf16_f32 v38, v43, v45
	v_ashrrev_i32_e32 v43, 31, v42
	v_lshlrev_b64 v[42:43], 11, v[42:43]
	v_lshl_add_u64 v[18:19], v[18:19], 0, v[42:43]
	v_cvt_pk_bf16_f32 v39, v47, v49
	v_cvt_pk_bf16_f32 v40, v51, v53
	v_cvt_pk_bf16_f32 v41, v55, v57
	global_store_dwordx4 v[18:19], v[38:41], off
	s_waitcnt lgkmcnt(0)

; template <class Map>
; __device__ __forceinline__ void transpose_item(const float* W, int K, int N, bf16_t* WT, float* scr, int item, int nblk, int lane, Map srccol) {
;     const int kb = item / nblk, nb = item % nblk, k0 = 64 * kb, n0 = 32 * nb;
;     const int sc = srccol(n0 + (lane & 31));
;     float tv[32];
;     const float* wp = W + (size_t)(k0 + (lane >> 5)) * N + (sc >= 0 ? sc : 0);
; #pragma unroll
;     for (int i = 0; i < 32; ++i) tv[i] = wp[(size_t)(2 * i) * N];
.LBB0_922:
	s_or_b64 exec, exec, s[6:7]
	s_lshl_b32 s26, s26, 6
	v_or_b32_e32 v0, s26, v22
	v_mov_b64_e32 v[38:39], s[16:17]
	s_movk_i32 s6, 0x3840
	v_mad_i64_i32 v[38:39], s[6:7], v0, s6, v[38:39]
	v_cmp_lt_i32_e64 s[6:7], -1, v18
	s_mov_b32 s27, 0x15000
	s_nop 0
	v_cndmask_b32_e64 v0, 0, v18, s[6:7]
	v_lshl_add_u64 v[18:19], v[0:1], 2, v[38:39]
	v_add_co_u32_e32 v38, vcc, 0x7000, v18
	global_load_dword v0, v[18:19], off
	s_nop 0
	v_addc_co_u32_e32 v39, vcc, 0, v19, vcc
	global_load_dword v40, v[38:39], off offset:128
	v_add_co_u32_e32 v38, vcc, s72, v18
	s_waitcnt vmcnt(1)
	v_cndmask_b32_e64 v0, 0, v0, s[6:7]
	v_addc_co_u32_e32 v39, vcc, 0, v19, vcc
	global_load_dword v41, v[38:39], off offset:256
	v_add_co_u32_e32 v38, vcc, s27, v18
	s_mov_b32 s27, 0x23000
	s_nop 0
	v_addc_co_u32_e32 v39, vcc, 0, v19, vcc
	global_load_dword v42, v[38:39], off offset:384
	v_add_co_u32_e32 v38, vcc, s62, v18
	ds_write_b32 v30, v0
	s_nop 0
	v_addc_co_u32_e32 v39, vcc, 0, v19, vcc
	global_load_dword v43, v[38:39], off offset:512
	v_add_co_u32_e32 v38, vcc, s27, v18
	s_mov_b32 s27, 0x31000
	s_nop 0
	v_addc_co_u32_e32 v39, vcc, 0, v19, vcc
	global_load_dword v44, v[38:39], off offset:640
	v_add_co_u32_e32 v38, vcc, s77, v18
	s_waitcnt vmcnt(4)
	v_cndmask_b32_e64 v0, 0, v40, s[6:7]
	v_addc_co_u32_e32 v39, vcc, 0, v19, vcc
	global_load_dword v45, v[38:39], off offset:768
	v_add_co_u32_e32 v38, vcc, s27, v18
	s_mov_b32 s27, 0x3f000
	s_nop 0
	v_addc_co_u32_e32 v39, vcc, 0, v19, vcc
	global_load_dword v46, v[38:39], off offset:896
	v_add_co_u32_e32 v38, vcc, s84, v18
	s_nop 1
	v_addc_co_u32_e32 v39, vcc, 0, v19, vcc
	global_load_dword v47, v[38:39], off offset:1024
	v_add_co_u32_e32 v38, vcc, s27, v18
	s_mov_b32 s27, 0x46000
	s_nop 0
	v_addc_co_u32_e32 v39, vcc, 0, v19, vcc
	global_load_dword v48, v[38:39], off offset:1152
	v_add_co_u32_e32 v38, vcc, s27, v18
	s_mov_b32 s27, 0x4d000
	s_nop 0
	v_addc_co_u32_e32 v39, vcc, 0, v19, vcc
	global_load_dword v49, v[38:39], off offset:1280
	v_add_co_u32_e32 v38, vcc, s27, v18
	s_mov_b32 s27, 0x54000
	s_nop 0
	v_addc_co_u32_e32 v39, vcc, 0, v19, vcc
	global_load_dword v50, v[38:39], off offset:1408
	v_add_co_u32_e32 v38, vcc, s27, v18
	s_mov_b32 s27, 0x5b000
	s_nop 0
	v_addc_co_u32_e32 v39, vcc, 0, v19, vcc
	global_load_dword v51, v[38:39], off offset:1536
	v_add_co_u32_e32 v38, vcc, s27, v18
	s_mov_b32 s27, 0x62000
	s_nop 0
	v_addc_co_u32_e32 v39, vcc, 0, v19, vcc
	global_load_dword v52, v[38:39], off offset:1664
	v_add_co_u32_e32 v38, vcc, s27, v18
	s_mov_b32 s27, 0x69000
	s_nop 0
	v_addc_co_u32_e32 v39, vcc, 0, v19, vcc
	global_load_dword v53, v[38:39], off offset:1792
	v_add_co_u32_e32 v38, vcc, s27, v18
	s_mov_b32 s27, 0x70000
	s_nop 0
	v_addc_co_u32_e32 v39, vcc, 0, v19, vcc
	global_load_dword v54, v[38:39], off offset:1920
	v_add_co_u32_e32 v38, vcc, s27, v18
	s_mov_b32 s27, 0x77000
	s_nop 0
	v_addc_co_u32_e32 v39, vcc, 0, v19, vcc
	global_load_dword v55, v[38:39], off offset:2048
	v_add_co_u32_e32 v38, vcc, s27, v18
	s_mov_b32 s27, 0x7e000
	s_nop 0
	v_addc_co_u32_e32 v39, vcc, 0, v19, vcc
	global_load_dword v56, v[38:39], off offset:2176
	v_add_co_u32_e32 v38, vcc, s27, v18
	s_mov_b32 s27, 0x85000
	s_nop 0
	v_addc_co_u32_e32 v39, vcc, 0, v19, vcc
	global_load_dword v57, v[38:39], off offset:2304
	v_add_co_u32_e32 v38, vcc, s27, v18
	s_mov_b32 s27, 0x8c000
	s_nop 0
	v_addc_co_u32_e32 v39, vcc, 0, v19, vcc
	global_load_dword v58, v[38:39], off offset:2432
	v_add_co_u32_e32 v38, vcc, s27, v18
	s_mov_b32 s27, 0x93000
	s_nop 0
	v_addc_co_u32_e32 v39, vcc, 0, v19, vcc
	global_load_dword v59, v[38:39], off offset:2560
	v_add_co_u32_e32 v38, vcc, s27, v18
	s_mov_b32 s27, 0x9a000
	s_nop 0
	v_addc_co_u32_e32 v39, vcc, 0, v19, vcc
	global_load_dword v60, v[38:39], off offset:2688
	v_add_co_u32_e32 v38, vcc, s27, v18
	s_mov_b32 s27, 0xa1000
	s_nop 0
	v_addc_co_u32_e32 v39, vcc, 0, v19, vcc
	global_load_dword v61, v[38:39], off offset:2816
	v_add_co_u32_e32 v38, vcc, s27, v18
	s_mov_b32 s27, 0xa8000
	s_nop 0
	v_addc_co_u32_e32 v39, vcc, 0, v19, vcc
	global_load_dword v62, v[38:39], off offset:2944
	v_add_co_u32_e32 v38, vcc, s27, v18
	s_mov_b32 s27, 0xaf000
	s_nop 0
	v_addc_co_u32_e32 v39, vcc, 0, v19, vcc
	global_load_dword v63, v[38:39], off offset:3072
	v_add_co_u32_e32 v38, vcc, s27, v18
	s_mov_b32 s27, 0xb6000
	s_nop 0
	v_addc_co_u32_e32 v39, vcc, 0, v19, vcc
	global_load_dword v64, v[38:39], off offset:3200
	v_add_co_u32_e32 v38, vcc, s27, v18
	s_mov_b32 s27, 0xbd000
	s_nop 0
	v_addc_co_u32_e32 v39, vcc, 0, v19, vcc
	global_load_dword v65, v[38:39], off offset:3328
	v_add_co_u32_e32 v38, vcc, s27, v18
	s_mov_b32 s27, 0xc4000
	s_nop 0
	v_addc_co_u32_e32 v39, vcc, 0, v19, vcc
	global_load_dword v66, v[38:39], off offset:3456
	v_add_co_u32_e32 v38, vcc, s27, v18
	s_mov_b32 s27, 0xcb000
	s_nop 0
	v_addc_co_u32_e32 v39, vcc, 0, v19, vcc
	global_load_dword v67, v[38:39], off offset:3584
	v_add_co_u32_e32 v38, vcc, s27, v18
	s_mov_b32 s27, 0xd2000
	s_nop 0
	v_addc_co_u32_e32 v39, vcc, 0, v19, vcc
	global_load_dword v68, v[38:39], off offset:3712
	v_add_co_u32_e32 v38, vcc, s27, v18
	s_mov_b32 s27, 0xd9000
	s_nop 0
	v_addc_co_u32_e32 v39, vcc, 0, v19, vcc
	v_add_co_u32_e32 v18, vcc, s27, v18
	global_load_dword v38, v[38:39], off offset:3840
	s_nop 0
	v_addc_co_u32_e32 v19, vcc, 0, v19, vcc
	global_load_dword v18, v[18:19], off offset:3968
	s_waitcnt vmcnt(29)
; __device__ __forceinline__ unsigned pk2(float lo, float hi) { unsigned r; asm("v_cvt_pk_bf16_f32 %0, %1, %2" : "=v"(r) : "v"(lo), "v"(hi)); return r; }
; template <class Map>
; __device__ __forceinline__ void transpose_item(const float* W, int K, int N, bf16_t* WT, float* scr, int item, int nblk, int lane, Map srccol) {
;     ...
; #pragma unroll
;     for (int i = 0; i < 32; ++i) { const int kk = 2 * i + (lane >> 5); scr[kk * 33 + (lane & 31)] = sc >= 0 ? tv[i] : 0.f; }
;     __builtin_amdgcn_s_waitcnt(0); asm volatile("" ::: "memory");
;     const int c = lane & 7;
; #pragma unroll
;     for (int j = 0; j < 4; ++j) { const int n = (lane >> 3) + 8 * j; const float* s = scr + (8 * c) * 33 + n;
;         u32x4 o; o.x = pk2(s[0 * 33], s[1 * 33]); o.y = pk2(s[2 * 33], s[3 * 33]); o.z = pk2(s[4 * 33], s[5 * 33]); o.w = pk2(s[6 * 33], s[7 * 33]);
;         *(u32x4*)(WT + (size_t)(n0 + n) * K + k0 + 8 * c) = o; }
;     __builtin_amdgcn_s_waitcnt(0); asm volatile("" ::: "memory");
	v_cndmask_b32_e64 v19, 0, v41, s[6:7]
	ds_write2_b32 v31, v0, v19 offset0:66 offset1:132
	s_waitcnt vmcnt(28)
	v_cndmask_b32_e64 v0, 0, v42, s[6:7]
	s_waitcnt vmcnt(27)
	v_cndmask_b32_e64 v19, 0, v43, s[6:7]
	v_add_u32_e32 v39, 0x200, v31
	ds_write2_b32 v39, v0, v19 offset0:70 offset1:136
	s_waitcnt vmcnt(26)
	v_cndmask_b32_e64 v0, 0, v44, s[6:7]
	s_waitcnt vmcnt(25)
	v_cndmask_b32_e64 v19, 0, v45, s[6:7]
	v_add_u32_e32 v39, 0x400, v31
	ds_write2_b32 v39, v0, v19 offset0:74 offset1:140
	s_waitcnt vmcnt(24)
	v_cndmask_b32_e64 v0, 0, v46, s[6:7]
	s_waitcnt vmcnt(23)
	v_cndmask_b32_e64 v19, 0, v47, s[6:7]
	v_add_u32_e32 v39, 0x600, v31
	ds_write2_b32 v39, v0, v19 offset0:78 offset1:144
	s_waitcnt vmcnt(22)
	v_cndmask_b32_e64 v0, 0, v48, s[6:7]
	s_waitcnt vmcnt(21)
	v_cndmask_b32_e64 v19, 0, v49, s[6:7]
	v_add_u32_e32 v39, 0x800, v31
	ds_write2_b32 v39, v0, v19 offset0:82 offset1:148
	s_waitcnt vmcnt(20)
	v_cndmask_b32_e64 v0, 0, v50, s[6:7]
	s_waitcnt vmcnt(19)
	v_cndmask_b32_e64 v19, 0, v51, s[6:7]
	v_add_u32_e32 v39, 0xa00, v31
	ds_write2_b32 v39, v0, v19 offset0:86 offset1:152
	s_waitcnt vmcnt(18)
	v_cndmask_b32_e64 v0, 0, v52, s[6:7]
	s_waitcnt vmcnt(17)
	v_cndmask_b32_e64 v19, 0, v53, s[6:7]
	v_add_u32_e32 v39, 0xc00, v31
	ds_write2_b32 v39, v0, v19 offset0:90 offset1:156
	s_waitcnt vmcnt(15)
	v_cndmask_b32_e64 v19, 0, v55, s[6:7]
	v_cndmask_b32_e64 v0, 0, v54, s[6:7]
	ds_write_b32 v32, v19
	s_waitcnt vmcnt(14)
	v_cndmask_b32_e64 v19, 0, v56, s[6:7]
	v_add_u32_e32 v39, 0xe00, v31
	ds_write2_b32 v39, v0, v19 offset0:94 offset1:226
	s_waitcnt vmcnt(13)
	v_cndmask_b32_e64 v0, 0, v57, s[6:7]
	s_waitcnt vmcnt(12)
	v_cndmask_b32_e64 v19, 0, v58, s[6:7]
	v_add_u32_e32 v39, 0x1000, v31
	ds_write2_b32 v39, v0, v19 offset0:164 offset1:230
	s_waitcnt vmcnt(11)
	v_cndmask_b32_e64 v0, 0, v59, s[6:7]
	s_waitcnt vmcnt(10)
	v_cndmask_b32_e64 v19, 0, v60, s[6:7]
	v_add_u32_e32 v39, 0x1400, v31
	ds_write2_b32 v39, v0, v19 offset0:40 offset1:106
	s_waitcnt vmcnt(9)
	v_cndmask_b32_e64 v0, 0, v61, s[6:7]
	s_waitcnt vmcnt(8)
	v_cndmask_b32_e64 v19, 0, v62, s[6:7]
	ds_write2_b32 v39, v0, v19 offset0:172 offset1:238
	s_waitcnt vmcnt(7)
	v_cndmask_b32_e64 v0, 0, v63, s[6:7]
	s_waitcnt vmcnt(6)
	v_cndmask_b32_e64 v19, 0, v64, s[6:7]
	v_add_u32_e32 v39, 0x1800, v31
	ds_write2_b32 v39, v0, v19 offset0:48 offset1:114
	v_add_u32_e32 v58, s47, v24
	s_ashr_i32 s27, s26, 31
	v_ashrrev_i32_e32 v59, 31, v58
	s_waitcnt vmcnt(5)
	v_cndmask_b32_e64 v0, 0, v65, s[6:7]
	v_lshlrev_b64 v[60:61], 11, v[58:59]
	s_waitcnt vmcnt(4)
	v_cndmask_b32_e64 v19, 0, v66, s[6:7]
	ds_write2_b32 v39, v0, v19 offset0:180 offset1:246
	v_add_u32_e32 v39, 0x1c00, v31
	s_waitcnt vmcnt(3)
	v_cndmask_b32_e64 v0, 0, v67, s[6:7]
	s_waitcnt vmcnt(2)
	v_cndmask_b32_e64 v19, 0, v68, s[6:7]
	ds_write2_b32 v39, v0, v19 offset0:56 offset1:122
	s_waitcnt vmcnt(1)
	v_cndmask_b32_e64 v0, 0, v38, s[6:7]
	s_waitcnt vmcnt(0)
	v_cndmask_b32_e64 v18, 0, v18, s[6:7]
	ds_write2_b32 v39, v0, v18 offset0:188 offset1:254
	s_waitcnt vmcnt(0) expcnt(0) lgkmcnt(0)
	ds_read2_b32 v[42:43], v25 offset0:33 offset1:41
	ds_read2_b32 v[44:45], v25 offset1:8
	ds_read2_b32 v[46:47], v25 offset0:66 offset1:74
	ds_read2_b32 v[48:49], v25 offset0:99 offset1:107
	ds_read2_b32 v[50:51], v25 offset0:132 offset1:140
	ds_read2_b32 v[52:53], v25 offset0:165 offset1:173
	ds_read2_b32 v[54:55], v25 offset0:198 offset1:206
	ds_read2_b32 v[56:57], v25 offset0:231 offset1:239
	v_lshl_add_u64 v[18:19], s[26:27], 1, v[6:7]
	s_waitcnt lgkmcnt(6)
	v_cvt_pk_bf16_f32 v38, v44, v42
	v_lshl_add_u64 v[60:61], v[18:19], 0, v[60:61]
	v_add_u32_e32 v42, 8, v58
	s_waitcnt lgkmcnt(4)
	v_cvt_pk_bf16_f32 v39, v46, v48
	s_waitcnt lgkmcnt(2)
	v_cvt_pk_bf16_f32 v40, v50, v52
	s_waitcnt lgkmcnt(0)
	v_cvt_pk_bf16_f32 v41, v54, v56
	global_store_dwordx4 v[60:61], v[38:41], off
	v_add_u32_e32 v60, 16, v58
	v_ashrrev_i32_e32 v61, 31, v60
	v_cvt_pk_bf16_f32 v38, v45, v43
	v_ashrrev_i32_e32 v43, 31, v42
	v_lshlrev_b64 v[42:43], 11, v[42:43]
	v_lshl_add_u64 v[42:43], v[18:19], 0, v[42:43]
	v_cvt_pk_bf16_f32 v39, v47, v49
	v_cvt_pk_bf16_f32 v40, v51, v53
	v_cvt_pk_bf16_f32 v41, v55, v57
	global_store_dwordx4 v[42:43], v[38:41], off
	ds_read2_b32 v[42:43], v25 offset0:16 offset1:24
	ds_read2_b32 v[44:45], v25 offset0:49 offset1:57
	ds_read2_b32 v[46:47], v25 offset0:82 offset1:90
	ds_read2_b32 v[48:49], v25 offset0:115 offset1:123
	ds_read2_b32 v[50:51], v25 offset0:148 offset1:156
	ds_read2_b32 v[52:53], v25 offset0:181 offset1:189
	ds_read2_b32 v[54:55], v25 offset0:214 offset1:222
	ds_read2_b32 v[56:57], v25 offset0:247 offset1:255
	v_lshlrev_b64 v[60:61], 11, v[60:61]
	s_waitcnt lgkmcnt(6)
	v_cvt_pk_bf16_f32 v38, v42, v44
	v_lshl_add_u64 v[60:61], v[18:19], 0, v[60:61]
	v_add_u32_e32 v42, 24, v58
	s_waitcnt lgkmcnt(4)
	v_cvt_pk_bf16_f32 v39, v46, v48
	s_waitcnt lgkmcnt(2)
	v_cvt_pk_bf16_f32 v40, v50, v52
	s_waitcnt lgkmcnt(0)
	v_cvt_pk_bf16_f32 v41, v54, v56
	global_store_dwordx4 v[60:61], v[38:41], off
	s_nop 1
	v_cvt_pk_bf16_f32 v38, v43, v45
	v_ashrrev_i32_e32 v43, 31, v42
	v_lshlrev_b64 v[42:43], 11, v[42:43]
	v_lshl_add_u64 v[18:19], v[18:19], 0, v[42:43]
	v_cvt_pk_bf16_f32 v39, v47, v49
	v_cvt_pk_bf16_f32 v40, v51, v53
	v_cvt_pk_bf16_f32 v41, v55, v57
	global_store_dwordx4 v[18:19], v[38:41], off
	s_waitcnt lgkmcnt(0)

; template <class Map>
; __device__ __forceinline__ void transpose_item(const float* W, int K, int N, bf16_t* WT, float* scr, int item, int nblk, int lane, Map srccol) {
;     const int kb = item / nblk, nb = item % nblk, k0 = 64 * kb, n0 = 32 * nb;
;     const int sc = srccol(n0 + (lane & 31));
;     float tv[32];
;     const float* wp = W + (size_t)(k0 + (lane >> 5)) * N + (sc >= 0 ? sc : 0);
; #pragma unroll
;     for (int i = 0; i < 32; ++i) tv[i] = wp[(size_t)(2 * i) * N];
.LBB0_924:
	s_and_b64 vcc, exec, s[6:7]
	s_cbranch_vccz .LBB0_926
	s_ashr_i32 s6, s41, 31
	s_lshr_b32 s6, s6, 27
	s_add_i32 s6, s41, s6
	s_and_b32 s7, s6, 0xffffffe0
	s_sub_i32 s7, s41, s7
	s_lshl_b32 s6, s6, 1
	s_lshl_b32 s47, s7, 5
	s_and_b32 s26, s6, 0xffffffc0
	v_and_b32_e32 v0, 24, v36
	v_bitop3_b32 v18, s47, v206, v21 bitop3:0xc8
	v_or3_b32 v0, v18, v0, v29
	v_or_b32_e32 v18, s26, v22
	v_ashrrev_i32_e32 v19, 31, v18
	s_cmp_gt_i32 s7, -1
	v_lshlrev_b64 v[18:19], 12, v[18:19]
	s_cselect_b64 vcc, -1, 0
	v_lshl_add_u64 v[18:19], s[10:11], 0, v[18:19]
	v_cndmask_b32_e32 v0, 0, v0, vcc
	v_lshl_add_u64 v[18:19], v[0:1], 2, v[18:19]
	v_add_co_u32_e64 v38, s[6:7], s63, v18
	global_load_dword v0, v[18:19], off
	s_nop 0
	v_addc_co_u32_e64 v39, s[6:7], 0, v19, s[6:7]
	global_load_dword v40, v[38:39], off
	v_add_co_u32_e64 v38, s[6:7], s96, v18
	s_ashr_i32 s27, s26, 31
	s_nop 0
	v_addc_co_u32_e64 v39, s[6:7], 0, v19, s[6:7]
	global_load_dword v41, v[38:39], off
	v_add_co_u32_e64 v38, s[6:7], s58, v18
	s_waitcnt vmcnt(2)
	v_cndmask_b32_e32 v0, 0, v0, vcc
	v_addc_co_u32_e64 v39, s[6:7], 0, v19, s[6:7]
	global_load_dword v42, v[38:39], off
	v_add_co_u32_e64 v38, s[6:7], s60, v18
	s_nop 1
	v_addc_co_u32_e64 v39, s[6:7], 0, v19, s[6:7]
	global_load_dword v43, v[38:39], off
	v_add_co_u32_e64 v38, s[6:7], s54, v18
	s_nop 1
	v_addc_co_u32_e64 v39, s[6:7], 0, v19, s[6:7]
	global_load_dword v44, v[38:39], off
	v_add_co_u32_e64 v38, s[6:7], s71, v18
	s_nop 1
	v_addc_co_u32_e64 v39, s[6:7], 0, v19, s[6:7]
	global_load_dword v45, v[38:39], off
	v_add_co_u32_e64 v38, s[6:7], s72, v18
	s_nop 1
	v_addc_co_u32_e64 v39, s[6:7], 0, v19, s[6:7]
	global_load_dword v46, v[38:39], off
	v_add_co_u32_e64 v38, s[6:7], s50, v18
	s_nop 1
	v_addc_co_u32_e64 v39, s[6:7], 0, v19, s[6:7]
	global_load_dword v47, v[38:39], off
	v_add_co_u32_e64 v38, s[6:7], s55, v18
	s_nop 1
	v_addc_co_u32_e64 v39, s[6:7], 0, v19, s[6:7]
	global_load_dword v48, v[38:39], off
	v_add_co_u32_e64 v38, s[6:7], s56, v18
	s_nop 1
	v_addc_co_u32_e64 v39, s[6:7], 0, v19, s[6:7]
	global_load_dword v49, v[38:39], off
	v_add_co_u32_e64 v38, s[6:7], s57, v18
	s_nop 1
	v_addc_co_u32_e64 v39, s[6:7], 0, v19, s[6:7]
	global_load_dword v50, v[38:39], off
	v_add_co_u32_e64 v38, s[6:7], s59, v18
	s_nop 1
	v_addc_co_u32_e64 v39, s[6:7], 0, v19, s[6:7]
	global_load_dword v51, v[38:39], off
	v_add_co_u32_e64 v38, s[6:7], s52, v18
	s_nop 1
	v_addc_co_u32_e64 v39, s[6:7], 0, v19, s[6:7]
	global_load_dword v52, v[38:39], off
	v_add_co_u32_e64 v38, s[6:7], s62, v18
	s_nop 1
	v_addc_co_u32_e64 v39, s[6:7], 0, v19, s[6:7]
	global_load_dword v53, v[38:39], off
	v_add_co_u32_e64 v38, s[6:7], s64, v18
	s_nop 1
	v_addc_co_u32_e64 v39, s[6:7], 0, v19, s[6:7]
	global_load_dword v54, v[38:39], off
	v_add_co_u32_e64 v38, s[6:7], s73, v18
	s_nop 1
	v_addc_co_u32_e64 v39, s[6:7], 0, v19, s[6:7]
	global_load_dword v55, v[38:39], off
	v_add_co_u32_e64 v38, s[6:7], s74, v18
	s_nop 1
	v_addc_co_u32_e64 v39, s[6:7], 0, v19, s[6:7]
	global_load_dword v56, v[38:39], off
	v_add_co_u32_e64 v38, s[6:7], s75, v18
	s_nop 1
	v_addc_co_u32_e64 v39, s[6:7], 0, v19, s[6:7]
	global_load_dword v57, v[38:39], off
	v_add_co_u32_e64 v38, s[6:7], s1, v18
	s_nop 1
	v_addc_co_u32_e64 v39, s[6:7], 0, v19, s[6:7]
	global_load_dword v58, v[38:39], off
	v_add_co_u32_e64 v38, s[6:7], s76, v18
	s_nop 1
	v_addc_co_u32_e64 v39, s[6:7], 0, v19, s[6:7]
	global_load_dword v59, v[38:39], off
	v_add_co_u32_e64 v38, s[6:7], s77, v18
	s_nop 1
	v_addc_co_u32_e64 v39, s[6:7], 0, v19, s[6:7]
	global_load_dword v60, v[38:39], off
	v_add_co_u32_e64 v38, s[6:7], s33, v18
	s_nop 1
	v_addc_co_u32_e64 v39, s[6:7], 0, v19, s[6:7]
	global_load_dword v61, v[38:39], off
	v_add_co_u32_e64 v38, s[6:7], s80, v18
	s_nop 1
	v_addc_co_u32_e64 v39, s[6:7], 0, v19, s[6:7]
	global_load_dword v62, v[38:39], off
	v_add_co_u32_e64 v38, s[6:7], s0, v18
	s_nop 1
	v_addc_co_u32_e64 v39, s[6:7], 0, v19, s[6:7]
	global_load_dword v63, v[38:39], off
	v_add_co_u32_e64 v38, s[6:7], s81, v18
	s_nop 1
	v_addc_co_u32_e64 v39, s[6:7], 0, v19, s[6:7]
	global_load_dword v64, v[38:39], off
	v_add_co_u32_e64 v38, s[6:7], s82, v18
	s_nop 1
	v_addc_co_u32_e64 v39, s[6:7], 0, v19, s[6:7]
	global_load_dword v65, v[38:39], off
	v_add_co_u32_e64 v38, s[6:7], s83, v18
	s_nop 1
	v_addc_co_u32_e64 v39, s[6:7], 0, v19, s[6:7]
	global_load_dword v66, v[38:39], off
	v_add_co_u32_e64 v38, s[6:7], s84, v18
	s_nop 1
	v_addc_co_u32_e64 v39, s[6:7], 0, v19, s[6:7]
	global_load_dword v67, v[38:39], off
	v_add_co_u32_e64 v38, s[6:7], s85, v18
	s_nop 1
	v_addc_co_u32_e64 v39, s[6:7], 0, v19, s[6:7]
	global_load_dword v68, v[38:39], off
	v_add_co_u32_e64 v38, s[6:7], s86, v18
	s_nop 1
	v_addc_co_u32_e64 v39, s[6:7], 0, v19, s[6:7]
	v_add_co_u32_e64 v18, s[6:7], s87, v18
	global_load_dword v38, v[38:39], off
	s_nop 0
	v_addc_co_u32_e64 v19, s[6:7], 0, v19, s[6:7]
	global_load_dword v18, v[18:19], off
	s_waitcnt vmcnt(30)
	v_cndmask_b32_e32 v19, 0, v40, vcc
	ds_write2_b32 v23, v0, v19 offset1:66
	s_waitcnt vmcnt(29)
; __device__ __forceinline__ unsigned pk2(float lo, float hi) { unsigned r; asm("v_cvt_pk_bf16_f32 %0, %1, %2" : "=v"(r) : "v"(lo), "v"(hi)); return r; }
; template <class Map>
; __device__ __forceinline__ void transpose_item(const float* W, int K, int N, bf16_t* WT, float* scr, int item, int nblk, int lane, Map srccol) {
;     ...
; #pragma unroll
;     for (int i = 0; i < 32; ++i) { const int kk = 2 * i + (lane >> 5); scr[kk * 33 + (lane & 31)] = sc >= 0 ? tv[i] : 0.f; }
;     __builtin_amdgcn_s_waitcnt(0); asm volatile("" ::: "memory");
;     const int c = lane & 7;
; #pragma unroll
;     for (int j = 0; j < 4; ++j) { const int n = (lane >> 3) + 8 * j; const float* s = scr + (8 * c) * 33 + n;
;         u32x4 o; o.x = pk2(s[0 * 33], s[1 * 33]); o.y = pk2(s[2 * 33], s[3 * 33]); o.z = pk2(s[4 * 33], s[5 * 33]); o.w = pk2(s[6 * 33], s[7 * 33]);
;         *(u32x4*)(WT + (size_t)(n0 + n) * K + k0 + 8 * c) = o; }
;     __builtin_amdgcn_s_waitcnt(0); asm volatile("" ::: "memory");
	v_cndmask_b32_e32 v0, 0, v41, vcc
	s_waitcnt vmcnt(28)
	v_cndmask_b32_e32 v19, 0, v42, vcc
	ds_write2_b32 v23, v0, v19 offset0:132 offset1:198
	s_waitcnt vmcnt(27)
	v_cndmask_b32_e32 v0, 0, v43, vcc
	s_waitcnt vmcnt(26)
	v_cndmask_b32_e32 v19, 0, v44, vcc
	v_add_u32_e32 v39, 0x400, v23
	ds_write2_b32 v39, v0, v19 offset0:8 offset1:74
	s_waitcnt vmcnt(25)
	v_cndmask_b32_e32 v0, 0, v45, vcc
	s_waitcnt vmcnt(24)
	v_cndmask_b32_e32 v19, 0, v46, vcc
	ds_write2_b32 v39, v0, v19 offset0:140 offset1:206
	s_waitcnt vmcnt(23)
	v_cndmask_b32_e32 v0, 0, v47, vcc
	s_waitcnt vmcnt(22)
	v_cndmask_b32_e32 v19, 0, v48, vcc
	v_add_u32_e32 v39, 0x800, v23
	ds_write2_b32 v39, v0, v19 offset0:16 offset1:82
	s_waitcnt vmcnt(21)
	v_cndmask_b32_e32 v0, 0, v49, vcc
	s_waitcnt vmcnt(20)
	v_cndmask_b32_e32 v19, 0, v50, vcc
	ds_write2_b32 v39, v0, v19 offset0:148 offset1:214
	s_waitcnt vmcnt(19)
	v_cndmask_b32_e32 v0, 0, v51, vcc
	s_waitcnt vmcnt(18)
	v_cndmask_b32_e32 v19, 0, v52, vcc
	v_add_u32_e32 v39, 0xc00, v23
	ds_write2_b32 v39, v0, v19 offset0:24 offset1:90
	s_waitcnt vmcnt(17)
	v_cndmask_b32_e32 v0, 0, v53, vcc
	s_waitcnt vmcnt(16)
	v_cndmask_b32_e32 v19, 0, v54, vcc
	ds_write2_b32 v39, v0, v19 offset0:156 offset1:222
	s_waitcnt vmcnt(15)
	v_cndmask_b32_e32 v0, 0, v55, vcc
	s_waitcnt vmcnt(14)
	v_cndmask_b32_e32 v19, 0, v56, vcc
	v_add_u32_e32 v39, 0x1000, v23
	ds_write2_b32 v39, v0, v19 offset0:32 offset1:98
	s_waitcnt vmcnt(13)
	v_cndmask_b32_e32 v0, 0, v57, vcc
	s_waitcnt vmcnt(12)
	v_cndmask_b32_e32 v19, 0, v58, vcc
	ds_write2_b32 v39, v0, v19 offset0:164 offset1:230
	s_waitcnt vmcnt(11)
	v_cndmask_b32_e32 v0, 0, v59, vcc
	s_waitcnt vmcnt(10)
	v_cndmask_b32_e32 v19, 0, v60, vcc
	v_add_u32_e32 v39, 0x1400, v23
	ds_write2_b32 v39, v0, v19 offset0:40 offset1:106
	s_waitcnt vmcnt(9)
	v_cndmask_b32_e32 v0, 0, v61, vcc
	s_waitcnt vmcnt(8)
	v_cndmask_b32_e32 v19, 0, v62, vcc
	ds_write2_b32 v39, v0, v19 offset0:172 offset1:238
	s_waitcnt vmcnt(7)
	v_cndmask_b32_e32 v0, 0, v63, vcc
	v_add_u32_e32 v39, 0x1800, v23
	s_waitcnt vmcnt(6)
	v_cndmask_b32_e32 v19, 0, v64, vcc
	ds_write2_b32 v39, v0, v19 offset0:48 offset1:114
	s_waitcnt vmcnt(5)
	v_cndmask_b32_e32 v0, 0, v65, vcc
	s_waitcnt vmcnt(4)
	v_cndmask_b32_e32 v19, 0, v66, vcc
	ds_write2_b32 v39, v0, v19 offset0:180 offset1:246
	v_add_u32_e32 v39, 0x1c00, v23
	s_waitcnt vmcnt(3)
	v_cndmask_b32_e32 v0, 0, v67, vcc
	s_waitcnt vmcnt(2)
	v_cndmask_b32_e32 v19, 0, v68, vcc
	ds_write2_b32 v39, v0, v19 offset0:56 offset1:122
	s_waitcnt vmcnt(1)
	v_cndmask_b32_e32 v0, 0, v38, vcc
	s_waitcnt vmcnt(0)
	v_cndmask_b32_e32 v18, 0, v18, vcc
	ds_write2_b32 v39, v0, v18 offset0:188 offset1:254
	s_waitcnt vmcnt(0) expcnt(0) lgkmcnt(0)
	ds_read2_b32 v[42:43], v25 offset0:33 offset1:41
	ds_read2_b32 v[44:45], v25 offset1:8
	ds_read2_b32 v[46:47], v25 offset0:66 offset1:74
	ds_read2_b32 v[48:49], v25 offset0:99 offset1:107
	ds_read2_b32 v[50:51], v25 offset0:132 offset1:140
	ds_read2_b32 v[52:53], v25 offset0:165 offset1:173
	ds_read2_b32 v[54:55], v25 offset0:198 offset1:206
	ds_read2_b32 v[56:57], v25 offset0:231 offset1:239
	v_or_b32_e32 v0, s47, v24
	v_mul_i32_i24_e32 v58, 0xb00, v0
	v_lshl_add_u64 v[18:19], s[26:27], 1, v[14:15]
	v_ashrrev_i32_e32 v59, 31, v58
	v_or_b32_e32 v0, s47, v26
	s_waitcnt lgkmcnt(6)
	v_cvt_pk_bf16_f32 v38, v44, v42
	v_lshl_add_u64 v[58:59], v[58:59], 1, v[18:19]
	v_mul_i32_i24_e32 v42, 0xb00, v0
	s_waitcnt lgkmcnt(4)
	v_cvt_pk_bf16_f32 v39, v46, v48
	s_waitcnt lgkmcnt(2)
	v_cvt_pk_bf16_f32 v40, v50, v52
	s_waitcnt lgkmcnt(0)
	v_cvt_pk_bf16_f32 v41, v54, v56
	global_store_dwordx4 v[58:59], v[38:41], off
	v_or_b32_e32 v0, s47, v27
	v_mul_i32_i24_e32 v58, 0xb00, v0
	v_cvt_pk_bf16_f32 v38, v45, v43
	v_ashrrev_i32_e32 v43, 31, v42
	v_lshl_add_u64 v[42:43], v[42:43], 1, v[18:19]
	v_cvt_pk_bf16_f32 v39, v47, v49
	v_cvt_pk_bf16_f32 v40, v51, v53
	v_cvt_pk_bf16_f32 v41, v55, v57
	global_store_dwordx4 v[42:43], v[38:41], off
	ds_read2_b32 v[42:43], v25 offset0:16 offset1:24
	ds_read2_b32 v[44:45], v25 offset0:49 offset1:57
	ds_read2_b32 v[46:47], v25 offset0:82 offset1:90
	ds_read2_b32 v[48:49], v25 offset0:115 offset1:123
	ds_read2_b32 v[50:51], v25 offset0:148 offset1:156
	ds_read2_b32 v[52:53], v25 offset0:181 offset1:189
	ds_read2_b32 v[54:55], v25 offset0:214 offset1:222
	ds_read2_b32 v[56:57], v25 offset0:247 offset1:255
	v_ashrrev_i32_e32 v59, 31, v58
	v_or_b32_e32 v0, s47, v28
	s_waitcnt lgkmcnt(6)
	v_cvt_pk_bf16_f32 v38, v42, v44
	v_lshl_add_u64 v[58:59], v[58:59], 1, v[18:19]
	v_mul_i32_i24_e32 v42, 0xb00, v0
	s_waitcnt lgkmcnt(4)
	v_cvt_pk_bf16_f32 v39, v46, v48
	s_waitcnt lgkmcnt(2)
	v_cvt_pk_bf16_f32 v40, v50, v52
	s_waitcnt lgkmcnt(0)
	v_cvt_pk_bf16_f32 v41, v54, v56
	global_store_dwordx4 v[58:59], v[38:41], off
	s_nop 1
	v_cvt_pk_bf16_f32 v38, v43, v45
	v_ashrrev_i32_e32 v43, 31, v42
	v_lshl_add_u64 v[18:19], v[42:43], 1, v[18:19]
	v_cvt_pk_bf16_f32 v39, v47, v49
	v_cvt_pk_bf16_f32 v40, v51, v53
	v_cvt_pk_bf16_f32 v41, v55, v57
	global_store_dwordx4 v[18:19], v[38:41], off
	s_waitcnt lgkmcnt(0)

; template <class Map>
; __device__ __forceinline__ void transpose_item(const float* W, int K, int N, bf16_t* WT, float* scr, int item, int nblk, int lane, Map srccol) {
;     const int kb = item / nblk, nb = item % nblk, k0 = 64 * kb, n0 = 32 * nb;
;     const int sc = srccol(n0 + (lane & 31));
;     float tv[32];
;     const float* wp = W + (size_t)(k0 + (lane >> 5)) * N + (sc >= 0 ? sc : 0);
; #pragma unroll
;     for (int i = 0; i < 32; ++i) tv[i] = wp[(size_t)(2 * i) * N];
.LBB0_927:
	s_andn2_b64 vcc, exec, s[6:7]
	s_cbranch_vccnz .LBB0_906
	s_mul_hi_i32 s6, s41, 0x2e8ba2e9
	s_lshr_b32 s7, s6, 31
	s_ashr_i32 s6, s6, 5
	s_add_i32 s6, s6, s7
	s_lshl_b32 s26, s6, 6
	s_mul_i32 s7, s6, 0xffffea00
	s_mulk_i32 s6, 0xf500
	s_add_i32 s47, s42, s7
	s_add_i32 s6, s44, s6
	v_or_b32_e32 v0, s47, v20
	s_and_b32 s6, s6, 0xffffff80
	v_add_u32_e32 v38, s6, v33
	s_and_b32 s6, s47, 0x60
	v_lshlrev_b32_e32 v0, 1, v0
	v_and_or_b32 v18, s41, 4, v34
	v_and_b32_e32 v0, 24, v0
	v_or_b32_e32 v18, s6, v18
	v_or3_b32 v0, v18, v0, v38
	v_or_b32_e32 v39, s26, v22
	v_mov_b64_e32 v[18:19], s[24:25]
	s_movk_i32 s6, 0x5800
	v_cmp_lt_i32_e32 vcc, -1, v38
	v_mad_i64_i32 v[18:19], s[6:7], v39, s6, v[18:19]
	s_nop 0
	v_cndmask_b32_e32 v0, 0, v0, vcc
	v_lshl_add_u64 v[18:19], v[0:1], 2, v[18:19]
	s_mov_b32 s6, 0xb000
	v_add_co_u32_e64 v38, s[6:7], s6, v18
	global_load_dword v0, v[18:19], off
	s_nop 0
	v_addc_co_u32_e64 v39, s[6:7], 0, v19, s[6:7]
	global_load_dword v40, v[38:39], off
	v_add_co_u32_e64 v38, s[6:7], s57, v18
	s_ashr_i32 s27, s26, 31
	s_nop 0
	v_addc_co_u32_e64 v39, s[6:7], 0, v19, s[6:7]
	s_mov_b32 s6, 0x21000
	global_load_dword v41, v[38:39], off
	v_add_co_u32_e64 v38, s[6:7], s6, v18
	s_waitcnt vmcnt(2)
	v_cndmask_b32_e32 v0, 0, v0, vcc
	v_addc_co_u32_e64 v39, s[6:7], 0, v19, s[6:7]
	global_load_dword v42, v[38:39], off
	v_add_co_u32_e64 v38, s[6:7], s33, v18
	s_nop 1
	v_addc_co_u32_e64 v39, s[6:7], 0, v19, s[6:7]
	s_mov_b32 s6, 0x37000
	global_load_dword v43, v[38:39], off
	v_add_co_u32_e64 v38, s[6:7], s6, v18
	s_nop 1
	v_addc_co_u32_e64 v39, s[6:7], 0, v19, s[6:7]
	s_mov_b32 s6, 0x42000
	global_load_dword v44, v[38:39], off
	v_add_co_u32_e64 v38, s[6:7], s6, v18
	s_nop 1
	v_addc_co_u32_e64 v39, s[6:7], 0, v19, s[6:7]
	s_mov_b32 s6, 0x4d000
	global_load_dword v45, v[38:39], off
	v_add_co_u32_e64 v38, s[6:7], s6, v18
	s_nop 1
	v_addc_co_u32_e64 v39, s[6:7], 0, v19, s[6:7]
	s_mov_b32 s6, 0x58000
	global_load_dword v46, v[38:39], off
	v_add_co_u32_e64 v38, s[6:7], s6, v18
	s_nop 1
	v_addc_co_u32_e64 v39, s[6:7], 0, v19, s[6:7]
	s_mov_b32 s6, 0x63000
	global_load_dword v47, v[38:39], off
	v_add_co_u32_e64 v38, s[6:7], s6, v18
	s_nop 1
	v_addc_co_u32_e64 v39, s[6:7], 0, v19, s[6:7]
	s_mov_b32 s6, 0x6e000
	global_load_dword v48, v[38:39], off
	v_add_co_u32_e64 v38, s[6:7], s6, v18
	s_nop 1
	v_addc_co_u32_e64 v39, s[6:7], 0, v19, s[6:7]
	s_mov_b32 s6, 0x79000
	global_load_dword v49, v[38:39], off
	v_add_co_u32_e64 v38, s[6:7], s6, v18
	s_nop 1
	v_addc_co_u32_e64 v39, s[6:7], 0, v19, s[6:7]
	s_mov_b32 s6, 0x84000
	global_load_dword v50, v[38:39], off
	v_add_co_u32_e64 v38, s[6:7], s6, v18
	s_nop 1
	v_addc_co_u32_e64 v39, s[6:7], 0, v19, s[6:7]
	s_mov_b32 s6, 0x8f000
	global_load_dword v51, v[38:39], off
	v_add_co_u32_e64 v38, s[6:7], s6, v18
	s_nop 1
	v_addc_co_u32_e64 v39, s[6:7], 0, v19, s[6:7]
	s_mov_b32 s6, 0x9a000
	global_load_dword v52, v[38:39], off
	v_add_co_u32_e64 v38, s[6:7], s6, v18
	s_nop 1
	v_addc_co_u32_e64 v39, s[6:7], 0, v19, s[6:7]
	s_mov_b32 s6, 0xa5000
	global_load_dword v53, v[38:39], off
	v_add_co_u32_e64 v38, s[6:7], s6, v18
	s_nop 1
	v_addc_co_u32_e64 v39, s[6:7], 0, v19, s[6:7]
	global_load_dword v54, v[38:39], off
	v_add_co_u32_e64 v38, s[6:7], s61, v18
	s_nop 1
	v_addc_co_u32_e64 v39, s[6:7], 0, v19, s[6:7]
	s_mov_b32 s6, 0xbb000
	global_load_dword v55, v[38:39], off
	v_add_co_u32_e64 v38, s[6:7], s6, v18
	s_nop 1
	v_addc_co_u32_e64 v39, s[6:7], 0, v19, s[6:7]
	s_mov_b32 s6, 0xc6000
	global_load_dword v56, v[38:39], off
	v_add_co_u32_e64 v38, s[6:7], s6, v18
	s_nop 1
	v_addc_co_u32_e64 v39, s[6:7], 0, v19, s[6:7]
	s_mov_b32 s6, 0xd1000
	global_load_dword v57, v[38:39], off
	v_add_co_u32_e64 v38, s[6:7], s6, v18
	s_nop 1
	v_addc_co_u32_e64 v39, s[6:7], 0, v19, s[6:7]
	s_mov_b32 s6, 0xdc000
	global_load_dword v58, v[38:39], off
	v_add_co_u32_e64 v38, s[6:7], s6, v18
	s_nop 1
	v_addc_co_u32_e64 v39, s[6:7], 0, v19, s[6:7]
	s_mov_b32 s6, 0xe7000
	global_load_dword v59, v[38:39], off
	v_add_co_u32_e64 v38, s[6:7], s6, v18
	s_nop 1
	v_addc_co_u32_e64 v39, s[6:7], 0, v19, s[6:7]
	s_mov_b32 s6, 0xf2000
	global_load_dword v60, v[38:39], off
	v_add_co_u32_e64 v38, s[6:7], s6, v18
	s_nop 1
	v_addc_co_u32_e64 v39, s[6:7], 0, v19, s[6:7]
	s_mov_b32 s6, 0xfd000
	global_load_dword v61, v[38:39], off
	v_add_co_u32_e64 v38, s[6:7], s6, v18
	s_nop 1
	v_addc_co_u32_e64 v39, s[6:7], 0, v19, s[6:7]
	s_mov_b32 s6, 0x108000
	global_load_dword v62, v[38:39], off
	v_add_co_u32_e64 v38, s[6:7], s6, v18
	s_nop 1
	v_addc_co_u32_e64 v39, s[6:7], 0, v19, s[6:7]
	s_mov_b32 s6, 0x113000
	global_load_dword v63, v[38:39], off
	v_add_co_u32_e64 v38, s[6:7], s6, v18
	s_nop 1
	v_addc_co_u32_e64 v39, s[6:7], 0, v19, s[6:7]
	s_mov_b32 s6, 0x11e000
	global_load_dword v64, v[38:39], off
	v_add_co_u32_e64 v38, s[6:7], s6, v18
	s_nop 1
	v_addc_co_u32_e64 v39, s[6:7], 0, v19, s[6:7]
	s_mov_b32 s6, 0x129000
	global_load_dword v65, v[38:39], off
	v_add_co_u32_e64 v38, s[6:7], s6, v18
	s_nop 1
	v_addc_co_u32_e64 v39, s[6:7], 0, v19, s[6:7]
	s_mov_b32 s6, 0x134000
	global_load_dword v66, v[38:39], off
	v_add_co_u32_e64 v38, s[6:7], s6, v18
	s_nop 1
	v_addc_co_u32_e64 v39, s[6:7], 0, v19, s[6:7]
	s_mov_b32 s6, 0x13f000
	global_load_dword v67, v[38:39], off
	v_add_co_u32_e64 v38, s[6:7], s6, v18
	s_nop 1
	v_addc_co_u32_e64 v39, s[6:7], 0, v19, s[6:7]
	s_mov_b32 s6, 0x14a000
	global_load_dword v68, v[38:39], off
	v_add_co_u32_e64 v38, s[6:7], s6, v18
	s_nop 1
	v_addc_co_u32_e64 v39, s[6:7], 0, v19, s[6:7]
	s_mov_b32 s6, 0x155000
	s_nop 0
	v_add_co_u32_e64 v18, s[6:7], s6, v18
	global_load_dword v38, v[38:39], off
	s_nop 0
	v_addc_co_u32_e64 v19, s[6:7], 0, v19, s[6:7]
	global_load_dword v18, v[18:19], off
	s_waitcnt vmcnt(30)
; __device__ __forceinline__ unsigned pk2(float lo, float hi) { unsigned r; asm("v_cvt_pk_bf16_f32 %0, %1, %2" : "=v"(r) : "v"(lo), "v"(hi)); return r; }
; template <class Map>
; __device__ __forceinline__ void transpose_item(const float* W, int K, int N, bf16_t* WT, float* scr, int item, int nblk, int lane, Map srccol) {
;     ...
; #pragma unroll
;     for (int i = 0; i < 32; ++i) { const int kk = 2 * i + (lane >> 5); scr[kk * 33 + (lane & 31)] = sc >= 0 ? tv[i] : 0.f; }
;     __builtin_amdgcn_s_waitcnt(0); asm volatile("" ::: "memory");
;     const int c = lane & 7;
; #pragma unroll
;     for (int j = 0; j < 4; ++j) { const int n = (lane >> 3) + 8 * j; const float* s = scr + (8 * c) * 33 + n;
;         u32x4 o; o.x = pk2(s[0 * 33], s[1 * 33]); o.y = pk2(s[2 * 33], s[3 * 33]); o.z = pk2(s[4 * 33], s[5 * 33]); o.w = pk2(s[6 * 33], s[7 * 33]);
;         *(u32x4*)(WT + (size_t)(n0 + n) * K + k0 + 8 * c) = o; }
;     __builtin_amdgcn_s_waitcnt(0); asm volatile("" ::: "memory");
	v_cndmask_b32_e32 v19, 0, v40, vcc
	ds_write2_b32 v35, v0, v19 offset1:66
	s_waitcnt vmcnt(29)
	v_cndmask_b32_e32 v0, 0, v41, vcc
	s_waitcnt vmcnt(28)
	v_cndmask_b32_e32 v19, 0, v42, vcc
	ds_write2_b32 v35, v0, v19 offset0:132 offset1:198
	s_waitcnt vmcnt(27)
	v_cndmask_b32_e32 v0, 0, v43, vcc
	s_waitcnt vmcnt(26)
	v_cndmask_b32_e32 v19, 0, v44, vcc
	v_add_u32_e32 v39, 0x400, v35
	ds_write2_b32 v39, v0, v19 offset0:8 offset1:74
	s_waitcnt vmcnt(25)
	v_cndmask_b32_e32 v0, 0, v45, vcc
	s_waitcnt vmcnt(24)
	v_cndmask_b32_e32 v19, 0, v46, vcc
	ds_write2_b32 v39, v0, v19 offset0:140 offset1:206
	s_waitcnt vmcnt(23)
	v_cndmask_b32_e32 v0, 0, v47, vcc
	s_waitcnt vmcnt(22)
	v_cndmask_b32_e32 v19, 0, v48, vcc
	v_add_u32_e32 v39, 0x800, v35
	ds_write2_b32 v39, v0, v19 offset0:16 offset1:82
	s_waitcnt vmcnt(21)
	v_cndmask_b32_e32 v0, 0, v49, vcc
	s_waitcnt vmcnt(20)
	v_cndmask_b32_e32 v19, 0, v50, vcc
	ds_write2_b32 v39, v0, v19 offset0:148 offset1:214
	s_waitcnt vmcnt(19)
	v_cndmask_b32_e32 v0, 0, v51, vcc
	s_waitcnt vmcnt(18)
	v_cndmask_b32_e32 v19, 0, v52, vcc
	v_add_u32_e32 v39, 0xc00, v35
	ds_write2_b32 v39, v0, v19 offset0:24 offset1:90
	s_waitcnt vmcnt(17)
	v_cndmask_b32_e32 v0, 0, v53, vcc
	s_waitcnt vmcnt(16)
	v_cndmask_b32_e32 v19, 0, v54, vcc
	ds_write2_b32 v39, v0, v19 offset0:156 offset1:222
	s_waitcnt vmcnt(15)
	v_cndmask_b32_e32 v0, 0, v55, vcc
	s_waitcnt vmcnt(14)
	v_cndmask_b32_e32 v19, 0, v56, vcc
	v_add_u32_e32 v39, 0x1000, v35
	ds_write2_b32 v39, v0, v19 offset0:32 offset1:98
	s_waitcnt vmcnt(13)
	v_cndmask_b32_e32 v0, 0, v57, vcc
	s_waitcnt vmcnt(12)
	v_cndmask_b32_e32 v19, 0, v58, vcc
	ds_write2_b32 v39, v0, v19 offset0:164 offset1:230
	s_waitcnt vmcnt(11)
	v_cndmask_b32_e32 v0, 0, v59, vcc
	s_waitcnt vmcnt(10)
	v_cndmask_b32_e32 v19, 0, v60, vcc
	v_add_u32_e32 v39, 0x1400, v35
	ds_write2_b32 v39, v0, v19 offset0:40 offset1:106
	s_waitcnt vmcnt(9)
	v_cndmask_b32_e32 v0, 0, v61, vcc
	s_waitcnt vmcnt(8)
	v_cndmask_b32_e32 v19, 0, v62, vcc
	ds_write2_b32 v39, v0, v19 offset0:172 offset1:238
	s_waitcnt vmcnt(7)
	v_cndmask_b32_e32 v0, 0, v63, vcc
	s_waitcnt vmcnt(6)
	v_cndmask_b32_e32 v19, 0, v64, vcc
	v_add_u32_e32 v39, 0x1800, v35
	ds_write2_b32 v39, v0, v19 offset0:48 offset1:114
	v_add_u32_e32 v58, s47, v24
	v_ashrrev_i32_e32 v59, 31, v58
	s_waitcnt vmcnt(5)
	v_cndmask_b32_e32 v0, 0, v65, vcc
	v_lshlrev_b64 v[60:61], 11, v[58:59]
	s_waitcnt vmcnt(4)
	v_cndmask_b32_e32 v19, 0, v66, vcc
	ds_write2_b32 v39, v0, v19 offset0:180 offset1:246
	v_add_u32_e32 v39, 0x1c00, v35
	s_waitcnt vmcnt(3)
	v_cndmask_b32_e32 v0, 0, v67, vcc
	s_waitcnt vmcnt(2)
	v_cndmask_b32_e32 v19, 0, v68, vcc
	ds_write2_b32 v39, v0, v19 offset0:56 offset1:122
	s_waitcnt vmcnt(1)
	v_cndmask_b32_e32 v0, 0, v38, vcc
	s_waitcnt vmcnt(0)
	v_cndmask_b32_e32 v18, 0, v18, vcc
	ds_write2_b32 v39, v0, v18 offset0:188 offset1:254
	s_waitcnt vmcnt(0) expcnt(0) lgkmcnt(0)
	ds_read2_b32 v[42:43], v25 offset0:33 offset1:41
	ds_read2_b32 v[44:45], v25 offset1:8
	ds_read2_b32 v[46:47], v25 offset0:66 offset1:74
	ds_read2_b32 v[48:49], v25 offset0:99 offset1:107
	ds_read2_b32 v[50:51], v25 offset0:132 offset1:140
	ds_read2_b32 v[52:53], v25 offset0:165 offset1:173
	ds_read2_b32 v[54:55], v25 offset0:198 offset1:206
	ds_read2_b32 v[56:57], v25 offset0:231 offset1:239
	v_lshl_add_u64 v[18:19], s[26:27], 1, v[16:17]
	s_waitcnt lgkmcnt(6)
	v_cvt_pk_bf16_f32 v38, v44, v42
	v_lshl_add_u64 v[60:61], v[18:19], 0, v[60:61]
	v_add_u32_e32 v42, 8, v58
	s_waitcnt lgkmcnt(4)
	v_cvt_pk_bf16_f32 v39, v46, v48
	s_waitcnt lgkmcnt(2)
	v_cvt_pk_bf16_f32 v40, v50, v52
	s_waitcnt lgkmcnt(0)
	v_cvt_pk_bf16_f32 v41, v54, v56
	global_store_dwordx4 v[60:61], v[38:41], off
	v_add_u32_e32 v60, 16, v58
	v_ashrrev_i32_e32 v61, 31, v60
	v_cvt_pk_bf16_f32 v38, v45, v43
	v_ashrrev_i32_e32 v43, 31, v42
	v_lshlrev_b64 v[42:43], 11, v[42:43]
	v_lshl_add_u64 v[42:43], v[18:19], 0, v[42:43]
	v_cvt_pk_bf16_f32 v39, v47, v49
	v_cvt_pk_bf16_f32 v40, v51, v53
	v_cvt_pk_bf16_f32 v41, v55, v57
	global_store_dwordx4 v[42:43], v[38:41], off
	ds_read2_b32 v[42:43], v25 offset0:16 offset1:24
	ds_read2_b32 v[44:45], v25 offset0:49 offset1:57
	ds_read2_b32 v[46:47], v25 offset0:82 offset1:90
	ds_read2_b32 v[48:49], v25 offset0:115 offset1:123
	ds_read2_b32 v[50:51], v25 offset0:148 offset1:156
	ds_read2_b32 v[52:53], v25 offset0:181 offset1:189
	ds_read2_b32 v[54:55], v25 offset0:214 offset1:222
	ds_read2_b32 v[56:57], v25 offset0:247 offset1:255
	v_lshlrev_b64 v[60:61], 11, v[60:61]
	s_waitcnt lgkmcnt(6)
	v_cvt_pk_bf16_f32 v38, v42, v44
	v_lshl_add_u64 v[60:61], v[18:19], 0, v[60:61]
	v_add_u32_e32 v42, 24, v58
	s_waitcnt lgkmcnt(4)
	v_cvt_pk_bf16_f32 v39, v46, v48
	s_waitcnt lgkmcnt(2)
	v_cvt_pk_bf16_f32 v40, v50, v52
	s_waitcnt lgkmcnt(0)
	v_cvt_pk_bf16_f32 v41, v54, v56
	global_store_dwordx4 v[60:61], v[38:41], off
	s_nop 1
	v_cvt_pk_bf16_f32 v38, v43, v45
	v_ashrrev_i32_e32 v43, 31, v42
	v_lshlrev_b64 v[42:43], 11, v[42:43]
	v_lshl_add_u64 v[18:19], v[18:19], 0, v[42:43]
	v_cvt_pk_bf16_f32 v39, v47, v49
	v_cvt_pk_bf16_f32 v40, v51, v53
	v_cvt_pk_bf16_f32 v41, v55, v57
	global_store_dwordx4 v[18:19], v[38:41], off
	s_waitcnt lgkmcnt(0)
	s_branch .LBB0_906
